# GEMM loops: satisfied lgkmcnt(0) at each MFMA segment head removed; M0 wait state provided by the address VALU op instead of s_nop; no setprio
# speedup vs baseline: 1.0014x; 1.0014x over previous
; #define PG8_STAGE(bufoff, gbase, voff) do { _Pragma("unroll") for (int _i = 0; _i < 2; ++_i) \
;         __builtin_amdgcn_global_load_lds((const unsigned*)((const char*)(gbase) + (voff)[_i]), (LAS unsigned*)(lds + (bufoff) + ldsw + _i * 8192), 16, 0, 0); } while (0)
; #define PG8_LDA(dst, b, h) do { _Pragma("unroll") for (int m = 0; m < 4; ++m) _Pragma("unroll") for (int k = 0; k < 2; ++k) dst[m][k] = *(const LAS bf16x8*)(lds + PG8_SA(b, h) + aoff + m * 2048 + k * 1024); } while (0)
; #define PG8_LDB(dst, b, h) do { _Pragma("unroll") for (int n = 0; n < 2; ++n) _Pragma("unroll") for (int k = 0; k < 2; ++k) dst[n][k] = *(const LAS bf16x8*)(lds + PG8_SB(b, h) + boff + n * 2048 + k * 1024); } while (0)
; #define PG8_MMA(ai, bj, At, Bt) do { __builtin_amdgcn_s_setprio(1); _Pragma("unroll") for (int m = 0; m < 4; ++m) _Pragma("unroll") for (int n = 0; n < 2; ++n) _Pragma("unroll") for (int k = 0; k < 2; ++k) \
;         acc[ai][bj][m][n] = __builtin_amdgcn_mfma_f32_16x16x32_bf16(Bt[n][k], At[m][k], acc[ai][bj][m][n], 0, 0, 0); __builtin_amdgcn_s_setprio(0); } while (0)
; #define PG8_WAIT_V(n) asm volatile("s_waitcnt vmcnt(" #n ")" ::: "memory")
; #define PG8_WAIT_L(n) asm volatile("s_waitcnt lgkmcnt(" #n ")" ::: "memory")
; template <class Epi, class Sched = StaticOrder, bool ALIGN_EPI = true>
; __device__ __forceinline__ void gemm_phase(LAS unsigned char* lds, const Gemm g, const Sched& S, const Epi& E) {
;     ...
;         const char* nA = has_next ? (const char*)g.A + (size_t)nxt.pm * tstep + (size_t)nxt.kp * K * 2 : cA; const char* nB = has_next ? (const char*)g.Bt + (size_t)nxt.pn * tstep + (size_t)nxt.kp * K * 2 : cB;
;         for (int t = 0; t < nt; t += 2) {
;             const bool last = (t == nt - 2);
;             const char* a1 = cA + (size_t)(t + 1) * kstep;
;             const char* a2 = last ? nA : cA + (size_t)(t + 2) * kstep; const char* b2 = last ? nB : cB + (size_t)(t + 2) * kstep;
;             const char* a3 = a2 + kstep; const char* b3 = b2 + kstep;
;             PG8_LDB(B0, 0, 0); PG8_LDB(B1, 0, 1); PG8_SCHED; PG8_LDA(At, 0, 0); PG8_STAGE(PG8_SA(1, 1), a1 + hstep, voffA);
;             PG8_WAIT_V(8); PG8_WAIT_L(0); PG8_BAR; PG8_MMA(0, 0, At, B0); PG8_MMA(0, 1, At, B1); PG8_BAR; PG8_SCHED;
;             PG8_LDA(At, 0, 1); PG8_STAGE(PG8_SB(0, 0), b2, voffB); PG8_STAGE(PG8_SB(0, 1), b2 + hstep, voffB); PG8_STAGE(PG8_SA(0, 0), a2, voffA);
.Lmy_nb_106:
	s_add_u32 s16, s80, 0xfff80080
	s_addc_u32 s17, s81, -1
	s_add_i32 s33, 0, 0x10000
	s_cmp_eq_u32 s49, 28
	s_cselect_b32 vcc_hi, s30, s17
	s_cselect_b32 vcc_lo, s31, s16
	v_add_u32_e32 v142, s33, v144
	s_cselect_b32 s47, s21, s43
	s_cselect_b32 s46, s36, s37
	s_add_i32 s70, 0, 0x14000
	ds_read_b128 v[148:151], v142
	ds_read_b128 v[160:163], v142 offset:1024
	ds_read_b128 v[164:167], v142 offset:2048
	ds_read_b128 v[168:171], v142 offset:3072
	v_add_u32_e32 v142, s70, v144
	ds_read_b128 v[172:175], v142
	ds_read_b128 v[176:179], v142 offset:1024
	ds_read_b128 v[180:183], v142 offset:2048
	ds_read_b128 v[184:187], v142 offset:3072
	v_lshl_add_u64 v[142:143], s[80:81], 0, v[138:139]
	s_add_i32 m0, s7, 0xc000
	ds_read_b128 v[188:191], v146
	ds_read_b128 v[192:195], v146 offset:1024
	ds_read_b128 v[210:213], v146 offset:2048
	ds_read_b128 v[214:217], v146 offset:3072
	ds_read_b128 v[218:221], v146 offset:4096
	ds_read_b128 v[222:225], v146 offset:5120
	ds_read_b128 v[226:229], v146 offset:6144
	ds_read_b128 v[230:233], v146 offset:7168
	global_load_lds_dwordx4 v[142:143], off
	s_add_i32 m0, s7, 0xe000
	v_lshl_add_u64 v[142:143], s[80:81], 0, v[140:141]
	global_load_lds_dwordx4 v[142:143], off
	s_waitcnt vmcnt(8)
	s_waitcnt lgkmcnt(0)
	s_barrier
	v_mfma_f32_16x16x32_bf16 v[126:129], v[148:151], v[188:191], 0
	v_mfma_f32_16x16x32_bf16 v[122:125], v[164:167], v[188:191], 0
	v_mfma_f32_16x16x32_bf16 v[118:121], v[148:151], v[210:213], 0
	v_mfma_f32_16x16x32_bf16 v[110:113], v[164:167], v[210:213], 0
	v_mfma_f32_16x16x32_bf16 v[102:105], v[148:151], v[218:221], 0
	v_mfma_f32_16x16x32_bf16 v[94:97], v[164:167], v[218:221], 0
	v_mfma_f32_16x16x32_bf16 v[82:85], v[148:151], v[226:229], 0
	v_mfma_f32_16x16x32_bf16 v[74:77], v[164:167], v[226:229], 0
	v_mfma_f32_16x16x32_bf16 v[126:129], v[160:163], v[192:195], v[126:129]
	v_mfma_f32_16x16x32_bf16 v[122:125], v[168:171], v[192:195], v[122:125]
	v_mfma_f32_16x16x32_bf16 v[118:121], v[160:163], v[214:217], v[118:121]
	v_mfma_f32_16x16x32_bf16 v[110:113], v[168:171], v[214:217], v[110:113]
	v_mfma_f32_16x16x32_bf16 v[102:105], v[160:163], v[222:225], v[102:105]
	v_mfma_f32_16x16x32_bf16 v[94:97], v[168:171], v[222:225], v[94:97]
	v_mfma_f32_16x16x32_bf16 v[82:85], v[160:163], v[230:233], v[82:85]
	v_mfma_f32_16x16x32_bf16 v[74:77], v[168:171], v[230:233], v[74:77]
	v_mfma_f32_16x16x32_bf16 v[114:117], v[172:175], v[188:191], 0
	v_mfma_f32_16x16x32_bf16 v[106:109], v[180:183], v[188:191], 0
	v_mfma_f32_16x16x32_bf16 v[98:101], v[172:175], v[210:213], 0
	v_mfma_f32_16x16x32_bf16 v[90:93], v[180:183], v[210:213], 0
	v_mfma_f32_16x16x32_bf16 v[86:89], v[172:175], v[218:221], 0
	v_mfma_f32_16x16x32_bf16 v[78:81], v[180:183], v[218:221], 0
	v_mfma_f32_16x16x32_bf16 v[70:73], v[172:175], v[226:229], 0
	v_mfma_f32_16x16x32_bf16 v[66:69], v[180:183], v[226:229], 0
	v_mfma_f32_16x16x32_bf16 v[114:117], v[176:179], v[192:195], v[114:117]
	v_mfma_f32_16x16x32_bf16 v[106:109], v[184:187], v[192:195], v[106:109]
	v_mfma_f32_16x16x32_bf16 v[98:101], v[176:179], v[214:217], v[98:101]
	v_mfma_f32_16x16x32_bf16 v[90:93], v[184:187], v[214:217], v[90:93]
	v_mfma_f32_16x16x32_bf16 v[86:89], v[176:179], v[222:225], v[86:89]
	v_mfma_f32_16x16x32_bf16 v[78:81], v[184:187], v[222:225], v[78:81]
	v_mfma_f32_16x16x32_bf16 v[70:73], v[176:179], v[230:233], v[70:73]
	v_mfma_f32_16x16x32_bf16 v[66:69], v[184:187], v[230:233], v[66:69]
	s_barrier
	s_add_i32 s16, s33, s5
	v_lshl_add_u64 v[142:143], s[46:47], 0, v[134:135]
	s_mov_b32 m0, s16
	ds_read_b128 v[188:191], v146 offset:16384
	ds_read_b128 v[192:195], v146 offset:17408
	ds_read_b128 v[210:213], v146 offset:18432
	ds_read_b128 v[214:217], v146 offset:19456
	ds_read_b128 v[218:221], v146 offset:20480
	ds_read_b128 v[222:225], v146 offset:21504
	ds_read_b128 v[226:229], v146 offset:22528
	ds_read_b128 v[230:233], v146 offset:23552
	global_load_lds_dwordx4 v[142:143], off
	s_add_i32 m0, s16, 0x2000
	s_add_u32 s16, s46, 0x80000
	v_lshl_add_u64 v[152:153], s[46:47], 0, v[130:131]
	s_addc_u32 s17, s47, 0
	s_add_i32 s33, s70, s5
	global_load_lds_dwordx4 v[152:153], off
	v_lshl_add_u64 v[196:197], s[16:17], 0, v[134:135]
	s_mov_b32 m0, s33
	v_lshl_add_u64 v[234:235], vcc, 0, v[132:133]
	global_load_lds_dwordx4 v[196:197], off
	s_add_i32 m0, s33, 0x2000
	v_lshl_add_u64 v[196:197], s[16:17], 0, v[130:131]
	global_load_lds_dwordx4 v[196:197], off
	s_mov_b32 m0, s7
	v_lshl_add_u64 v[196:197], vcc, 0, v[136:137]
	global_load_lds_dwordx4 v[196:197], off
	s_mov_b32 m0, s8
	s_nop 0
	global_load_lds_dwordx4 v[234:235], off
	s_waitcnt vmcnt(8)
	s_waitcnt lgkmcnt(0)
	s_barrier
; #define PG8_STAGE(bufoff, gbase, voff) do { _Pragma("unroll") for (int _i = 0; _i < 2; ++_i) \
;         __builtin_amdgcn_global_load_lds((const unsigned*)((const char*)(gbase) + (voff)[_i]), (LAS unsigned*)(lds + (bufoff) + ldsw + _i * 8192), 16, 0, 0); } while (0)
; #define PG8_LDA(dst, b, h) do { _Pragma("unroll") for (int m = 0; m < 4; ++m) _Pragma("unroll") for (int k = 0; k < 2; ++k) dst[m][k] = *(const LAS bf16x8*)(lds + PG8_SA(b, h) + aoff + m * 2048 + k * 1024); } while (0)
; #define PG8_LDB(dst, b, h) do { _Pragma("unroll") for (int n = 0; n < 2; ++n) _Pragma("unroll") for (int k = 0; k < 2; ++k) dst[n][k] = *(const LAS bf16x8*)(lds + PG8_SB(b, h) + boff + n * 2048 + k * 1024); } while (0)
; #define PG8_MMA(ai, bj, At, Bt) do { __builtin_amdgcn_s_setprio(1); _Pragma("unroll") for (int m = 0; m < 4; ++m) _Pragma("unroll") for (int n = 0; n < 2; ++n) _Pragma("unroll") for (int k = 0; k < 2; ++k) \
;         acc[ai][bj][m][n] = __builtin_amdgcn_mfma_f32_16x16x32_bf16(Bt[n][k], At[m][k], acc[ai][bj][m][n], 0, 0, 0); __builtin_amdgcn_s_setprio(0); } while (0)
; #define PG8_WAIT_V(n) asm volatile("s_waitcnt vmcnt(" #n ")" ::: "memory")
; #define PG8_WAIT_L(n) asm volatile("s_waitcnt lgkmcnt(" #n ")" ::: "memory")
; #define PG8_BAR __builtin_amdgcn_s_barrier()
; #define PG8_SCHED __builtin_amdgcn_sched_barrier(0)
; template <class Epi, class Sched = StaticOrder, bool ALIGN_EPI = true>
; __device__ __forceinline__ void gemm_phase(LAS unsigned char* lds, const Gemm g, const Sched& S, const Epi& E) {
;     ...
;             PG8_WAIT_V(8); PG8_WAIT_L(0); PG8_BAR; PG8_MMA(1, 0, At, B0); PG8_MMA(1, 1, At, B1); PG8_BAR; PG8_SCHED;
;             PG8_LDB(B0, 1, 0); PG8_LDB(B1, 1, 1); PG8_SCHED; PG8_LDA(At, 1, 0); PG8_STAGE(PG8_SA(0, 1), a2 + hstep, voffA);
;             PG8_WAIT_V(8); PG8_WAIT_L(0); PG8_BAR; PG8_MMA(0, 0, At, B0); PG8_MMA(0, 1, At, B1); PG8_BAR; PG8_SCHED;
	v_mfma_f32_16x16x32_bf16 v[62:65], v[148:151], v[188:191], 0
	v_mfma_f32_16x16x32_bf16 v[58:61], v[164:167], v[188:191], 0
	v_mfma_f32_16x16x32_bf16 v[54:57], v[148:151], v[210:213], 0
	v_mfma_f32_16x16x32_bf16 v[46:49], v[164:167], v[210:213], 0
	v_mfma_f32_16x16x32_bf16 v[38:41], v[148:151], v[218:221], 0
	v_mfma_f32_16x16x32_bf16 v[30:33], v[164:167], v[218:221], 0
	v_mfma_f32_16x16x32_bf16 v[22:25], v[148:151], v[226:229], 0
	v_mfma_f32_16x16x32_bf16 v[14:17], v[164:167], v[226:229], 0
	v_mfma_f32_16x16x32_bf16 v[62:65], v[160:163], v[192:195], v[62:65]
	v_mfma_f32_16x16x32_bf16 v[58:61], v[168:171], v[192:195], v[58:61]
	v_mfma_f32_16x16x32_bf16 v[54:57], v[160:163], v[214:217], v[54:57]
	v_mfma_f32_16x16x32_bf16 v[46:49], v[168:171], v[214:217], v[46:49]
	v_mfma_f32_16x16x32_bf16 v[38:41], v[160:163], v[222:225], v[38:41]
	v_mfma_f32_16x16x32_bf16 v[30:33], v[168:171], v[222:225], v[30:33]
	v_mfma_f32_16x16x32_bf16 v[22:25], v[160:163], v[230:233], v[22:25]
	v_mfma_f32_16x16x32_bf16 v[14:17], v[168:171], v[230:233], v[14:17]
	v_mfma_f32_16x16x32_bf16 v[50:53], v[172:175], v[188:191], 0
	v_mfma_f32_16x16x32_bf16 v[42:45], v[180:183], v[188:191], 0
	v_mfma_f32_16x16x32_bf16 v[34:37], v[172:175], v[210:213], 0
	v_mfma_f32_16x16x32_bf16 v[26:29], v[180:183], v[210:213], 0
	v_mfma_f32_16x16x32_bf16 v[18:21], v[172:175], v[218:221], 0
	v_mfma_f32_16x16x32_bf16 v[10:13], v[180:183], v[218:221], 0
	v_mfma_f32_16x16x32_bf16 v[6:9], v[172:175], v[226:229], 0
	v_mfma_f32_16x16x32_bf16 v[2:5], v[180:183], v[226:229], 0
	v_mfma_f32_16x16x32_bf16 v[50:53], v[176:179], v[192:195], v[50:53]
	v_mfma_f32_16x16x32_bf16 v[42:45], v[184:187], v[192:195], v[42:45]
	v_mfma_f32_16x16x32_bf16 v[34:37], v[176:179], v[214:217], v[34:37]
	v_mfma_f32_16x16x32_bf16 v[26:29], v[184:187], v[214:217], v[26:29]
	v_mfma_f32_16x16x32_bf16 v[18:21], v[176:179], v[222:225], v[18:21]
	v_mfma_f32_16x16x32_bf16 v[10:13], v[184:187], v[222:225], v[10:13]
	v_mfma_f32_16x16x32_bf16 v[6:9], v[176:179], v[230:233], v[6:9]
	v_mfma_f32_16x16x32_bf16 v[2:5], v[184:187], v[230:233], v[2:5]
	s_barrier
	s_add_i32 s33, 0, 0x18000
	v_add_u32_e32 v147, s33, v144
	s_add_i32 s70, 0, 0x1c000
	ds_read_b128 v[148:151], v147
	ds_read_b128 v[160:163], v147 offset:1024
	ds_read_b128 v[164:167], v147 offset:2048
	ds_read_b128 v[168:171], v147 offset:3072
	v_add_u32_e32 v147, s70, v144
	ds_read_b128 v[172:175], v147
	ds_read_b128 v[176:179], v147 offset:1024
	ds_read_b128 v[180:183], v147 offset:2048
	ds_read_b128 v[184:187], v147 offset:3072
	s_add_u32 s16, vcc_lo, 0x80000
	s_addc_u32 s17, vcc_hi, 0
	s_mov_b32 m0, s9
	v_lshl_add_u64 v[236:237], s[16:17], 0, v[136:137]
	ds_read_b128 v[188:191], v146 offset:32768
	ds_read_b128 v[192:195], v146 offset:33792
	ds_read_b128 v[210:213], v146 offset:34816
	ds_read_b128 v[214:217], v146 offset:35840
	ds_read_b128 v[218:221], v146 offset:36864
	ds_read_b128 v[222:225], v146 offset:37888
	ds_read_b128 v[226:229], v146 offset:38912
	ds_read_b128 v[230:233], v146 offset:39936
	global_load_lds_dwordx4 v[236:237], off
	s_mov_b32 m0, s10
	v_lshl_add_u64 v[236:237], s[16:17], 0, v[132:133]
	global_load_lds_dwordx4 v[236:237], off
	s_waitcnt vmcnt(8)
	s_waitcnt lgkmcnt(0)
	s_barrier
	v_mfma_f32_16x16x32_bf16 v[126:129], v[148:151], v[188:191], v[126:129]
	v_mfma_f32_16x16x32_bf16 v[122:125], v[164:167], v[188:191], v[122:125]
	v_mfma_f32_16x16x32_bf16 v[118:121], v[148:151], v[210:213], v[118:121]
	v_mfma_f32_16x16x32_bf16 v[110:113], v[164:167], v[210:213], v[110:113]
	v_mfma_f32_16x16x32_bf16 v[102:105], v[148:151], v[218:221], v[102:105]
	v_mfma_f32_16x16x32_bf16 v[94:97], v[164:167], v[218:221], v[94:97]
	v_mfma_f32_16x16x32_bf16 v[82:85], v[148:151], v[226:229], v[82:85]
	v_mfma_f32_16x16x32_bf16 v[74:77], v[164:167], v[226:229], v[74:77]
	v_mfma_f32_16x16x32_bf16 v[126:129], v[160:163], v[192:195], v[126:129]
	v_mfma_f32_16x16x32_bf16 v[122:125], v[168:171], v[192:195], v[122:125]
	v_mfma_f32_16x16x32_bf16 v[118:121], v[160:163], v[214:217], v[118:121]
	v_mfma_f32_16x16x32_bf16 v[110:113], v[168:171], v[214:217], v[110:113]
	v_mfma_f32_16x16x32_bf16 v[102:105], v[160:163], v[222:225], v[102:105]
	v_mfma_f32_16x16x32_bf16 v[94:97], v[168:171], v[222:225], v[94:97]
	v_mfma_f32_16x16x32_bf16 v[82:85], v[160:163], v[230:233], v[82:85]
	v_mfma_f32_16x16x32_bf16 v[74:77], v[168:171], v[230:233], v[74:77]
	v_mfma_f32_16x16x32_bf16 v[114:117], v[172:175], v[188:191], v[114:117]
	v_mfma_f32_16x16x32_bf16 v[106:109], v[180:183], v[188:191], v[106:109]
	v_mfma_f32_16x16x32_bf16 v[98:101], v[172:175], v[210:213], v[98:101]
	v_mfma_f32_16x16x32_bf16 v[90:93], v[180:183], v[210:213], v[90:93]
	v_mfma_f32_16x16x32_bf16 v[86:89], v[172:175], v[218:221], v[86:89]
	v_mfma_f32_16x16x32_bf16 v[78:81], v[180:183], v[218:221], v[78:81]
	v_mfma_f32_16x16x32_bf16 v[70:73], v[172:175], v[226:229], v[70:73]
	v_mfma_f32_16x16x32_bf16 v[66:69], v[180:183], v[226:229], v[66:69]
	v_mfma_f32_16x16x32_bf16 v[114:117], v[176:179], v[192:195], v[114:117]
	v_mfma_f32_16x16x32_bf16 v[106:109], v[184:187], v[192:195], v[106:109]
	v_mfma_f32_16x16x32_bf16 v[98:101], v[176:179], v[214:217], v[98:101]
	v_mfma_f32_16x16x32_bf16 v[90:93], v[184:187], v[214:217], v[90:93]
	v_mfma_f32_16x16x32_bf16 v[86:89], v[176:179], v[222:225], v[86:89]
	v_mfma_f32_16x16x32_bf16 v[78:81], v[184:187], v[222:225], v[78:81]
	v_mfma_f32_16x16x32_bf16 v[70:73], v[176:179], v[230:233], v[70:73]
	v_mfma_f32_16x16x32_bf16 v[66:69], v[184:187], v[230:233], v[66:69]
	s_barrier
; #define PG8_STAGE(bufoff, gbase, voff) do { _Pragma("unroll") for (int _i = 0; _i < 2; ++_i) \
;         __builtin_amdgcn_global_load_lds((const unsigned*)((const char*)(gbase) + (voff)[_i]), (LAS unsigned*)(lds + (bufoff) + ldsw + _i * 8192), 16, 0, 0); } while (0)
; #define PG8_LDA(dst, b, h) do { _Pragma("unroll") for (int m = 0; m < 4; ++m) _Pragma("unroll") for (int k = 0; k < 2; ++k) dst[m][k] = *(const LAS bf16x8*)(lds + PG8_SA(b, h) + aoff + m * 2048 + k * 1024); } while (0)
; #define PG8_LDB(dst, b, h) do { _Pragma("unroll") for (int n = 0; n < 2; ++n) _Pragma("unroll") for (int k = 0; k < 2; ++k) dst[n][k] = *(const LAS bf16x8*)(lds + PG8_SB(b, h) + boff + n * 2048 + k * 1024); } while (0)
; #define PG8_MMA(ai, bj, At, Bt) do { __builtin_amdgcn_s_setprio(1); _Pragma("unroll") for (int m = 0; m < 4; ++m) _Pragma("unroll") for (int n = 0; n < 2; ++n) _Pragma("unroll") for (int k = 0; k < 2; ++k) \
;         acc[ai][bj][m][n] = __builtin_amdgcn_mfma_f32_16x16x32_bf16(Bt[n][k], At[m][k], acc[ai][bj][m][n], 0, 0, 0); __builtin_amdgcn_s_setprio(0); } while (0)
; #define PG8_WAIT_V(n) asm volatile("s_waitcnt vmcnt(" #n ")" ::: "memory")
; template <class Epi, class Sched = StaticOrder, bool ALIGN_EPI = true>
; __device__ __forceinline__ void gemm_phase(LAS unsigned char* lds, const Gemm g, const Sched& S, const Epi& E) {
;     ...
;             PG8_LDB(B0, 0, 0); PG8_LDB(B1, 0, 1); PG8_SCHED; PG8_LDA(At, 0, 0); PG8_STAGE(PG8_SA(1, 1), a1 + hstep, voffA);
;             PG8_WAIT_V(8); PG8_WAIT_L(0); PG8_BAR; PG8_MMA(0, 0, At, B0); PG8_MMA(0, 1, At, B1); PG8_BAR; PG8_SCHED;
;             PG8_LDA(At, 0, 1); PG8_STAGE(PG8_SB(0, 0), b2, voffB); PG8_STAGE(PG8_SB(0, 1), b2 + hstep, voffB); PG8_STAGE(PG8_SA(0, 0), a2, voffA);
;             PG8_WAIT_V(8); PG8_WAIT_L(0); PG8_BAR; PG8_MMA(1, 0, At, B0); PG8_MMA(1, 1, At, B1); PG8_BAR; PG8_SCHED;
;             PG8_LDB(B0, 1, 0); PG8_LDB(B1, 1, 1); PG8_SCHED; PG8_LDA(At, 1, 0); PG8_STAGE(PG8_SA(0, 1), a2 + hstep, voffA);
;             PG8_WAIT_V(8); PG8_WAIT_L(0); PG8_BAR; PG8_MMA(0, 0, At, B0); PG8_MMA(0, 1, At, B1); PG8_BAR; PG8_SCHED;
;             PG8_LDA(At, 1, 1); PG8_STAGE(PG8_SB(1, 0), b3, voffB); PG8_STAGE(PG8_SB(1, 1), b3 + hstep, voffB); PG8_STAGE(PG8_SA(1, 0), a3, voffA);
;             PG8_WAIT_V(8); PG8_WAIT_L(0); PG8_BAR; PG8_MMA(1, 0, At, B0); PG8_MMA(1, 1, At, B1); PG8_BAR; PG8_SCHED;
	s_add_i32 s16, s33, s5
	v_lshl_add_u64 v[142:143], v[142:143], 0, s[34:35]
	s_mov_b32 m0, s16
	ds_read_b128 v[188:191], v146 offset:49152
	ds_read_b128 v[192:195], v146 offset:50176
	ds_read_b128 v[210:213], v146 offset:51200
	ds_read_b128 v[214:217], v146 offset:52224
	ds_read_b128 v[218:221], v146 offset:53248
	ds_read_b128 v[222:225], v146 offset:54272
	ds_read_b128 v[226:229], v146 offset:55296
	ds_read_b128 v[230:233], v146 offset:56320
	global_load_lds_dwordx4 v[142:143], off
	s_add_i32 m0, s16, 0x2000
	s_add_u32 s16, s46, 0x80080
	v_lshl_add_u64 v[142:143], v[152:153], 0, s[34:35]
	s_addc_u32 s17, s47, 0
	s_add_i32 s33, s70, s5
	global_load_lds_dwordx4 v[142:143], off
	s_mov_b32 m0, s33
	v_lshl_add_u64 v[142:143], s[16:17], 0, v[134:135]
	global_load_lds_dwordx4 v[142:143], off
	s_add_i32 m0, s33, 0x2000
	v_lshl_add_u64 v[142:143], s[16:17], 0, v[130:131]
	global_load_lds_dwordx4 v[142:143], off
	s_mov_b32 m0, s11
	v_lshl_add_u64 v[142:143], v[196:197], 0, s[34:35]
	global_load_lds_dwordx4 v[142:143], off
	s_mov_b32 m0, s18
	v_lshl_add_u64 v[142:143], v[234:235], 0, s[34:35]
	global_load_lds_dwordx4 v[142:143], off
	s_waitcnt vmcnt(8)
	s_waitcnt lgkmcnt(0)
	s_barrier
	v_mfma_f32_16x16x32_bf16 v[62:65], v[148:151], v[188:191], v[62:65]
	v_mfma_f32_16x16x32_bf16 v[58:61], v[164:167], v[188:191], v[58:61]
	v_mfma_f32_16x16x32_bf16 v[54:57], v[148:151], v[210:213], v[54:57]
	v_mfma_f32_16x16x32_bf16 v[46:49], v[164:167], v[210:213], v[46:49]
	v_mfma_f32_16x16x32_bf16 v[38:41], v[148:151], v[218:221], v[38:41]
	v_mfma_f32_16x16x32_bf16 v[30:33], v[164:167], v[218:221], v[30:33]
	v_mfma_f32_16x16x32_bf16 v[22:25], v[148:151], v[226:229], v[22:25]
	v_mfma_f32_16x16x32_bf16 v[14:17], v[164:167], v[226:229], v[14:17]
	v_mfma_f32_16x16x32_bf16 v[62:65], v[160:163], v[192:195], v[62:65]
	v_mfma_f32_16x16x32_bf16 v[58:61], v[168:171], v[192:195], v[58:61]
	v_mfma_f32_16x16x32_bf16 v[54:57], v[160:163], v[214:217], v[54:57]
	v_mfma_f32_16x16x32_bf16 v[46:49], v[168:171], v[214:217], v[46:49]
	v_mfma_f32_16x16x32_bf16 v[38:41], v[160:163], v[222:225], v[38:41]
	v_mfma_f32_16x16x32_bf16 v[30:33], v[168:171], v[222:225], v[30:33]
	v_mfma_f32_16x16x32_bf16 v[22:25], v[160:163], v[230:233], v[22:25]
	v_mfma_f32_16x16x32_bf16 v[14:17], v[168:171], v[230:233], v[14:17]
	v_mfma_f32_16x16x32_bf16 v[50:53], v[172:175], v[188:191], v[50:53]
	v_mfma_f32_16x16x32_bf16 v[42:45], v[180:183], v[188:191], v[42:45]
	v_mfma_f32_16x16x32_bf16 v[34:37], v[172:175], v[210:213], v[34:37]
	v_mfma_f32_16x16x32_bf16 v[26:29], v[180:183], v[210:213], v[26:29]
	v_mfma_f32_16x16x32_bf16 v[18:21], v[172:175], v[218:221], v[18:21]
	v_mfma_f32_16x16x32_bf16 v[10:13], v[180:183], v[218:221], v[10:13]
	v_mfma_f32_16x16x32_bf16 v[6:9], v[172:175], v[226:229], v[6:9]
	v_mfma_f32_16x16x32_bf16 v[2:5], v[180:183], v[226:229], v[2:5]
	v_mfma_f32_16x16x32_bf16 v[50:53], v[176:179], v[192:195], v[50:53]
	v_mfma_f32_16x16x32_bf16 v[42:45], v[184:187], v[192:195], v[42:45]
	v_mfma_f32_16x16x32_bf16 v[34:37], v[176:179], v[214:217], v[34:37]
	v_mfma_f32_16x16x32_bf16 v[26:29], v[184:187], v[214:217], v[26:29]
	v_mfma_f32_16x16x32_bf16 v[18:21], v[176:179], v[222:225], v[18:21]
	v_mfma_f32_16x16x32_bf16 v[10:13], v[184:187], v[222:225], v[10:13]
	v_mfma_f32_16x16x32_bf16 v[6:9], v[176:179], v[230:233], v[6:9]
	v_mfma_f32_16x16x32_bf16 v[2:5], v[184:187], v[230:233], v[2:5]
	s_barrier
	s_add_i32 s49, s49, 2
	s_add_u32 s80, s80, 0x100
	s_addc_u32 s81, s81, 0
	s_add_u32 s37, s37, 0x100
	s_addc_u32 s43, s43, 0
	s_cmp_gt_u32 s49, 29
	s_cbranch_scc0 .LBB0_106
.LBB0_106:
	s_add_u32 s16, s80, 0xfff80080
	s_addc_u32 s17, s81, -1
	s_add_i32 s33, 0, 0x10000
	s_cmp_eq_u32 s49, 28
	s_cselect_b32 vcc_hi, s30, s17
	s_cselect_b32 vcc_lo, s31, s16
	v_add_u32_e32 v142, s33, v144
	s_cselect_b32 s47, s21, s43
	s_cselect_b32 s46, s36, s37
	s_add_i32 s70, 0, 0x14000
	ds_read_b128 v[148:151], v142
	ds_read_b128 v[160:163], v142 offset:1024
	ds_read_b128 v[164:167], v142 offset:2048
	ds_read_b128 v[168:171], v142 offset:3072
	v_add_u32_e32 v142, s70, v144
	ds_read_b128 v[172:175], v142
	ds_read_b128 v[176:179], v142 offset:1024
	ds_read_b128 v[180:183], v142 offset:2048
	ds_read_b128 v[184:187], v142 offset:3072
	v_lshl_add_u64 v[142:143], s[80:81], 0, v[138:139]
	s_add_i32 m0, s7, 0xc000
	ds_read_b128 v[188:191], v146
	ds_read_b128 v[192:195], v146 offset:1024
	ds_read_b128 v[210:213], v146 offset:2048
	ds_read_b128 v[214:217], v146 offset:3072
	ds_read_b128 v[218:221], v146 offset:4096
	ds_read_b128 v[222:225], v146 offset:5120
	ds_read_b128 v[226:229], v146 offset:6144
	ds_read_b128 v[230:233], v146 offset:7168
	global_load_lds_dwordx4 v[142:143], off
	s_add_i32 m0, s7, 0xe000
	v_lshl_add_u64 v[142:143], s[80:81], 0, v[140:141]
	global_load_lds_dwordx4 v[142:143], off
	s_waitcnt vmcnt(8)
	s_waitcnt lgkmcnt(0)
	s_barrier
; #define PG8_STAGE(bufoff, gbase, voff) do { _Pragma("unroll") for (int _i = 0; _i < 2; ++_i) \
;         __builtin_amdgcn_global_load_lds((const unsigned*)((const char*)(gbase) + (voff)[_i]), (LAS unsigned*)(lds + (bufoff) + ldsw + _i * 8192), 16, 0, 0); } while (0)
; #define PG8_LDA(dst, b, h) do { _Pragma("unroll") for (int m = 0; m < 4; ++m) _Pragma("unroll") for (int k = 0; k < 2; ++k) dst[m][k] = *(const LAS bf16x8*)(lds + PG8_SA(b, h) + aoff + m * 2048 + k * 1024); } while (0)
; #define PG8_MMA(ai, bj, At, Bt) do { __builtin_amdgcn_s_setprio(1); _Pragma("unroll") for (int m = 0; m < 4; ++m) _Pragma("unroll") for (int n = 0; n < 2; ++n) _Pragma("unroll") for (int k = 0; k < 2; ++k) \
;         acc[ai][bj][m][n] = __builtin_amdgcn_mfma_f32_16x16x32_bf16(Bt[n][k], At[m][k], acc[ai][bj][m][n], 0, 0, 0); __builtin_amdgcn_s_setprio(0); } while (0)
; #define PG8_WAIT_V(n) asm volatile("s_waitcnt vmcnt(" #n ")" ::: "memory")
; #define PG8_WAIT_L(n) asm volatile("s_waitcnt lgkmcnt(" #n ")" ::: "memory")
; #define PG8_BAR __builtin_amdgcn_s_barrier()
; #define PG8_SCHED __builtin_amdgcn_sched_barrier(0)
; template <class Epi, class Sched = StaticOrder, bool ALIGN_EPI = true>
; __device__ __forceinline__ void gemm_phase(LAS unsigned char* lds, const Gemm g, const Sched& S, const Epi& E) {
;     ...
;             PG8_WAIT_V(8); PG8_WAIT_L(0); PG8_BAR; PG8_MMA(0, 0, At, B0); PG8_MMA(0, 1, At, B1); PG8_BAR; PG8_SCHED;
;             PG8_LDA(At, 0, 1); PG8_STAGE(PG8_SB(0, 0), b2, voffB); PG8_STAGE(PG8_SB(0, 1), b2 + hstep, voffB); PG8_STAGE(PG8_SA(0, 0), a2, voffA);
;             PG8_WAIT_V(8); PG8_WAIT_L(0); PG8_BAR; PG8_MMA(1, 0, At, B0); PG8_MMA(1, 1, At, B1); PG8_BAR; PG8_SCHED;
	v_mfma_f32_16x16x32_bf16 v[126:129], v[148:151], v[188:191], v[126:129]
	v_mfma_f32_16x16x32_bf16 v[122:125], v[164:167], v[188:191], v[122:125]
	v_mfma_f32_16x16x32_bf16 v[118:121], v[148:151], v[210:213], v[118:121]
	v_mfma_f32_16x16x32_bf16 v[110:113], v[164:167], v[210:213], v[110:113]
	v_mfma_f32_16x16x32_bf16 v[102:105], v[148:151], v[218:221], v[102:105]
	v_mfma_f32_16x16x32_bf16 v[94:97], v[164:167], v[218:221], v[94:97]
	v_mfma_f32_16x16x32_bf16 v[82:85], v[148:151], v[226:229], v[82:85]
	v_mfma_f32_16x16x32_bf16 v[74:77], v[164:167], v[226:229], v[74:77]
	v_mfma_f32_16x16x32_bf16 v[126:129], v[160:163], v[192:195], v[126:129]
	v_mfma_f32_16x16x32_bf16 v[122:125], v[168:171], v[192:195], v[122:125]
	v_mfma_f32_16x16x32_bf16 v[118:121], v[160:163], v[214:217], v[118:121]
	v_mfma_f32_16x16x32_bf16 v[110:113], v[168:171], v[214:217], v[110:113]
	v_mfma_f32_16x16x32_bf16 v[102:105], v[160:163], v[222:225], v[102:105]
	v_mfma_f32_16x16x32_bf16 v[94:97], v[168:171], v[222:225], v[94:97]
	v_mfma_f32_16x16x32_bf16 v[82:85], v[160:163], v[230:233], v[82:85]
	v_mfma_f32_16x16x32_bf16 v[74:77], v[168:171], v[230:233], v[74:77]
	v_mfma_f32_16x16x32_bf16 v[114:117], v[172:175], v[188:191], v[114:117]
	v_mfma_f32_16x16x32_bf16 v[106:109], v[180:183], v[188:191], v[106:109]
	v_mfma_f32_16x16x32_bf16 v[98:101], v[172:175], v[210:213], v[98:101]
	v_mfma_f32_16x16x32_bf16 v[90:93], v[180:183], v[210:213], v[90:93]
	v_mfma_f32_16x16x32_bf16 v[86:89], v[172:175], v[218:221], v[86:89]
	v_mfma_f32_16x16x32_bf16 v[78:81], v[180:183], v[218:221], v[78:81]
	v_mfma_f32_16x16x32_bf16 v[70:73], v[172:175], v[226:229], v[70:73]
	v_mfma_f32_16x16x32_bf16 v[66:69], v[180:183], v[226:229], v[66:69]
	v_mfma_f32_16x16x32_bf16 v[114:117], v[176:179], v[192:195], v[114:117]
	v_mfma_f32_16x16x32_bf16 v[106:109], v[184:187], v[192:195], v[106:109]
	v_mfma_f32_16x16x32_bf16 v[98:101], v[176:179], v[214:217], v[98:101]
	v_mfma_f32_16x16x32_bf16 v[90:93], v[184:187], v[214:217], v[90:93]
	v_mfma_f32_16x16x32_bf16 v[86:89], v[176:179], v[222:225], v[86:89]
	v_mfma_f32_16x16x32_bf16 v[78:81], v[184:187], v[222:225], v[78:81]
	v_mfma_f32_16x16x32_bf16 v[70:73], v[176:179], v[230:233], v[70:73]
	v_mfma_f32_16x16x32_bf16 v[66:69], v[184:187], v[230:233], v[66:69]
	s_barrier
	s_add_i32 s16, s33, s5
	v_lshl_add_u64 v[142:143], s[46:47], 0, v[134:135]
	s_mov_b32 m0, s16
	ds_read_b128 v[188:191], v146 offset:16384
	ds_read_b128 v[192:195], v146 offset:17408
	ds_read_b128 v[210:213], v146 offset:18432
	ds_read_b128 v[214:217], v146 offset:19456
	ds_read_b128 v[218:221], v146 offset:20480
	ds_read_b128 v[222:225], v146 offset:21504
	ds_read_b128 v[226:229], v146 offset:22528
	ds_read_b128 v[230:233], v146 offset:23552
	global_load_lds_dwordx4 v[142:143], off
	s_add_i32 m0, s16, 0x2000
	s_add_u32 s16, s46, 0x80000
	v_lshl_add_u64 v[152:153], s[46:47], 0, v[130:131]
	s_addc_u32 s17, s47, 0
	s_add_i32 s33, s70, s5
	global_load_lds_dwordx4 v[152:153], off
	v_lshl_add_u64 v[196:197], s[16:17], 0, v[134:135]
	s_mov_b32 m0, s33
	v_lshl_add_u64 v[234:235], vcc, 0, v[132:133]
	global_load_lds_dwordx4 v[196:197], off
	s_add_i32 m0, s33, 0x2000
	v_lshl_add_u64 v[196:197], s[16:17], 0, v[130:131]
	global_load_lds_dwordx4 v[196:197], off
	s_mov_b32 m0, s7
	v_lshl_add_u64 v[196:197], vcc, 0, v[136:137]
	global_load_lds_dwordx4 v[196:197], off
	s_mov_b32 m0, s8
	s_nop 0
	global_load_lds_dwordx4 v[234:235], off
	s_waitcnt vmcnt(8)
	s_waitcnt lgkmcnt(0)
	s_barrier
	v_mfma_f32_16x16x32_bf16 v[62:65], v[148:151], v[188:191], v[62:65]
	v_mfma_f32_16x16x32_bf16 v[58:61], v[164:167], v[188:191], v[58:61]
	v_mfma_f32_16x16x32_bf16 v[54:57], v[148:151], v[210:213], v[54:57]
	v_mfma_f32_16x16x32_bf16 v[46:49], v[164:167], v[210:213], v[46:49]
	v_mfma_f32_16x16x32_bf16 v[38:41], v[148:151], v[218:221], v[38:41]
	v_mfma_f32_16x16x32_bf16 v[30:33], v[164:167], v[218:221], v[30:33]
	v_mfma_f32_16x16x32_bf16 v[22:25], v[148:151], v[226:229], v[22:25]
	v_mfma_f32_16x16x32_bf16 v[14:17], v[164:167], v[226:229], v[14:17]
	v_mfma_f32_16x16x32_bf16 v[62:65], v[160:163], v[192:195], v[62:65]
	v_mfma_f32_16x16x32_bf16 v[58:61], v[168:171], v[192:195], v[58:61]
	v_mfma_f32_16x16x32_bf16 v[54:57], v[160:163], v[214:217], v[54:57]
	v_mfma_f32_16x16x32_bf16 v[46:49], v[168:171], v[214:217], v[46:49]
	v_mfma_f32_16x16x32_bf16 v[38:41], v[160:163], v[222:225], v[38:41]
	v_mfma_f32_16x16x32_bf16 v[30:33], v[168:171], v[222:225], v[30:33]
	v_mfma_f32_16x16x32_bf16 v[22:25], v[160:163], v[230:233], v[22:25]
	v_mfma_f32_16x16x32_bf16 v[14:17], v[168:171], v[230:233], v[14:17]
	v_mfma_f32_16x16x32_bf16 v[50:53], v[172:175], v[188:191], v[50:53]
	v_mfma_f32_16x16x32_bf16 v[42:45], v[180:183], v[188:191], v[42:45]
	v_mfma_f32_16x16x32_bf16 v[34:37], v[172:175], v[210:213], v[34:37]
	v_mfma_f32_16x16x32_bf16 v[26:29], v[180:183], v[210:213], v[26:29]
	v_mfma_f32_16x16x32_bf16 v[18:21], v[172:175], v[218:221], v[18:21]
	v_mfma_f32_16x16x32_bf16 v[10:13], v[180:183], v[218:221], v[10:13]
	v_mfma_f32_16x16x32_bf16 v[6:9], v[172:175], v[226:229], v[6:9]
	v_mfma_f32_16x16x32_bf16 v[2:5], v[180:183], v[226:229], v[2:5]
	v_mfma_f32_16x16x32_bf16 v[50:53], v[176:179], v[192:195], v[50:53]
	v_mfma_f32_16x16x32_bf16 v[42:45], v[184:187], v[192:195], v[42:45]
	v_mfma_f32_16x16x32_bf16 v[34:37], v[176:179], v[214:217], v[34:37]
	v_mfma_f32_16x16x32_bf16 v[26:29], v[184:187], v[214:217], v[26:29]
	v_mfma_f32_16x16x32_bf16 v[18:21], v[176:179], v[222:225], v[18:21]
	v_mfma_f32_16x16x32_bf16 v[10:13], v[184:187], v[222:225], v[10:13]
	v_mfma_f32_16x16x32_bf16 v[6:9], v[176:179], v[230:233], v[6:9]
	v_mfma_f32_16x16x32_bf16 v[2:5], v[184:187], v[230:233], v[2:5]
	s_barrier
; #define PG8_STAGE(bufoff, gbase, voff) do { _Pragma("unroll") for (int _i = 0; _i < 2; ++_i) \
;         __builtin_amdgcn_global_load_lds((const unsigned*)((const char*)(gbase) + (voff)[_i]), (LAS unsigned*)(lds + (bufoff) + ldsw + _i * 8192), 16, 0, 0); } while (0)
; #define PG8_LDA(dst, b, h) do { _Pragma("unroll") for (int m = 0; m < 4; ++m) _Pragma("unroll") for (int k = 0; k < 2; ++k) dst[m][k] = *(const LAS bf16x8*)(lds + PG8_SA(b, h) + aoff + m * 2048 + k * 1024); } while (0)
; #define PG8_LDB(dst, b, h) do { _Pragma("unroll") for (int n = 0; n < 2; ++n) _Pragma("unroll") for (int k = 0; k < 2; ++k) dst[n][k] = *(const LAS bf16x8*)(lds + PG8_SB(b, h) + boff + n * 2048 + k * 1024); } while (0)
; #define PG8_MMA(ai, bj, At, Bt) do { __builtin_amdgcn_s_setprio(1); _Pragma("unroll") for (int m = 0; m < 4; ++m) _Pragma("unroll") for (int n = 0; n < 2; ++n) _Pragma("unroll") for (int k = 0; k < 2; ++k) \
;         acc[ai][bj][m][n] = __builtin_amdgcn_mfma_f32_16x16x32_bf16(Bt[n][k], At[m][k], acc[ai][bj][m][n], 0, 0, 0); __builtin_amdgcn_s_setprio(0); } while (0)
; #define PG8_WAIT_V(n) asm volatile("s_waitcnt vmcnt(" #n ")" ::: "memory")
; #define PG8_WAIT_L(n) asm volatile("s_waitcnt lgkmcnt(" #n ")" ::: "memory")
; #define PG8_BAR __builtin_amdgcn_s_barrier()
; #define PG8_SCHED __builtin_amdgcn_sched_barrier(0)
; template <class Epi, class Sched = StaticOrder, bool ALIGN_EPI = true>
; __device__ __forceinline__ void gemm_phase(LAS unsigned char* lds, const Gemm g, const Sched& S, const Epi& E) {
;     ...
;             PG8_LDB(B0, 1, 0); PG8_LDB(B1, 1, 1); PG8_SCHED; PG8_LDA(At, 1, 0); PG8_STAGE(PG8_SA(0, 1), a2 + hstep, voffA);
;             PG8_WAIT_V(8); PG8_WAIT_L(0); PG8_BAR; PG8_MMA(0, 0, At, B0); PG8_MMA(0, 1, At, B1); PG8_BAR; PG8_SCHED;
;             PG8_LDA(At, 1, 1); PG8_STAGE(PG8_SB(1, 0), b3, voffB); PG8_STAGE(PG8_SB(1, 1), b3 + hstep, voffB); PG8_STAGE(PG8_SA(1, 0), a3, voffA);
;             PG8_WAIT_V(8); PG8_WAIT_L(0); PG8_BAR; PG8_MMA(1, 0, At, B0); PG8_MMA(1, 1, At, B1); PG8_BAR; PG8_SCHED;
	s_add_i32 s33, 0, 0x18000
	v_add_u32_e32 v147, s33, v144
	s_add_i32 s70, 0, 0x1c000
	ds_read_b128 v[148:151], v147
	ds_read_b128 v[160:163], v147 offset:1024
	ds_read_b128 v[164:167], v147 offset:2048
	ds_read_b128 v[168:171], v147 offset:3072
	v_add_u32_e32 v147, s70, v144
	ds_read_b128 v[172:175], v147
	ds_read_b128 v[176:179], v147 offset:1024
	ds_read_b128 v[180:183], v147 offset:2048
	ds_read_b128 v[184:187], v147 offset:3072
	s_add_u32 s16, vcc_lo, 0x80000
	s_addc_u32 s17, vcc_hi, 0
	s_mov_b32 m0, s9
	v_lshl_add_u64 v[236:237], s[16:17], 0, v[136:137]
	ds_read_b128 v[188:191], v146 offset:32768
	ds_read_b128 v[192:195], v146 offset:33792
	ds_read_b128 v[210:213], v146 offset:34816
	ds_read_b128 v[214:217], v146 offset:35840
	ds_read_b128 v[218:221], v146 offset:36864
	ds_read_b128 v[222:225], v146 offset:37888
	ds_read_b128 v[226:229], v146 offset:38912
	ds_read_b128 v[230:233], v146 offset:39936
	global_load_lds_dwordx4 v[236:237], off
	s_mov_b32 m0, s10
	v_lshl_add_u64 v[236:237], s[16:17], 0, v[132:133]
	global_load_lds_dwordx4 v[236:237], off
	s_waitcnt vmcnt(8)
	s_waitcnt lgkmcnt(0)
	s_barrier
	v_mfma_f32_16x16x32_bf16 v[126:129], v[148:151], v[188:191], v[126:129]
	v_mfma_f32_16x16x32_bf16 v[122:125], v[164:167], v[188:191], v[122:125]
	v_mfma_f32_16x16x32_bf16 v[118:121], v[148:151], v[210:213], v[118:121]
	v_mfma_f32_16x16x32_bf16 v[110:113], v[164:167], v[210:213], v[110:113]
	v_mfma_f32_16x16x32_bf16 v[102:105], v[148:151], v[218:221], v[102:105]
	v_mfma_f32_16x16x32_bf16 v[94:97], v[164:167], v[218:221], v[94:97]
	v_mfma_f32_16x16x32_bf16 v[82:85], v[148:151], v[226:229], v[82:85]
	v_mfma_f32_16x16x32_bf16 v[74:77], v[164:167], v[226:229], v[74:77]
	v_mfma_f32_16x16x32_bf16 v[126:129], v[160:163], v[192:195], v[126:129]
	v_mfma_f32_16x16x32_bf16 v[122:125], v[168:171], v[192:195], v[122:125]
	v_mfma_f32_16x16x32_bf16 v[118:121], v[160:163], v[214:217], v[118:121]
	v_mfma_f32_16x16x32_bf16 v[110:113], v[168:171], v[214:217], v[110:113]
	v_mfma_f32_16x16x32_bf16 v[102:105], v[160:163], v[222:225], v[102:105]
	v_mfma_f32_16x16x32_bf16 v[94:97], v[168:171], v[222:225], v[94:97]
	v_mfma_f32_16x16x32_bf16 v[82:85], v[160:163], v[230:233], v[82:85]
	v_mfma_f32_16x16x32_bf16 v[74:77], v[168:171], v[230:233], v[74:77]
	v_mfma_f32_16x16x32_bf16 v[114:117], v[172:175], v[188:191], v[114:117]
	v_mfma_f32_16x16x32_bf16 v[106:109], v[180:183], v[188:191], v[106:109]
	v_mfma_f32_16x16x32_bf16 v[98:101], v[172:175], v[210:213], v[98:101]
	v_mfma_f32_16x16x32_bf16 v[90:93], v[180:183], v[210:213], v[90:93]
	v_mfma_f32_16x16x32_bf16 v[86:89], v[172:175], v[218:221], v[86:89]
	v_mfma_f32_16x16x32_bf16 v[78:81], v[180:183], v[218:221], v[78:81]
	v_mfma_f32_16x16x32_bf16 v[70:73], v[172:175], v[226:229], v[70:73]
	v_mfma_f32_16x16x32_bf16 v[66:69], v[180:183], v[226:229], v[66:69]
	v_mfma_f32_16x16x32_bf16 v[114:117], v[176:179], v[192:195], v[114:117]
	v_mfma_f32_16x16x32_bf16 v[106:109], v[184:187], v[192:195], v[106:109]
	v_mfma_f32_16x16x32_bf16 v[98:101], v[176:179], v[214:217], v[98:101]
	v_mfma_f32_16x16x32_bf16 v[90:93], v[184:187], v[214:217], v[90:93]
	v_mfma_f32_16x16x32_bf16 v[86:89], v[176:179], v[222:225], v[86:89]
	v_mfma_f32_16x16x32_bf16 v[78:81], v[184:187], v[222:225], v[78:81]
	v_mfma_f32_16x16x32_bf16 v[70:73], v[176:179], v[230:233], v[70:73]
	v_mfma_f32_16x16x32_bf16 v[66:69], v[184:187], v[230:233], v[66:69]
	s_barrier
	s_add_i32 s16, s33, s5
	v_lshl_add_u64 v[142:143], v[142:143], 0, s[34:35]
	s_mov_b32 m0, s16
	ds_read_b128 v[188:191], v146 offset:49152
	ds_read_b128 v[192:195], v146 offset:50176
	ds_read_b128 v[210:213], v146 offset:51200
	ds_read_b128 v[214:217], v146 offset:52224
	ds_read_b128 v[218:221], v146 offset:53248
	ds_read_b128 v[222:225], v146 offset:54272
	ds_read_b128 v[226:229], v146 offset:55296
	ds_read_b128 v[230:233], v146 offset:56320
	global_load_lds_dwordx4 v[142:143], off
	s_add_i32 m0, s16, 0x2000
	s_add_u32 s16, s46, 0x80080
	v_lshl_add_u64 v[142:143], v[152:153], 0, s[34:35]
	s_addc_u32 s17, s47, 0
	s_add_i32 s33, s70, s5
	global_load_lds_dwordx4 v[142:143], off
	s_mov_b32 m0, s33
	v_lshl_add_u64 v[142:143], s[16:17], 0, v[134:135]
	global_load_lds_dwordx4 v[142:143], off
	s_add_i32 m0, s33, 0x2000
	v_lshl_add_u64 v[142:143], s[16:17], 0, v[130:131]
	global_load_lds_dwordx4 v[142:143], off
	s_mov_b32 m0, s11
	v_lshl_add_u64 v[142:143], v[196:197], 0, s[34:35]
	global_load_lds_dwordx4 v[142:143], off
	s_mov_b32 m0, s18
	v_lshl_add_u64 v[142:143], v[234:235], 0, s[34:35]
	global_load_lds_dwordx4 v[142:143], off
	s_waitcnt vmcnt(8)
	s_waitcnt lgkmcnt(0)
	s_barrier
	v_mfma_f32_16x16x32_bf16 v[62:65], v[148:151], v[188:191], v[62:65]
	v_mfma_f32_16x16x32_bf16 v[58:61], v[164:167], v[188:191], v[58:61]
	v_mfma_f32_16x16x32_bf16 v[54:57], v[148:151], v[210:213], v[54:57]
	v_mfma_f32_16x16x32_bf16 v[46:49], v[164:167], v[210:213], v[46:49]
	v_mfma_f32_16x16x32_bf16 v[38:41], v[148:151], v[218:221], v[38:41]
	v_mfma_f32_16x16x32_bf16 v[30:33], v[164:167], v[218:221], v[30:33]
	v_mfma_f32_16x16x32_bf16 v[22:25], v[148:151], v[226:229], v[22:25]
	v_mfma_f32_16x16x32_bf16 v[14:17], v[164:167], v[226:229], v[14:17]
	v_mfma_f32_16x16x32_bf16 v[62:65], v[160:163], v[192:195], v[62:65]
	v_mfma_f32_16x16x32_bf16 v[58:61], v[168:171], v[192:195], v[58:61]
	v_mfma_f32_16x16x32_bf16 v[54:57], v[160:163], v[214:217], v[54:57]
	v_mfma_f32_16x16x32_bf16 v[46:49], v[168:171], v[214:217], v[46:49]
	v_mfma_f32_16x16x32_bf16 v[38:41], v[160:163], v[222:225], v[38:41]
	v_mfma_f32_16x16x32_bf16 v[30:33], v[168:171], v[222:225], v[30:33]
	v_mfma_f32_16x16x32_bf16 v[22:25], v[160:163], v[230:233], v[22:25]
	v_mfma_f32_16x16x32_bf16 v[14:17], v[168:171], v[230:233], v[14:17]
	v_mfma_f32_16x16x32_bf16 v[50:53], v[172:175], v[188:191], v[50:53]
	v_mfma_f32_16x16x32_bf16 v[42:45], v[180:183], v[188:191], v[42:45]
	v_mfma_f32_16x16x32_bf16 v[34:37], v[172:175], v[210:213], v[34:37]
	v_mfma_f32_16x16x32_bf16 v[26:29], v[180:183], v[210:213], v[26:29]
	v_mfma_f32_16x16x32_bf16 v[18:21], v[172:175], v[218:221], v[18:21]
	v_mfma_f32_16x16x32_bf16 v[10:13], v[180:183], v[218:221], v[10:13]
	v_mfma_f32_16x16x32_bf16 v[6:9], v[172:175], v[226:229], v[6:9]
	v_mfma_f32_16x16x32_bf16 v[2:5], v[180:183], v[226:229], v[2:5]
	v_mfma_f32_16x16x32_bf16 v[50:53], v[176:179], v[192:195], v[50:53]
	v_mfma_f32_16x16x32_bf16 v[42:45], v[184:187], v[192:195], v[42:45]
	v_mfma_f32_16x16x32_bf16 v[34:37], v[176:179], v[214:217], v[34:37]
	v_mfma_f32_16x16x32_bf16 v[26:29], v[184:187], v[214:217], v[26:29]
	v_mfma_f32_16x16x32_bf16 v[18:21], v[176:179], v[222:225], v[18:21]
	v_mfma_f32_16x16x32_bf16 v[10:13], v[184:187], v[222:225], v[10:13]
	v_mfma_f32_16x16x32_bf16 v[6:9], v[176:179], v[230:233], v[6:9]
	v_mfma_f32_16x16x32_bf16 v[2:5], v[184:187], v[230:233], v[2:5]
	s_barrier
	s_add_i32 s49, s49, 2
	s_add_u32 s80, s80, 0x100
	s_addc_u32 s81, s81, 0
	s_add_u32 s37, s37, 0x100
	s_addc_u32 s43, s43, 0
	s_cmp_gt_u32 s49, 29
	s_cbranch_scc0 .LBB0_106

; #define PG8_STAGE(bufoff, gbase, voff) do { _Pragma("unroll") for (int _i = 0; _i < 2; ++_i) \
;         __builtin_amdgcn_global_load_lds((const unsigned*)((const char*)(gbase) + (voff)[_i]), (LAS unsigned*)(lds + (bufoff) + ldsw + _i * 8192), 16, 0, 0); } while (0)
; #define PG8_LDA(dst, b, h) do { _Pragma("unroll") for (int m = 0; m < 4; ++m) _Pragma("unroll") for (int k = 0; k < 2; ++k) dst[m][k] = *(const LAS bf16x8*)(lds + PG8_SA(b, h) + aoff + m * 2048 + k * 1024); } while (0)
; #define PG8_LDB(dst, b, h) do { _Pragma("unroll") for (int n = 0; n < 2; ++n) _Pragma("unroll") for (int k = 0; k < 2; ++k) dst[n][k] = *(const LAS bf16x8*)(lds + PG8_SB(b, h) + boff + n * 2048 + k * 1024); } while (0)
; #define PG8_MMA(ai, bj, At, Bt) do { __builtin_amdgcn_s_setprio(1); _Pragma("unroll") for (int m = 0; m < 4; ++m) _Pragma("unroll") for (int n = 0; n < 2; ++n) _Pragma("unroll") for (int k = 0; k < 2; ++k) \
;         acc[ai][bj][m][n] = __builtin_amdgcn_mfma_f32_16x16x32_bf16(Bt[n][k], At[m][k], acc[ai][bj][m][n], 0, 0, 0); __builtin_amdgcn_s_setprio(0); } while (0)
; #define PG8_WAIT_V(n) asm volatile("s_waitcnt vmcnt(" #n ")" ::: "memory")
; #define PG8_WAIT_L(n) asm volatile("s_waitcnt lgkmcnt(" #n ")" ::: "memory")
; #define PG8_BAR __builtin_amdgcn_s_barrier()
; #define PG8_SCHED __builtin_amdgcn_sched_barrier(0)
; template <class Epi, class Sched = StaticOrder, bool ALIGN_EPI = true>
; __device__ __forceinline__ void gemm_phase(LAS unsigned char* lds, const Gemm g, const Sched& S, const Epi& E) {
;     ...
;         for (int t = 0; t < nt; t += 2) {
;             const bool last = (t == nt - 2);
;             const char* a1 = cA + (size_t)(t + 1) * kstep;
;             const char* a2 = last ? nA : cA + (size_t)(t + 2) * kstep; const char* b2 = last ? nB : cB + (size_t)(t + 2) * kstep;
;             const char* a3 = a2 + kstep; const char* b3 = b2 + kstep;
;             PG8_LDB(B0, 0, 0); PG8_LDB(B1, 0, 1); PG8_SCHED; PG8_LDA(At, 0, 0); PG8_STAGE(PG8_SA(1, 1), a1 + hstep, voffA);
;             PG8_WAIT_V(8); PG8_WAIT_L(0); PG8_BAR; PG8_MMA(0, 0, At, B0); PG8_MMA(0, 1, At, B1); PG8_BAR; PG8_SCHED;
;             PG8_LDA(At, 0, 1); PG8_STAGE(PG8_SB(0, 0), b2, voffB); PG8_STAGE(PG8_SB(0, 1), b2 + hstep, voffB); PG8_STAGE(PG8_SA(0, 0), a2, voffA);
;             PG8_WAIT_V(8); PG8_WAIT_L(0); PG8_BAR; PG8_MMA(1, 0, At, B0); PG8_MMA(1, 1, At, B1); PG8_BAR; PG8_SCHED;
.Lmy_nb_336:
	s_add_u32 s0, s80, 0xfff80080
	s_addc_u32 s1, s81, -1
	s_add_i32 s16, 0, 0x10000
	s_cmp_eq_u32 s79, 28
	s_cselect_b32 s31, s36, s1
	s_cselect_b32 s30, s37, s0
	v_add_u32_e32 v142, s16, v144
	s_cselect_b32 s1, s21, s70
	s_cselect_b32 s0, s43, s49
	s_add_i32 s33, 0, 0x14000
	ds_read_b128 v[148:151], v142
	ds_read_b128 v[160:163], v142 offset:1024
	ds_read_b128 v[164:167], v142 offset:2048
	ds_read_b128 v[168:171], v142 offset:3072
	v_add_u32_e32 v142, s33, v144
	ds_read_b128 v[172:175], v142
	ds_read_b128 v[176:179], v142 offset:1024
	ds_read_b128 v[180:183], v142 offset:2048
	ds_read_b128 v[184:187], v142 offset:3072
	v_lshl_add_u64 v[142:143], s[80:81], 0, v[138:139]
	s_add_i32 m0, s7, 0xc000
	ds_read_b128 v[188:191], v146
	ds_read_b128 v[192:195], v146 offset:1024
	ds_read_b128 v[210:213], v146 offset:2048
	ds_read_b128 v[214:217], v146 offset:3072
	ds_read_b128 v[218:221], v146 offset:4096
	ds_read_b128 v[222:225], v146 offset:5120
	ds_read_b128 v[226:229], v146 offset:6144
	ds_read_b128 v[230:233], v146 offset:7168
	global_load_lds_dwordx4 v[142:143], off
	s_add_i32 m0, s7, 0xe000
	v_lshl_add_u64 v[142:143], s[80:81], 0, v[140:141]
	global_load_lds_dwordx4 v[142:143], off
	s_waitcnt vmcnt(8)
	s_waitcnt lgkmcnt(0)
	s_barrier
	v_mfma_f32_16x16x32_bf16 v[126:129], v[148:151], v[188:191], 0
	v_mfma_f32_16x16x32_bf16 v[122:125], v[164:167], v[188:191], 0
	v_mfma_f32_16x16x32_bf16 v[118:121], v[148:151], v[210:213], 0
	v_mfma_f32_16x16x32_bf16 v[110:113], v[164:167], v[210:213], 0
	v_mfma_f32_16x16x32_bf16 v[102:105], v[148:151], v[218:221], 0
	v_mfma_f32_16x16x32_bf16 v[94:97], v[164:167], v[218:221], 0
	v_mfma_f32_16x16x32_bf16 v[86:89], v[148:151], v[226:229], 0
	v_mfma_f32_16x16x32_bf16 v[78:81], v[164:167], v[226:229], 0
	v_mfma_f32_16x16x32_bf16 v[126:129], v[160:163], v[192:195], v[126:129]
	v_mfma_f32_16x16x32_bf16 v[122:125], v[168:171], v[192:195], v[122:125]
	v_mfma_f32_16x16x32_bf16 v[118:121], v[160:163], v[214:217], v[118:121]
	v_mfma_f32_16x16x32_bf16 v[110:113], v[168:171], v[214:217], v[110:113]
	v_mfma_f32_16x16x32_bf16 v[102:105], v[160:163], v[222:225], v[102:105]
	v_mfma_f32_16x16x32_bf16 v[94:97], v[168:171], v[222:225], v[94:97]
	v_mfma_f32_16x16x32_bf16 v[86:89], v[160:163], v[230:233], v[86:89]
	v_mfma_f32_16x16x32_bf16 v[78:81], v[168:171], v[230:233], v[78:81]
	v_mfma_f32_16x16x32_bf16 v[114:117], v[172:175], v[188:191], 0
	v_mfma_f32_16x16x32_bf16 v[106:109], v[180:183], v[188:191], 0
	v_mfma_f32_16x16x32_bf16 v[98:101], v[172:175], v[210:213], 0
	v_mfma_f32_16x16x32_bf16 v[90:93], v[180:183], v[210:213], 0
	v_mfma_f32_16x16x32_bf16 v[82:85], v[172:175], v[218:221], 0
	v_mfma_f32_16x16x32_bf16 v[74:77], v[180:183], v[218:221], 0
	v_mfma_f32_16x16x32_bf16 v[70:73], v[172:175], v[226:229], 0
	v_mfma_f32_16x16x32_bf16 v[66:69], v[180:183], v[226:229], 0
	v_mfma_f32_16x16x32_bf16 v[114:117], v[176:179], v[192:195], v[114:117]
	v_mfma_f32_16x16x32_bf16 v[106:109], v[184:187], v[192:195], v[106:109]
	v_mfma_f32_16x16x32_bf16 v[98:101], v[176:179], v[214:217], v[98:101]
	v_mfma_f32_16x16x32_bf16 v[90:93], v[184:187], v[214:217], v[90:93]
	v_mfma_f32_16x16x32_bf16 v[82:85], v[176:179], v[222:225], v[82:85]
	v_mfma_f32_16x16x32_bf16 v[74:77], v[184:187], v[222:225], v[74:77]
	v_mfma_f32_16x16x32_bf16 v[70:73], v[176:179], v[230:233], v[70:73]
	v_mfma_f32_16x16x32_bf16 v[66:69], v[184:187], v[230:233], v[66:69]
	s_barrier
	s_add_i32 s16, s16, s5
	v_lshl_add_u64 v[142:143], s[0:1], 0, v[134:135]
	s_mov_b32 m0, s16
	ds_read_b128 v[188:191], v146 offset:16384
	ds_read_b128 v[192:195], v146 offset:17408
	ds_read_b128 v[210:213], v146 offset:18432
	ds_read_b128 v[214:217], v146 offset:19456
	ds_read_b128 v[218:221], v146 offset:20480
	ds_read_b128 v[222:225], v146 offset:21504
	ds_read_b128 v[226:229], v146 offset:22528
	ds_read_b128 v[230:233], v146 offset:23552
	global_load_lds_dwordx4 v[142:143], off
	s_add_i32 m0, s16, 0x2000
	s_add_u32 s16, s0, 0x80000
	v_lshl_add_u64 v[152:153], s[0:1], 0, v[130:131]
	s_addc_u32 s17, s1, 0
	s_add_i32 s33, s33, s5
	global_load_lds_dwordx4 v[152:153], off
	v_lshl_add_u64 v[196:197], s[16:17], 0, v[134:135]
	s_mov_b32 m0, s33
	v_lshl_add_u64 v[234:235], s[30:31], 0, v[132:133]
	global_load_lds_dwordx4 v[196:197], off
	s_add_i32 m0, s33, 0x2000
	v_lshl_add_u64 v[196:197], s[16:17], 0, v[130:131]
	global_load_lds_dwordx4 v[196:197], off
	s_mov_b32 m0, s7
	v_lshl_add_u64 v[196:197], s[30:31], 0, v[136:137]
	global_load_lds_dwordx4 v[196:197], off
	s_mov_b32 m0, s8
	s_nop 0
	global_load_lds_dwordx4 v[234:235], off
	s_waitcnt vmcnt(8)
	s_waitcnt lgkmcnt(0)
	s_barrier
; #define PG8_STAGE(bufoff, gbase, voff) do { _Pragma("unroll") for (int _i = 0; _i < 2; ++_i) \
;         __builtin_amdgcn_global_load_lds((const unsigned*)((const char*)(gbase) + (voff)[_i]), (LAS unsigned*)(lds + (bufoff) + ldsw + _i * 8192), 16, 0, 0); } while (0)
; #define PG8_LDA(dst, b, h) do { _Pragma("unroll") for (int m = 0; m < 4; ++m) _Pragma("unroll") for (int k = 0; k < 2; ++k) dst[m][k] = *(const LAS bf16x8*)(lds + PG8_SA(b, h) + aoff + m * 2048 + k * 1024); } while (0)
; #define PG8_LDB(dst, b, h) do { _Pragma("unroll") for (int n = 0; n < 2; ++n) _Pragma("unroll") for (int k = 0; k < 2; ++k) dst[n][k] = *(const LAS bf16x8*)(lds + PG8_SB(b, h) + boff + n * 2048 + k * 1024); } while (0)
; #define PG8_MMA(ai, bj, At, Bt) do { __builtin_amdgcn_s_setprio(1); _Pragma("unroll") for (int m = 0; m < 4; ++m) _Pragma("unroll") for (int n = 0; n < 2; ++n) _Pragma("unroll") for (int k = 0; k < 2; ++k) \
;         acc[ai][bj][m][n] = __builtin_amdgcn_mfma_f32_16x16x32_bf16(Bt[n][k], At[m][k], acc[ai][bj][m][n], 0, 0, 0); __builtin_amdgcn_s_setprio(0); } while (0)
; #define PG8_WAIT_V(n) asm volatile("s_waitcnt vmcnt(" #n ")" ::: "memory")
; #define PG8_WAIT_L(n) asm volatile("s_waitcnt lgkmcnt(" #n ")" ::: "memory")
; #define PG8_BAR __builtin_amdgcn_s_barrier()
; #define PG8_SCHED __builtin_amdgcn_sched_barrier(0)
; template <class Epi, class Sched = StaticOrder, bool ALIGN_EPI = true>
; __device__ __forceinline__ void gemm_phase(LAS unsigned char* lds, const Gemm g, const Sched& S, const Epi& E) {
;     ...
;             PG8_WAIT_V(8); PG8_WAIT_L(0); PG8_BAR; PG8_MMA(1, 0, At, B0); PG8_MMA(1, 1, At, B1); PG8_BAR; PG8_SCHED;
;             PG8_LDB(B0, 1, 0); PG8_LDB(B1, 1, 1); PG8_SCHED; PG8_LDA(At, 1, 0); PG8_STAGE(PG8_SA(0, 1), a2 + hstep, voffA);
;             PG8_WAIT_V(8); PG8_WAIT_L(0); PG8_BAR; PG8_MMA(0, 0, At, B0); PG8_MMA(0, 1, At, B1); PG8_BAR; PG8_SCHED;
	v_mfma_f32_16x16x32_bf16 v[62:65], v[148:151], v[188:191], 0
	v_mfma_f32_16x16x32_bf16 v[58:61], v[164:167], v[188:191], 0
	v_mfma_f32_16x16x32_bf16 v[54:57], v[148:151], v[210:213], 0
	v_mfma_f32_16x16x32_bf16 v[46:49], v[164:167], v[210:213], 0
	v_mfma_f32_16x16x32_bf16 v[38:41], v[148:151], v[218:221], 0
	v_mfma_f32_16x16x32_bf16 v[30:33], v[164:167], v[218:221], 0
	v_mfma_f32_16x16x32_bf16 v[22:25], v[148:151], v[226:229], 0
	v_mfma_f32_16x16x32_bf16 v[14:17], v[164:167], v[226:229], 0
	v_mfma_f32_16x16x32_bf16 v[62:65], v[160:163], v[192:195], v[62:65]
	v_mfma_f32_16x16x32_bf16 v[58:61], v[168:171], v[192:195], v[58:61]
	v_mfma_f32_16x16x32_bf16 v[54:57], v[160:163], v[214:217], v[54:57]
	v_mfma_f32_16x16x32_bf16 v[46:49], v[168:171], v[214:217], v[46:49]
	v_mfma_f32_16x16x32_bf16 v[38:41], v[160:163], v[222:225], v[38:41]
	v_mfma_f32_16x16x32_bf16 v[30:33], v[168:171], v[222:225], v[30:33]
	v_mfma_f32_16x16x32_bf16 v[22:25], v[160:163], v[230:233], v[22:25]
	v_mfma_f32_16x16x32_bf16 v[14:17], v[168:171], v[230:233], v[14:17]
	v_mfma_f32_16x16x32_bf16 v[50:53], v[172:175], v[188:191], 0
	v_mfma_f32_16x16x32_bf16 v[42:45], v[180:183], v[188:191], 0
	v_mfma_f32_16x16x32_bf16 v[34:37], v[172:175], v[210:213], 0
	v_mfma_f32_16x16x32_bf16 v[26:29], v[180:183], v[210:213], 0
	v_mfma_f32_16x16x32_bf16 v[18:21], v[172:175], v[218:221], 0
	v_mfma_f32_16x16x32_bf16 v[10:13], v[180:183], v[218:221], 0
	v_mfma_f32_16x16x32_bf16 v[6:9], v[172:175], v[226:229], 0
	v_mfma_f32_16x16x32_bf16 v[2:5], v[180:183], v[226:229], 0
	v_mfma_f32_16x16x32_bf16 v[50:53], v[176:179], v[192:195], v[50:53]
	v_mfma_f32_16x16x32_bf16 v[42:45], v[184:187], v[192:195], v[42:45]
	v_mfma_f32_16x16x32_bf16 v[34:37], v[176:179], v[214:217], v[34:37]
	v_mfma_f32_16x16x32_bf16 v[26:29], v[184:187], v[214:217], v[26:29]
	v_mfma_f32_16x16x32_bf16 v[18:21], v[176:179], v[222:225], v[18:21]
	v_mfma_f32_16x16x32_bf16 v[10:13], v[184:187], v[222:225], v[10:13]
	v_mfma_f32_16x16x32_bf16 v[6:9], v[176:179], v[230:233], v[6:9]
	v_mfma_f32_16x16x32_bf16 v[2:5], v[184:187], v[230:233], v[2:5]
	s_barrier
	s_add_i32 s33, 0, 0x18000
	v_add_u32_e32 v147, s33, v144
	s_add_i32 s82, 0, 0x1c000
	ds_read_b128 v[148:151], v147
	ds_read_b128 v[160:163], v147 offset:1024
	ds_read_b128 v[164:167], v147 offset:2048
	ds_read_b128 v[168:171], v147 offset:3072
	v_add_u32_e32 v147, s82, v144
	ds_read_b128 v[172:175], v147
	ds_read_b128 v[176:179], v147 offset:1024
	ds_read_b128 v[180:183], v147 offset:2048
	ds_read_b128 v[184:187], v147 offset:3072
	s_add_u32 s16, s30, 0x80000
	s_addc_u32 s17, s31, 0
	s_mov_b32 m0, s9
	v_lshl_add_u64 v[236:237], s[16:17], 0, v[136:137]
	ds_read_b128 v[188:191], v146 offset:32768
	ds_read_b128 v[192:195], v146 offset:33792
	ds_read_b128 v[210:213], v146 offset:34816
	ds_read_b128 v[214:217], v146 offset:35840
	ds_read_b128 v[218:221], v146 offset:36864
	ds_read_b128 v[222:225], v146 offset:37888
	ds_read_b128 v[226:229], v146 offset:38912
	ds_read_b128 v[230:233], v146 offset:39936
	global_load_lds_dwordx4 v[236:237], off
	s_mov_b32 m0, s10
	v_lshl_add_u64 v[236:237], s[16:17], 0, v[132:133]
	global_load_lds_dwordx4 v[236:237], off
	s_waitcnt vmcnt(8)
	s_waitcnt lgkmcnt(0)
	s_barrier
	v_mfma_f32_16x16x32_bf16 v[126:129], v[148:151], v[188:191], v[126:129]
	v_mfma_f32_16x16x32_bf16 v[122:125], v[164:167], v[188:191], v[122:125]
	v_mfma_f32_16x16x32_bf16 v[118:121], v[148:151], v[210:213], v[118:121]
	v_mfma_f32_16x16x32_bf16 v[110:113], v[164:167], v[210:213], v[110:113]
	v_mfma_f32_16x16x32_bf16 v[102:105], v[148:151], v[218:221], v[102:105]
	v_mfma_f32_16x16x32_bf16 v[94:97], v[164:167], v[218:221], v[94:97]
	v_mfma_f32_16x16x32_bf16 v[86:89], v[148:151], v[226:229], v[86:89]
	v_mfma_f32_16x16x32_bf16 v[78:81], v[164:167], v[226:229], v[78:81]
	v_mfma_f32_16x16x32_bf16 v[126:129], v[160:163], v[192:195], v[126:129]
	v_mfma_f32_16x16x32_bf16 v[122:125], v[168:171], v[192:195], v[122:125]
	v_mfma_f32_16x16x32_bf16 v[118:121], v[160:163], v[214:217], v[118:121]
	v_mfma_f32_16x16x32_bf16 v[110:113], v[168:171], v[214:217], v[110:113]
	v_mfma_f32_16x16x32_bf16 v[102:105], v[160:163], v[222:225], v[102:105]
	v_mfma_f32_16x16x32_bf16 v[94:97], v[168:171], v[222:225], v[94:97]
	v_mfma_f32_16x16x32_bf16 v[86:89], v[160:163], v[230:233], v[86:89]
	v_mfma_f32_16x16x32_bf16 v[78:81], v[168:171], v[230:233], v[78:81]
	v_mfma_f32_16x16x32_bf16 v[114:117], v[172:175], v[188:191], v[114:117]
	v_mfma_f32_16x16x32_bf16 v[106:109], v[180:183], v[188:191], v[106:109]
	v_mfma_f32_16x16x32_bf16 v[98:101], v[172:175], v[210:213], v[98:101]
	v_mfma_f32_16x16x32_bf16 v[90:93], v[180:183], v[210:213], v[90:93]
	v_mfma_f32_16x16x32_bf16 v[82:85], v[172:175], v[218:221], v[82:85]
	v_mfma_f32_16x16x32_bf16 v[74:77], v[180:183], v[218:221], v[74:77]
	v_mfma_f32_16x16x32_bf16 v[70:73], v[172:175], v[226:229], v[70:73]
	v_mfma_f32_16x16x32_bf16 v[66:69], v[180:183], v[226:229], v[66:69]
	v_mfma_f32_16x16x32_bf16 v[114:117], v[176:179], v[192:195], v[114:117]
	v_mfma_f32_16x16x32_bf16 v[106:109], v[184:187], v[192:195], v[106:109]
	v_mfma_f32_16x16x32_bf16 v[98:101], v[176:179], v[214:217], v[98:101]
	v_mfma_f32_16x16x32_bf16 v[90:93], v[184:187], v[214:217], v[90:93]
	v_mfma_f32_16x16x32_bf16 v[82:85], v[176:179], v[222:225], v[82:85]
	v_mfma_f32_16x16x32_bf16 v[74:77], v[184:187], v[222:225], v[74:77]
	v_mfma_f32_16x16x32_bf16 v[70:73], v[176:179], v[230:233], v[70:73]
	v_mfma_f32_16x16x32_bf16 v[66:69], v[184:187], v[230:233], v[66:69]
	s_barrier
; #define PG8_STAGE(bufoff, gbase, voff) do { _Pragma("unroll") for (int _i = 0; _i < 2; ++_i) \
;         __builtin_amdgcn_global_load_lds((const unsigned*)((const char*)(gbase) + (voff)[_i]), (LAS unsigned*)(lds + (bufoff) + ldsw + _i * 8192), 16, 0, 0); } while (0)
; #define PG8_LDA(dst, b, h) do { _Pragma("unroll") for (int m = 0; m < 4; ++m) _Pragma("unroll") for (int k = 0; k < 2; ++k) dst[m][k] = *(const LAS bf16x8*)(lds + PG8_SA(b, h) + aoff + m * 2048 + k * 1024); } while (0)
; #define PG8_LDB(dst, b, h) do { _Pragma("unroll") for (int n = 0; n < 2; ++n) _Pragma("unroll") for (int k = 0; k < 2; ++k) dst[n][k] = *(const LAS bf16x8*)(lds + PG8_SB(b, h) + boff + n * 2048 + k * 1024); } while (0)
; #define PG8_MMA(ai, bj, At, Bt) do { __builtin_amdgcn_s_setprio(1); _Pragma("unroll") for (int m = 0; m < 4; ++m) _Pragma("unroll") for (int n = 0; n < 2; ++n) _Pragma("unroll") for (int k = 0; k < 2; ++k) \
;         acc[ai][bj][m][n] = __builtin_amdgcn_mfma_f32_16x16x32_bf16(Bt[n][k], At[m][k], acc[ai][bj][m][n], 0, 0, 0); __builtin_amdgcn_s_setprio(0); } while (0)
; #define PG8_WAIT_V(n) asm volatile("s_waitcnt vmcnt(" #n ")" ::: "memory")
; #define PG8_WAIT_L(n) asm volatile("s_waitcnt lgkmcnt(" #n ")" ::: "memory")
; #define PG8_BAR __builtin_amdgcn_s_barrier()
; #define PG8_SCHED __builtin_amdgcn_sched_barrier(0)
; template <class Epi, class Sched = StaticOrder, bool ALIGN_EPI = true>
; __device__ __forceinline__ void gemm_phase(LAS unsigned char* lds, const Gemm g, const Sched& S, const Epi& E) {
;     ...
;         for (int t = 0; t < nt; t += 2) {
;             const bool last = (t == nt - 2);
;             const char* a1 = cA + (size_t)(t + 1) * kstep;
;             const char* a2 = last ? nA : cA + (size_t)(t + 2) * kstep; const char* b2 = last ? nB : cB + (size_t)(t + 2) * kstep;
;             const char* a3 = a2 + kstep; const char* b3 = b2 + kstep;
;             PG8_LDB(B0, 0, 0); PG8_LDB(B1, 0, 1); PG8_SCHED; PG8_LDA(At, 0, 0); PG8_STAGE(PG8_SA(1, 1), a1 + hstep, voffA);
;     ...
;             PG8_LDA(At, 1, 1); PG8_STAGE(PG8_SB(1, 0), b3, voffB); PG8_STAGE(PG8_SB(1, 1), b3 + hstep, voffB); PG8_STAGE(PG8_SA(1, 0), a3, voffA);
;             PG8_WAIT_V(8); PG8_WAIT_L(0); PG8_BAR; PG8_MMA(1, 0, At, B0); PG8_MMA(1, 1, At, B1); PG8_BAR; PG8_SCHED;
	s_add_i32 s16, s33, s5
	v_lshl_add_u64 v[142:143], v[142:143], 0, s[34:35]
	s_mov_b32 m0, s16
	ds_read_b128 v[188:191], v146 offset:49152
	ds_read_b128 v[192:195], v146 offset:50176
	ds_read_b128 v[210:213], v146 offset:51200
	ds_read_b128 v[214:217], v146 offset:52224
	ds_read_b128 v[218:221], v146 offset:53248
	ds_read_b128 v[222:225], v146 offset:54272
	ds_read_b128 v[226:229], v146 offset:55296
	ds_read_b128 v[230:233], v146 offset:56320
	global_load_lds_dwordx4 v[142:143], off
	s_add_i32 m0, s16, 0x2000
	s_add_u32 s0, s0, 0x80080
	v_lshl_add_u64 v[142:143], v[152:153], 0, s[34:35]
	s_addc_u32 s1, s1, 0
	s_add_i32 s16, s82, s5
	global_load_lds_dwordx4 v[142:143], off
	s_mov_b32 m0, s16
	v_lshl_add_u64 v[142:143], s[0:1], 0, v[134:135]
	global_load_lds_dwordx4 v[142:143], off
	s_add_i32 m0, s16, 0x2000
	v_lshl_add_u64 v[142:143], s[0:1], 0, v[130:131]
	global_load_lds_dwordx4 v[142:143], off
	s_mov_b32 m0, s11
	v_lshl_add_u64 v[142:143], v[196:197], 0, s[34:35]
	global_load_lds_dwordx4 v[142:143], off
	s_mov_b32 m0, s18
	v_lshl_add_u64 v[142:143], v[234:235], 0, s[34:35]
	global_load_lds_dwordx4 v[142:143], off
	s_waitcnt vmcnt(8)
	s_waitcnt lgkmcnt(0)
	s_barrier
	v_mfma_f32_16x16x32_bf16 v[62:65], v[148:151], v[188:191], v[62:65]
	v_mfma_f32_16x16x32_bf16 v[58:61], v[164:167], v[188:191], v[58:61]
	v_mfma_f32_16x16x32_bf16 v[54:57], v[148:151], v[210:213], v[54:57]
	v_mfma_f32_16x16x32_bf16 v[46:49], v[164:167], v[210:213], v[46:49]
	v_mfma_f32_16x16x32_bf16 v[38:41], v[148:151], v[218:221], v[38:41]
	v_mfma_f32_16x16x32_bf16 v[30:33], v[164:167], v[218:221], v[30:33]
	v_mfma_f32_16x16x32_bf16 v[22:25], v[148:151], v[226:229], v[22:25]
	v_mfma_f32_16x16x32_bf16 v[14:17], v[164:167], v[226:229], v[14:17]
	v_mfma_f32_16x16x32_bf16 v[62:65], v[160:163], v[192:195], v[62:65]
	v_mfma_f32_16x16x32_bf16 v[58:61], v[168:171], v[192:195], v[58:61]
	v_mfma_f32_16x16x32_bf16 v[54:57], v[160:163], v[214:217], v[54:57]
	v_mfma_f32_16x16x32_bf16 v[46:49], v[168:171], v[214:217], v[46:49]
	v_mfma_f32_16x16x32_bf16 v[38:41], v[160:163], v[222:225], v[38:41]
	v_mfma_f32_16x16x32_bf16 v[30:33], v[168:171], v[222:225], v[30:33]
	v_mfma_f32_16x16x32_bf16 v[22:25], v[160:163], v[230:233], v[22:25]
	v_mfma_f32_16x16x32_bf16 v[14:17], v[168:171], v[230:233], v[14:17]
	v_mfma_f32_16x16x32_bf16 v[50:53], v[172:175], v[188:191], v[50:53]
	v_mfma_f32_16x16x32_bf16 v[42:45], v[180:183], v[188:191], v[42:45]
	v_mfma_f32_16x16x32_bf16 v[34:37], v[172:175], v[210:213], v[34:37]
	v_mfma_f32_16x16x32_bf16 v[26:29], v[180:183], v[210:213], v[26:29]
	v_mfma_f32_16x16x32_bf16 v[18:21], v[172:175], v[218:221], v[18:21]
	v_mfma_f32_16x16x32_bf16 v[10:13], v[180:183], v[218:221], v[10:13]
	v_mfma_f32_16x16x32_bf16 v[6:9], v[172:175], v[226:229], v[6:9]
	v_mfma_f32_16x16x32_bf16 v[2:5], v[180:183], v[226:229], v[2:5]
	v_mfma_f32_16x16x32_bf16 v[50:53], v[176:179], v[192:195], v[50:53]
	v_mfma_f32_16x16x32_bf16 v[42:45], v[184:187], v[192:195], v[42:45]
	v_mfma_f32_16x16x32_bf16 v[34:37], v[176:179], v[214:217], v[34:37]
	v_mfma_f32_16x16x32_bf16 v[26:29], v[184:187], v[214:217], v[26:29]
	v_mfma_f32_16x16x32_bf16 v[18:21], v[176:179], v[222:225], v[18:21]
	v_mfma_f32_16x16x32_bf16 v[10:13], v[184:187], v[222:225], v[10:13]
	v_mfma_f32_16x16x32_bf16 v[6:9], v[176:179], v[230:233], v[6:9]
	v_mfma_f32_16x16x32_bf16 v[2:5], v[184:187], v[230:233], v[2:5]
	s_barrier
	s_add_i32 s79, s79, 2
	s_add_u32 s80, s80, 0x100
	s_addc_u32 s81, s81, 0
	s_add_u32 s49, s49, 0x100
	s_addc_u32 s70, s70, 0
	s_cmp_gt_u32 s79, 29
	s_cbranch_scc0 .LBB0_336
.LBB0_336:
	s_add_u32 s0, s80, 0xfff80080
	s_addc_u32 s1, s81, -1
	s_add_i32 s16, 0, 0x10000
	s_cmp_eq_u32 s79, 28
	s_cselect_b32 s31, s36, s1
	s_cselect_b32 s30, s37, s0
	v_add_u32_e32 v142, s16, v144
	s_cselect_b32 s1, s21, s70
	s_cselect_b32 s0, s43, s49
	s_add_i32 s33, 0, 0x14000
	ds_read_b128 v[148:151], v142
	ds_read_b128 v[160:163], v142 offset:1024
	ds_read_b128 v[164:167], v142 offset:2048
	ds_read_b128 v[168:171], v142 offset:3072
	v_add_u32_e32 v142, s33, v144
	ds_read_b128 v[172:175], v142
	ds_read_b128 v[176:179], v142 offset:1024
	ds_read_b128 v[180:183], v142 offset:2048
	ds_read_b128 v[184:187], v142 offset:3072
	v_lshl_add_u64 v[142:143], s[80:81], 0, v[138:139]
	s_add_i32 m0, s7, 0xc000
	ds_read_b128 v[188:191], v146
	ds_read_b128 v[192:195], v146 offset:1024
	ds_read_b128 v[210:213], v146 offset:2048
	ds_read_b128 v[214:217], v146 offset:3072
	ds_read_b128 v[218:221], v146 offset:4096
	ds_read_b128 v[222:225], v146 offset:5120
	ds_read_b128 v[226:229], v146 offset:6144
	ds_read_b128 v[230:233], v146 offset:7168
	global_load_lds_dwordx4 v[142:143], off
	s_add_i32 m0, s7, 0xe000
	v_lshl_add_u64 v[142:143], s[80:81], 0, v[140:141]
	global_load_lds_dwordx4 v[142:143], off
	s_waitcnt vmcnt(8)
	s_waitcnt lgkmcnt(0)
	s_barrier
; #define PG8_STAGE(bufoff, gbase, voff) do { _Pragma("unroll") for (int _i = 0; _i < 2; ++_i) \
;         __builtin_amdgcn_global_load_lds((const unsigned*)((const char*)(gbase) + (voff)[_i]), (LAS unsigned*)(lds + (bufoff) + ldsw + _i * 8192), 16, 0, 0); } while (0)
; #define PG8_LDA(dst, b, h) do { _Pragma("unroll") for (int m = 0; m < 4; ++m) _Pragma("unroll") for (int k = 0; k < 2; ++k) dst[m][k] = *(const LAS bf16x8*)(lds + PG8_SA(b, h) + aoff + m * 2048 + k * 1024); } while (0)
; #define PG8_MMA(ai, bj, At, Bt) do { __builtin_amdgcn_s_setprio(1); _Pragma("unroll") for (int m = 0; m < 4; ++m) _Pragma("unroll") for (int n = 0; n < 2; ++n) _Pragma("unroll") for (int k = 0; k < 2; ++k) \
;         acc[ai][bj][m][n] = __builtin_amdgcn_mfma_f32_16x16x32_bf16(Bt[n][k], At[m][k], acc[ai][bj][m][n], 0, 0, 0); __builtin_amdgcn_s_setprio(0); } while (0)
; #define PG8_WAIT_V(n) asm volatile("s_waitcnt vmcnt(" #n ")" ::: "memory")
; #define PG8_WAIT_L(n) asm volatile("s_waitcnt lgkmcnt(" #n ")" ::: "memory")
; #define PG8_BAR __builtin_amdgcn_s_barrier()
; #define PG8_SCHED __builtin_amdgcn_sched_barrier(0)
; template <class Epi, class Sched = StaticOrder, bool ALIGN_EPI = true>
; __device__ __forceinline__ void gemm_phase(LAS unsigned char* lds, const Gemm g, const Sched& S, const Epi& E) {
;     ...
;             PG8_WAIT_V(8); PG8_WAIT_L(0); PG8_BAR; PG8_MMA(0, 0, At, B0); PG8_MMA(0, 1, At, B1); PG8_BAR; PG8_SCHED;
;             PG8_LDA(At, 0, 1); PG8_STAGE(PG8_SB(0, 0), b2, voffB); PG8_STAGE(PG8_SB(0, 1), b2 + hstep, voffB); PG8_STAGE(PG8_SA(0, 0), a2, voffA);
;             PG8_WAIT_V(8); PG8_WAIT_L(0); PG8_BAR; PG8_MMA(1, 0, At, B0); PG8_MMA(1, 1, At, B1); PG8_BAR; PG8_SCHED;
	v_mfma_f32_16x16x32_bf16 v[126:129], v[148:151], v[188:191], v[126:129]
	v_mfma_f32_16x16x32_bf16 v[122:125], v[164:167], v[188:191], v[122:125]
	v_mfma_f32_16x16x32_bf16 v[118:121], v[148:151], v[210:213], v[118:121]
	v_mfma_f32_16x16x32_bf16 v[110:113], v[164:167], v[210:213], v[110:113]
	v_mfma_f32_16x16x32_bf16 v[102:105], v[148:151], v[218:221], v[102:105]
	v_mfma_f32_16x16x32_bf16 v[94:97], v[164:167], v[218:221], v[94:97]
	v_mfma_f32_16x16x32_bf16 v[86:89], v[148:151], v[226:229], v[86:89]
	v_mfma_f32_16x16x32_bf16 v[78:81], v[164:167], v[226:229], v[78:81]
	v_mfma_f32_16x16x32_bf16 v[126:129], v[160:163], v[192:195], v[126:129]
	v_mfma_f32_16x16x32_bf16 v[122:125], v[168:171], v[192:195], v[122:125]
	v_mfma_f32_16x16x32_bf16 v[118:121], v[160:163], v[214:217], v[118:121]
	v_mfma_f32_16x16x32_bf16 v[110:113], v[168:171], v[214:217], v[110:113]
	v_mfma_f32_16x16x32_bf16 v[102:105], v[160:163], v[222:225], v[102:105]
	v_mfma_f32_16x16x32_bf16 v[94:97], v[168:171], v[222:225], v[94:97]
	v_mfma_f32_16x16x32_bf16 v[86:89], v[160:163], v[230:233], v[86:89]
	v_mfma_f32_16x16x32_bf16 v[78:81], v[168:171], v[230:233], v[78:81]
	v_mfma_f32_16x16x32_bf16 v[114:117], v[172:175], v[188:191], v[114:117]
	v_mfma_f32_16x16x32_bf16 v[106:109], v[180:183], v[188:191], v[106:109]
	v_mfma_f32_16x16x32_bf16 v[98:101], v[172:175], v[210:213], v[98:101]
	v_mfma_f32_16x16x32_bf16 v[90:93], v[180:183], v[210:213], v[90:93]
	v_mfma_f32_16x16x32_bf16 v[82:85], v[172:175], v[218:221], v[82:85]
	v_mfma_f32_16x16x32_bf16 v[74:77], v[180:183], v[218:221], v[74:77]
	v_mfma_f32_16x16x32_bf16 v[70:73], v[172:175], v[226:229], v[70:73]
	v_mfma_f32_16x16x32_bf16 v[66:69], v[180:183], v[226:229], v[66:69]
	v_mfma_f32_16x16x32_bf16 v[114:117], v[176:179], v[192:195], v[114:117]
	v_mfma_f32_16x16x32_bf16 v[106:109], v[184:187], v[192:195], v[106:109]
	v_mfma_f32_16x16x32_bf16 v[98:101], v[176:179], v[214:217], v[98:101]
	v_mfma_f32_16x16x32_bf16 v[90:93], v[184:187], v[214:217], v[90:93]
	v_mfma_f32_16x16x32_bf16 v[82:85], v[176:179], v[222:225], v[82:85]
	v_mfma_f32_16x16x32_bf16 v[74:77], v[184:187], v[222:225], v[74:77]
	v_mfma_f32_16x16x32_bf16 v[70:73], v[176:179], v[230:233], v[70:73]
	v_mfma_f32_16x16x32_bf16 v[66:69], v[184:187], v[230:233], v[66:69]
	s_barrier
	s_add_i32 s16, s16, s5
	v_lshl_add_u64 v[142:143], s[0:1], 0, v[134:135]
	s_mov_b32 m0, s16
	ds_read_b128 v[188:191], v146 offset:16384
	ds_read_b128 v[192:195], v146 offset:17408
	ds_read_b128 v[210:213], v146 offset:18432
	ds_read_b128 v[214:217], v146 offset:19456
	ds_read_b128 v[218:221], v146 offset:20480
	ds_read_b128 v[222:225], v146 offset:21504
	ds_read_b128 v[226:229], v146 offset:22528
	ds_read_b128 v[230:233], v146 offset:23552
	global_load_lds_dwordx4 v[142:143], off
	s_add_i32 m0, s16, 0x2000
	s_add_u32 s16, s0, 0x80000
	v_lshl_add_u64 v[152:153], s[0:1], 0, v[130:131]
	s_addc_u32 s17, s1, 0
	s_add_i32 s33, s33, s5
	global_load_lds_dwordx4 v[152:153], off
	v_lshl_add_u64 v[196:197], s[16:17], 0, v[134:135]
	s_mov_b32 m0, s33
	v_lshl_add_u64 v[234:235], s[30:31], 0, v[132:133]
	global_load_lds_dwordx4 v[196:197], off
	s_add_i32 m0, s33, 0x2000
	v_lshl_add_u64 v[196:197], s[16:17], 0, v[130:131]
	global_load_lds_dwordx4 v[196:197], off
	s_mov_b32 m0, s7
	v_lshl_add_u64 v[196:197], s[30:31], 0, v[136:137]
	global_load_lds_dwordx4 v[196:197], off
	s_mov_b32 m0, s8
	s_nop 0
	global_load_lds_dwordx4 v[234:235], off
	s_waitcnt vmcnt(8)
	s_waitcnt lgkmcnt(0)
	s_barrier
	v_mfma_f32_16x16x32_bf16 v[62:65], v[148:151], v[188:191], v[62:65]
	v_mfma_f32_16x16x32_bf16 v[58:61], v[164:167], v[188:191], v[58:61]
	v_mfma_f32_16x16x32_bf16 v[54:57], v[148:151], v[210:213], v[54:57]
	v_mfma_f32_16x16x32_bf16 v[46:49], v[164:167], v[210:213], v[46:49]
	v_mfma_f32_16x16x32_bf16 v[38:41], v[148:151], v[218:221], v[38:41]
	v_mfma_f32_16x16x32_bf16 v[30:33], v[164:167], v[218:221], v[30:33]
	v_mfma_f32_16x16x32_bf16 v[22:25], v[148:151], v[226:229], v[22:25]
	v_mfma_f32_16x16x32_bf16 v[14:17], v[164:167], v[226:229], v[14:17]
	v_mfma_f32_16x16x32_bf16 v[62:65], v[160:163], v[192:195], v[62:65]
	v_mfma_f32_16x16x32_bf16 v[58:61], v[168:171], v[192:195], v[58:61]
	v_mfma_f32_16x16x32_bf16 v[54:57], v[160:163], v[214:217], v[54:57]
	v_mfma_f32_16x16x32_bf16 v[46:49], v[168:171], v[214:217], v[46:49]
	v_mfma_f32_16x16x32_bf16 v[38:41], v[160:163], v[222:225], v[38:41]
	v_mfma_f32_16x16x32_bf16 v[30:33], v[168:171], v[222:225], v[30:33]
	v_mfma_f32_16x16x32_bf16 v[22:25], v[160:163], v[230:233], v[22:25]
	v_mfma_f32_16x16x32_bf16 v[14:17], v[168:171], v[230:233], v[14:17]
	v_mfma_f32_16x16x32_bf16 v[50:53], v[172:175], v[188:191], v[50:53]
	v_mfma_f32_16x16x32_bf16 v[42:45], v[180:183], v[188:191], v[42:45]
	v_mfma_f32_16x16x32_bf16 v[34:37], v[172:175], v[210:213], v[34:37]
	v_mfma_f32_16x16x32_bf16 v[26:29], v[180:183], v[210:213], v[26:29]
	v_mfma_f32_16x16x32_bf16 v[18:21], v[172:175], v[218:221], v[18:21]
	v_mfma_f32_16x16x32_bf16 v[10:13], v[180:183], v[218:221], v[10:13]
	v_mfma_f32_16x16x32_bf16 v[6:9], v[172:175], v[226:229], v[6:9]
	v_mfma_f32_16x16x32_bf16 v[2:5], v[180:183], v[226:229], v[2:5]
	v_mfma_f32_16x16x32_bf16 v[50:53], v[176:179], v[192:195], v[50:53]
	v_mfma_f32_16x16x32_bf16 v[42:45], v[184:187], v[192:195], v[42:45]
	v_mfma_f32_16x16x32_bf16 v[34:37], v[176:179], v[214:217], v[34:37]
	v_mfma_f32_16x16x32_bf16 v[26:29], v[184:187], v[214:217], v[26:29]
	v_mfma_f32_16x16x32_bf16 v[18:21], v[176:179], v[222:225], v[18:21]
	v_mfma_f32_16x16x32_bf16 v[10:13], v[184:187], v[222:225], v[10:13]
	v_mfma_f32_16x16x32_bf16 v[6:9], v[176:179], v[230:233], v[6:9]
	v_mfma_f32_16x16x32_bf16 v[2:5], v[184:187], v[230:233], v[2:5]
	s_barrier
; #define PG8_STAGE(bufoff, gbase, voff) do { _Pragma("unroll") for (int _i = 0; _i < 2; ++_i) \
;         __builtin_amdgcn_global_load_lds((const unsigned*)((const char*)(gbase) + (voff)[_i]), (LAS unsigned*)(lds + (bufoff) + ldsw + _i * 8192), 16, 0, 0); } while (0)
; #define PG8_LDA(dst, b, h) do { _Pragma("unroll") for (int m = 0; m < 4; ++m) _Pragma("unroll") for (int k = 0; k < 2; ++k) dst[m][k] = *(const LAS bf16x8*)(lds + PG8_SA(b, h) + aoff + m * 2048 + k * 1024); } while (0)
; #define PG8_LDB(dst, b, h) do { _Pragma("unroll") for (int n = 0; n < 2; ++n) _Pragma("unroll") for (int k = 0; k < 2; ++k) dst[n][k] = *(const LAS bf16x8*)(lds + PG8_SB(b, h) + boff + n * 2048 + k * 1024); } while (0)
; #define PG8_MMA(ai, bj, At, Bt) do { __builtin_amdgcn_s_setprio(1); _Pragma("unroll") for (int m = 0; m < 4; ++m) _Pragma("unroll") for (int n = 0; n < 2; ++n) _Pragma("unroll") for (int k = 0; k < 2; ++k) \
;         acc[ai][bj][m][n] = __builtin_amdgcn_mfma_f32_16x16x32_bf16(Bt[n][k], At[m][k], acc[ai][bj][m][n], 0, 0, 0); __builtin_amdgcn_s_setprio(0); } while (0)
; #define PG8_WAIT_V(n) asm volatile("s_waitcnt vmcnt(" #n ")" ::: "memory")
; #define PG8_WAIT_L(n) asm volatile("s_waitcnt lgkmcnt(" #n ")" ::: "memory")
; #define PG8_BAR __builtin_amdgcn_s_barrier()
; #define PG8_SCHED __builtin_amdgcn_sched_barrier(0)
; template <class Epi, class Sched = StaticOrder, bool ALIGN_EPI = true>
; __device__ __forceinline__ void gemm_phase(LAS unsigned char* lds, const Gemm g, const Sched& S, const Epi& E) {
;     ...
;             PG8_LDB(B0, 1, 0); PG8_LDB(B1, 1, 1); PG8_SCHED; PG8_LDA(At, 1, 0); PG8_STAGE(PG8_SA(0, 1), a2 + hstep, voffA);
;             PG8_WAIT_V(8); PG8_WAIT_L(0); PG8_BAR; PG8_MMA(0, 0, At, B0); PG8_MMA(0, 1, At, B1); PG8_BAR; PG8_SCHED;
;             PG8_LDA(At, 1, 1); PG8_STAGE(PG8_SB(1, 0), b3, voffB); PG8_STAGE(PG8_SB(1, 1), b3 + hstep, voffB); PG8_STAGE(PG8_SA(1, 0), a3, voffA);
;             PG8_WAIT_V(8); PG8_WAIT_L(0); PG8_BAR; PG8_MMA(1, 0, At, B0); PG8_MMA(1, 1, At, B1); PG8_BAR; PG8_SCHED;
	s_add_i32 s33, 0, 0x18000
	v_add_u32_e32 v147, s33, v144
	s_add_i32 s82, 0, 0x1c000
	ds_read_b128 v[148:151], v147
	ds_read_b128 v[160:163], v147 offset:1024
	ds_read_b128 v[164:167], v147 offset:2048
	ds_read_b128 v[168:171], v147 offset:3072
	v_add_u32_e32 v147, s82, v144
	ds_read_b128 v[172:175], v147
	ds_read_b128 v[176:179], v147 offset:1024
	ds_read_b128 v[180:183], v147 offset:2048
	ds_read_b128 v[184:187], v147 offset:3072
	s_add_u32 s16, s30, 0x80000
	s_addc_u32 s17, s31, 0
	s_mov_b32 m0, s9
	v_lshl_add_u64 v[236:237], s[16:17], 0, v[136:137]
	ds_read_b128 v[188:191], v146 offset:32768
	ds_read_b128 v[192:195], v146 offset:33792
	ds_read_b128 v[210:213], v146 offset:34816
	ds_read_b128 v[214:217], v146 offset:35840
	ds_read_b128 v[218:221], v146 offset:36864
	ds_read_b128 v[222:225], v146 offset:37888
	ds_read_b128 v[226:229], v146 offset:38912
	ds_read_b128 v[230:233], v146 offset:39936
	global_load_lds_dwordx4 v[236:237], off
	s_mov_b32 m0, s10
	v_lshl_add_u64 v[236:237], s[16:17], 0, v[132:133]
	global_load_lds_dwordx4 v[236:237], off
	s_waitcnt vmcnt(8)
	s_waitcnt lgkmcnt(0)
	s_barrier
	v_mfma_f32_16x16x32_bf16 v[126:129], v[148:151], v[188:191], v[126:129]
	v_mfma_f32_16x16x32_bf16 v[122:125], v[164:167], v[188:191], v[122:125]
	v_mfma_f32_16x16x32_bf16 v[118:121], v[148:151], v[210:213], v[118:121]
	v_mfma_f32_16x16x32_bf16 v[110:113], v[164:167], v[210:213], v[110:113]
	v_mfma_f32_16x16x32_bf16 v[102:105], v[148:151], v[218:221], v[102:105]
	v_mfma_f32_16x16x32_bf16 v[94:97], v[164:167], v[218:221], v[94:97]
	v_mfma_f32_16x16x32_bf16 v[86:89], v[148:151], v[226:229], v[86:89]
	v_mfma_f32_16x16x32_bf16 v[78:81], v[164:167], v[226:229], v[78:81]
	v_mfma_f32_16x16x32_bf16 v[126:129], v[160:163], v[192:195], v[126:129]
	v_mfma_f32_16x16x32_bf16 v[122:125], v[168:171], v[192:195], v[122:125]
	v_mfma_f32_16x16x32_bf16 v[118:121], v[160:163], v[214:217], v[118:121]
	v_mfma_f32_16x16x32_bf16 v[110:113], v[168:171], v[214:217], v[110:113]
	v_mfma_f32_16x16x32_bf16 v[102:105], v[160:163], v[222:225], v[102:105]
	v_mfma_f32_16x16x32_bf16 v[94:97], v[168:171], v[222:225], v[94:97]
	v_mfma_f32_16x16x32_bf16 v[86:89], v[160:163], v[230:233], v[86:89]
	v_mfma_f32_16x16x32_bf16 v[78:81], v[168:171], v[230:233], v[78:81]
	v_mfma_f32_16x16x32_bf16 v[114:117], v[172:175], v[188:191], v[114:117]
	v_mfma_f32_16x16x32_bf16 v[106:109], v[180:183], v[188:191], v[106:109]
	v_mfma_f32_16x16x32_bf16 v[98:101], v[172:175], v[210:213], v[98:101]
	v_mfma_f32_16x16x32_bf16 v[90:93], v[180:183], v[210:213], v[90:93]
	v_mfma_f32_16x16x32_bf16 v[82:85], v[172:175], v[218:221], v[82:85]
	v_mfma_f32_16x16x32_bf16 v[74:77], v[180:183], v[218:221], v[74:77]
	v_mfma_f32_16x16x32_bf16 v[70:73], v[172:175], v[226:229], v[70:73]
	v_mfma_f32_16x16x32_bf16 v[66:69], v[180:183], v[226:229], v[66:69]
	v_mfma_f32_16x16x32_bf16 v[114:117], v[176:179], v[192:195], v[114:117]
	v_mfma_f32_16x16x32_bf16 v[106:109], v[184:187], v[192:195], v[106:109]
	v_mfma_f32_16x16x32_bf16 v[98:101], v[176:179], v[214:217], v[98:101]
	v_mfma_f32_16x16x32_bf16 v[90:93], v[184:187], v[214:217], v[90:93]
	v_mfma_f32_16x16x32_bf16 v[82:85], v[176:179], v[222:225], v[82:85]
	v_mfma_f32_16x16x32_bf16 v[74:77], v[184:187], v[222:225], v[74:77]
	v_mfma_f32_16x16x32_bf16 v[70:73], v[176:179], v[230:233], v[70:73]
	v_mfma_f32_16x16x32_bf16 v[66:69], v[184:187], v[230:233], v[66:69]
	s_barrier
	s_add_i32 s16, s33, s5
	v_lshl_add_u64 v[142:143], v[142:143], 0, s[34:35]
	s_mov_b32 m0, s16
	ds_read_b128 v[188:191], v146 offset:49152
	ds_read_b128 v[192:195], v146 offset:50176
	ds_read_b128 v[210:213], v146 offset:51200
	ds_read_b128 v[214:217], v146 offset:52224
	ds_read_b128 v[218:221], v146 offset:53248
	ds_read_b128 v[222:225], v146 offset:54272
	ds_read_b128 v[226:229], v146 offset:55296
	ds_read_b128 v[230:233], v146 offset:56320
	global_load_lds_dwordx4 v[142:143], off
	s_add_i32 m0, s16, 0x2000
	s_add_u32 s0, s0, 0x80080
	v_lshl_add_u64 v[142:143], v[152:153], 0, s[34:35]
	s_addc_u32 s1, s1, 0
	s_add_i32 s16, s82, s5
	global_load_lds_dwordx4 v[142:143], off
	s_mov_b32 m0, s16
	v_lshl_add_u64 v[142:143], s[0:1], 0, v[134:135]
	global_load_lds_dwordx4 v[142:143], off
	s_add_i32 m0, s16, 0x2000
	v_lshl_add_u64 v[142:143], s[0:1], 0, v[130:131]
	global_load_lds_dwordx4 v[142:143], off
	s_mov_b32 m0, s11
	v_lshl_add_u64 v[142:143], v[196:197], 0, s[34:35]
	global_load_lds_dwordx4 v[142:143], off
	s_mov_b32 m0, s18
	v_lshl_add_u64 v[142:143], v[234:235], 0, s[34:35]
	global_load_lds_dwordx4 v[142:143], off
	s_waitcnt vmcnt(8)
	s_waitcnt lgkmcnt(0)
	s_barrier
	v_mfma_f32_16x16x32_bf16 v[62:65], v[148:151], v[188:191], v[62:65]
	v_mfma_f32_16x16x32_bf16 v[58:61], v[164:167], v[188:191], v[58:61]
	v_mfma_f32_16x16x32_bf16 v[54:57], v[148:151], v[210:213], v[54:57]
	v_mfma_f32_16x16x32_bf16 v[46:49], v[164:167], v[210:213], v[46:49]
	v_mfma_f32_16x16x32_bf16 v[38:41], v[148:151], v[218:221], v[38:41]
	v_mfma_f32_16x16x32_bf16 v[30:33], v[164:167], v[218:221], v[30:33]
	v_mfma_f32_16x16x32_bf16 v[22:25], v[148:151], v[226:229], v[22:25]
	v_mfma_f32_16x16x32_bf16 v[14:17], v[164:167], v[226:229], v[14:17]
	v_mfma_f32_16x16x32_bf16 v[62:65], v[160:163], v[192:195], v[62:65]
	v_mfma_f32_16x16x32_bf16 v[58:61], v[168:171], v[192:195], v[58:61]
	v_mfma_f32_16x16x32_bf16 v[54:57], v[160:163], v[214:217], v[54:57]
	v_mfma_f32_16x16x32_bf16 v[46:49], v[168:171], v[214:217], v[46:49]
	v_mfma_f32_16x16x32_bf16 v[38:41], v[160:163], v[222:225], v[38:41]
	v_mfma_f32_16x16x32_bf16 v[30:33], v[168:171], v[222:225], v[30:33]
	v_mfma_f32_16x16x32_bf16 v[22:25], v[160:163], v[230:233], v[22:25]
	v_mfma_f32_16x16x32_bf16 v[14:17], v[168:171], v[230:233], v[14:17]
	v_mfma_f32_16x16x32_bf16 v[50:53], v[172:175], v[188:191], v[50:53]
	v_mfma_f32_16x16x32_bf16 v[42:45], v[180:183], v[188:191], v[42:45]
	v_mfma_f32_16x16x32_bf16 v[34:37], v[172:175], v[210:213], v[34:37]
	v_mfma_f32_16x16x32_bf16 v[26:29], v[180:183], v[210:213], v[26:29]
	v_mfma_f32_16x16x32_bf16 v[18:21], v[172:175], v[218:221], v[18:21]
	v_mfma_f32_16x16x32_bf16 v[10:13], v[180:183], v[218:221], v[10:13]
	v_mfma_f32_16x16x32_bf16 v[6:9], v[172:175], v[226:229], v[6:9]
	v_mfma_f32_16x16x32_bf16 v[2:5], v[180:183], v[226:229], v[2:5]
	v_mfma_f32_16x16x32_bf16 v[50:53], v[176:179], v[192:195], v[50:53]
	v_mfma_f32_16x16x32_bf16 v[42:45], v[184:187], v[192:195], v[42:45]
	v_mfma_f32_16x16x32_bf16 v[34:37], v[176:179], v[214:217], v[34:37]
	v_mfma_f32_16x16x32_bf16 v[26:29], v[184:187], v[214:217], v[26:29]
	v_mfma_f32_16x16x32_bf16 v[18:21], v[176:179], v[222:225], v[18:21]
	v_mfma_f32_16x16x32_bf16 v[10:13], v[184:187], v[222:225], v[10:13]
	v_mfma_f32_16x16x32_bf16 v[6:9], v[176:179], v[230:233], v[6:9]
	v_mfma_f32_16x16x32_bf16 v[2:5], v[184:187], v[230:233], v[2:5]
	s_barrier
	s_add_i32 s79, s79, 2
	s_add_u32 s80, s80, 0x100
	s_addc_u32 s81, s81, 0
	s_add_u32 s49, s49, 0x100
	s_addc_u32 s70, s70, 0
	s_cmp_gt_u32 s79, 29
	s_cbranch_scc0 .LBB0_336

; #define PG8_STAGE(bufoff, gbase, voff) do { _Pragma("unroll") for (int _i = 0; _i < 2; ++_i) \
;         __builtin_amdgcn_global_load_lds((const unsigned*)((const char*)(gbase) + (voff)[_i]), (LAS unsigned*)(lds + (bufoff) + ldsw + _i * 8192), 16, 0, 0); } while (0)
; #define PG8_LDA(dst, b, h) do { _Pragma("unroll") for (int m = 0; m < 4; ++m) _Pragma("unroll") for (int k = 0; k < 2; ++k) dst[m][k] = *(const LAS bf16x8*)(lds + PG8_SA(b, h) + aoff + m * 2048 + k * 1024); } while (0)
; #define PG8_LDB(dst, b, h) do { _Pragma("unroll") for (int n = 0; n < 2; ++n) _Pragma("unroll") for (int k = 0; k < 2; ++k) dst[n][k] = *(const LAS bf16x8*)(lds + PG8_SB(b, h) + boff + n * 2048 + k * 1024); } while (0)
; #define PG8_MMA(ai, bj, At, Bt) do { __builtin_amdgcn_s_setprio(1); _Pragma("unroll") for (int m = 0; m < 4; ++m) _Pragma("unroll") for (int n = 0; n < 2; ++n) _Pragma("unroll") for (int k = 0; k < 2; ++k) \
;         acc[ai][bj][m][n] = __builtin_amdgcn_mfma_f32_16x16x32_bf16(Bt[n][k], At[m][k], acc[ai][bj][m][n], 0, 0, 0); __builtin_amdgcn_s_setprio(0); } while (0)
; #define PG8_WAIT_V(n) asm volatile("s_waitcnt vmcnt(" #n ")" ::: "memory")
; #define PG8_WAIT_L(n) asm volatile("s_waitcnt lgkmcnt(" #n ")" ::: "memory")
; #define PG8_BAR __builtin_amdgcn_s_barrier()
; #define PG8_SCHED __builtin_amdgcn_sched_barrier(0)
; template <class Epi, class Sched = StaticOrder, bool ALIGN_EPI = true>
; __device__ __forceinline__ void gemm_phase(LAS unsigned char* lds, const Gemm g, const Sched& S, const Epi& E) {
;     ...
;         for (int t = 0; t < nt; t += 2) {
;             const bool last = (t == nt - 2);
;             const char* a1 = cA + (size_t)(t + 1) * kstep;
;             const char* a2 = last ? nA : cA + (size_t)(t + 2) * kstep; const char* b2 = last ? nB : cB + (size_t)(t + 2) * kstep;
;             const char* a3 = a2 + kstep; const char* b3 = b2 + kstep;
;             PG8_LDB(B0, 0, 0); PG8_LDB(B1, 0, 1); PG8_SCHED; PG8_LDA(At, 0, 0); PG8_STAGE(PG8_SA(1, 1), a1 + hstep, voffA);
;             PG8_WAIT_V(8); PG8_WAIT_L(0); PG8_BAR; PG8_MMA(0, 0, At, B0); PG8_MMA(0, 1, At, B1); PG8_BAR; PG8_SCHED;
;             PG8_LDA(At, 0, 1); PG8_STAGE(PG8_SB(0, 0), b2, voffB); PG8_STAGE(PG8_SB(0, 1), b2 + hstep, voffB); PG8_STAGE(PG8_SA(0, 0), a2, voffA);
;             PG8_WAIT_V(8); PG8_WAIT_L(0); PG8_BAR; PG8_MMA(1, 0, At, B0); PG8_MMA(1, 1, At, B1); PG8_BAR; PG8_SCHED;
.Lmy_nb_370:
	s_add_u32 s46, s44, 0x100
	s_addc_u32 s47, s45, 0
	s_add_i32 s16, 0, 0x10000
	s_cmpk_eq_i32 s82, 0x54
	s_cselect_b32 s31, s37, s47
	s_cselect_b32 s30, s36, s46
	v_add_u32_e32 v142, s16, v144
	s_cselect_b32 s1, s43, s92
	s_cselect_b32 s0, s42, s79
	s_add_i32 s33, 0, 0x14000
	ds_read_b128 v[148:151], v142
	ds_read_b128 v[160:163], v142 offset:1024
	ds_read_b128 v[164:167], v142 offset:2048
	ds_read_b128 v[168:171], v142 offset:3072
	v_add_u32_e32 v142, s33, v144
	ds_read_b128 v[172:175], v142
	ds_read_b128 v[176:179], v142 offset:1024
	ds_read_b128 v[180:183], v142 offset:2048
	ds_read_b128 v[184:187], v142 offset:3072
	v_lshl_add_u64 v[142:143], s[44:45], 0, v[138:139]
	s_add_i32 m0, s6, 0xc000
	ds_read_b128 v[188:191], v146
	ds_read_b128 v[192:195], v146 offset:1024
	ds_read_b128 v[210:213], v146 offset:2048
	ds_read_b128 v[214:217], v146 offset:3072
	ds_read_b128 v[218:221], v146 offset:4096
	ds_read_b128 v[222:225], v146 offset:5120
	ds_read_b128 v[226:229], v146 offset:6144
	ds_read_b128 v[230:233], v146 offset:7168
	global_load_lds_dwordx4 v[142:143], off
	s_add_i32 m0, s6, 0xe000
	v_lshl_add_u64 v[142:143], s[44:45], 0, v[140:141]
	global_load_lds_dwordx4 v[142:143], off
	s_waitcnt vmcnt(8)
	s_waitcnt lgkmcnt(0)
	s_barrier
	v_mfma_f32_16x16x32_bf16 v[126:129], v[148:151], v[188:191], 0
	v_mfma_f32_16x16x32_bf16 v[122:125], v[164:167], v[188:191], 0
	v_mfma_f32_16x16x32_bf16 v[118:121], v[148:151], v[210:213], 0
	v_mfma_f32_16x16x32_bf16 v[110:113], v[164:167], v[210:213], 0
	v_mfma_f32_16x16x32_bf16 v[102:105], v[148:151], v[218:221], 0
	v_mfma_f32_16x16x32_bf16 v[94:97], v[164:167], v[218:221], 0
	v_mfma_f32_16x16x32_bf16 v[82:85], v[148:151], v[226:229], 0
	v_mfma_f32_16x16x32_bf16 v[74:77], v[164:167], v[226:229], 0
	v_mfma_f32_16x16x32_bf16 v[126:129], v[160:163], v[192:195], v[126:129]
	v_mfma_f32_16x16x32_bf16 v[122:125], v[168:171], v[192:195], v[122:125]
	v_mfma_f32_16x16x32_bf16 v[118:121], v[160:163], v[214:217], v[118:121]
	v_mfma_f32_16x16x32_bf16 v[110:113], v[168:171], v[214:217], v[110:113]
	v_mfma_f32_16x16x32_bf16 v[102:105], v[160:163], v[222:225], v[102:105]
	v_mfma_f32_16x16x32_bf16 v[94:97], v[168:171], v[222:225], v[94:97]
	v_mfma_f32_16x16x32_bf16 v[82:85], v[160:163], v[230:233], v[82:85]
	v_mfma_f32_16x16x32_bf16 v[74:77], v[168:171], v[230:233], v[74:77]
	v_mfma_f32_16x16x32_bf16 v[114:117], v[172:175], v[188:191], 0
	v_mfma_f32_16x16x32_bf16 v[106:109], v[180:183], v[188:191], 0
	v_mfma_f32_16x16x32_bf16 v[98:101], v[172:175], v[210:213], 0
	v_mfma_f32_16x16x32_bf16 v[90:93], v[180:183], v[210:213], 0
	v_mfma_f32_16x16x32_bf16 v[86:89], v[172:175], v[218:221], 0
	v_mfma_f32_16x16x32_bf16 v[78:81], v[180:183], v[218:221], 0
	v_mfma_f32_16x16x32_bf16 v[70:73], v[172:175], v[226:229], 0
	v_mfma_f32_16x16x32_bf16 v[66:69], v[180:183], v[226:229], 0
	v_mfma_f32_16x16x32_bf16 v[114:117], v[176:179], v[192:195], v[114:117]
	v_mfma_f32_16x16x32_bf16 v[106:109], v[184:187], v[192:195], v[106:109]
	v_mfma_f32_16x16x32_bf16 v[98:101], v[176:179], v[214:217], v[98:101]
	v_mfma_f32_16x16x32_bf16 v[90:93], v[184:187], v[214:217], v[90:93]
	v_mfma_f32_16x16x32_bf16 v[86:89], v[176:179], v[222:225], v[86:89]
	v_mfma_f32_16x16x32_bf16 v[78:81], v[184:187], v[222:225], v[78:81]
	v_mfma_f32_16x16x32_bf16 v[70:73], v[176:179], v[230:233], v[70:73]
	v_mfma_f32_16x16x32_bf16 v[66:69], v[184:187], v[230:233], v[66:69]
	s_barrier
	s_add_i32 s16, s16, s4
	v_lshl_add_u64 v[142:143], s[0:1], 0, v[134:135]
	s_mov_b32 m0, s16
	ds_read_b128 v[188:191], v146 offset:16384
	ds_read_b128 v[192:195], v146 offset:17408
	ds_read_b128 v[210:213], v146 offset:18432
	ds_read_b128 v[214:217], v146 offset:19456
	ds_read_b128 v[218:221], v146 offset:20480
	ds_read_b128 v[222:225], v146 offset:21504
	ds_read_b128 v[226:229], v146 offset:22528
	ds_read_b128 v[230:233], v146 offset:23552
	global_load_lds_dwordx4 v[142:143], off
	s_add_i32 m0, s16, 0x2000
	s_add_u32 s16, s0, 0x160000
	v_lshl_add_u64 v[152:153], s[0:1], 0, v[130:131]
	s_addc_u32 s17, s1, 0
	s_add_i32 s33, s33, s4
	global_load_lds_dwordx4 v[152:153], off
	v_lshl_add_u64 v[196:197], s[16:17], 0, v[134:135]
	s_mov_b32 m0, s33
	v_lshl_add_u64 v[234:235], s[30:31], 0, v[132:133]
	global_load_lds_dwordx4 v[196:197], off
	s_add_i32 m0, s33, 0x2000
	v_lshl_add_u64 v[196:197], s[16:17], 0, v[130:131]
	global_load_lds_dwordx4 v[196:197], off
	s_mov_b32 m0, s6
	v_lshl_add_u64 v[196:197], s[30:31], 0, v[136:137]
	global_load_lds_dwordx4 v[196:197], off
	s_mov_b32 m0, s7
	s_nop 0
	global_load_lds_dwordx4 v[234:235], off
	s_waitcnt vmcnt(8)
	s_waitcnt lgkmcnt(0)
	s_barrier
; #define PG8_STAGE(bufoff, gbase, voff) do { _Pragma("unroll") for (int _i = 0; _i < 2; ++_i) \
;         __builtin_amdgcn_global_load_lds((const unsigned*)((const char*)(gbase) + (voff)[_i]), (LAS unsigned*)(lds + (bufoff) + ldsw + _i * 8192), 16, 0, 0); } while (0)
; #define PG8_LDA(dst, b, h) do { _Pragma("unroll") for (int m = 0; m < 4; ++m) _Pragma("unroll") for (int k = 0; k < 2; ++k) dst[m][k] = *(const LAS bf16x8*)(lds + PG8_SA(b, h) + aoff + m * 2048 + k * 1024); } while (0)
; #define PG8_LDB(dst, b, h) do { _Pragma("unroll") for (int n = 0; n < 2; ++n) _Pragma("unroll") for (int k = 0; k < 2; ++k) dst[n][k] = *(const LAS bf16x8*)(lds + PG8_SB(b, h) + boff + n * 2048 + k * 1024); } while (0)
; #define PG8_MMA(ai, bj, At, Bt) do { __builtin_amdgcn_s_setprio(1); _Pragma("unroll") for (int m = 0; m < 4; ++m) _Pragma("unroll") for (int n = 0; n < 2; ++n) _Pragma("unroll") for (int k = 0; k < 2; ++k) \
;         acc[ai][bj][m][n] = __builtin_amdgcn_mfma_f32_16x16x32_bf16(Bt[n][k], At[m][k], acc[ai][bj][m][n], 0, 0, 0); __builtin_amdgcn_s_setprio(0); } while (0)
; #define PG8_WAIT_V(n) asm volatile("s_waitcnt vmcnt(" #n ")" ::: "memory")
; #define PG8_WAIT_L(n) asm volatile("s_waitcnt lgkmcnt(" #n ")" ::: "memory")
; #define PG8_BAR __builtin_amdgcn_s_barrier()
; #define PG8_SCHED __builtin_amdgcn_sched_barrier(0)
; template <class Epi, class Sched = StaticOrder, bool ALIGN_EPI = true>
; __device__ __forceinline__ void gemm_phase(LAS unsigned char* lds, const Gemm g, const Sched& S, const Epi& E) {
;     ...
;             PG8_WAIT_V(8); PG8_WAIT_L(0); PG8_BAR; PG8_MMA(1, 0, At, B0); PG8_MMA(1, 1, At, B1); PG8_BAR; PG8_SCHED;
;             PG8_LDB(B0, 1, 0); PG8_LDB(B1, 1, 1); PG8_SCHED; PG8_LDA(At, 1, 0); PG8_STAGE(PG8_SA(0, 1), a2 + hstep, voffA);
;             PG8_WAIT_V(8); PG8_WAIT_L(0); PG8_BAR; PG8_MMA(0, 0, At, B0); PG8_MMA(0, 1, At, B1); PG8_BAR; PG8_SCHED;
	v_mfma_f32_16x16x32_bf16 v[62:65], v[148:151], v[188:191], 0
	v_mfma_f32_16x16x32_bf16 v[58:61], v[164:167], v[188:191], 0
	v_mfma_f32_16x16x32_bf16 v[54:57], v[148:151], v[210:213], 0
	v_mfma_f32_16x16x32_bf16 v[46:49], v[164:167], v[210:213], 0
	v_mfma_f32_16x16x32_bf16 v[38:41], v[148:151], v[218:221], 0
	v_mfma_f32_16x16x32_bf16 v[30:33], v[164:167], v[218:221], 0
	v_mfma_f32_16x16x32_bf16 v[22:25], v[148:151], v[226:229], 0
	v_mfma_f32_16x16x32_bf16 v[14:17], v[164:167], v[226:229], 0
	v_mfma_f32_16x16x32_bf16 v[62:65], v[160:163], v[192:195], v[62:65]
	v_mfma_f32_16x16x32_bf16 v[58:61], v[168:171], v[192:195], v[58:61]
	v_mfma_f32_16x16x32_bf16 v[54:57], v[160:163], v[214:217], v[54:57]
	v_mfma_f32_16x16x32_bf16 v[46:49], v[168:171], v[214:217], v[46:49]
	v_mfma_f32_16x16x32_bf16 v[38:41], v[160:163], v[222:225], v[38:41]
	v_mfma_f32_16x16x32_bf16 v[30:33], v[168:171], v[222:225], v[30:33]
	v_mfma_f32_16x16x32_bf16 v[22:25], v[160:163], v[230:233], v[22:25]
	v_mfma_f32_16x16x32_bf16 v[14:17], v[168:171], v[230:233], v[14:17]
	v_mfma_f32_16x16x32_bf16 v[50:53], v[172:175], v[188:191], 0
	v_mfma_f32_16x16x32_bf16 v[42:45], v[180:183], v[188:191], 0
	v_mfma_f32_16x16x32_bf16 v[34:37], v[172:175], v[210:213], 0
	v_mfma_f32_16x16x32_bf16 v[26:29], v[180:183], v[210:213], 0
	v_mfma_f32_16x16x32_bf16 v[18:21], v[172:175], v[218:221], 0
	v_mfma_f32_16x16x32_bf16 v[10:13], v[180:183], v[218:221], 0
	v_mfma_f32_16x16x32_bf16 v[6:9], v[172:175], v[226:229], 0
	v_mfma_f32_16x16x32_bf16 v[2:5], v[180:183], v[226:229], 0
	v_mfma_f32_16x16x32_bf16 v[50:53], v[176:179], v[192:195], v[50:53]
	v_mfma_f32_16x16x32_bf16 v[42:45], v[184:187], v[192:195], v[42:45]
	v_mfma_f32_16x16x32_bf16 v[34:37], v[176:179], v[214:217], v[34:37]
	v_mfma_f32_16x16x32_bf16 v[26:29], v[184:187], v[214:217], v[26:29]
	v_mfma_f32_16x16x32_bf16 v[18:21], v[176:179], v[222:225], v[18:21]
	v_mfma_f32_16x16x32_bf16 v[10:13], v[184:187], v[222:225], v[10:13]
	v_mfma_f32_16x16x32_bf16 v[6:9], v[176:179], v[230:233], v[6:9]
	v_mfma_f32_16x16x32_bf16 v[2:5], v[184:187], v[230:233], v[2:5]
	s_barrier
	s_add_i32 s33, 0, 0x18000
	v_add_u32_e32 v147, s33, v144
	s_add_i32 s44, 0, 0x1c000
	ds_read_b128 v[148:151], v147
	ds_read_b128 v[160:163], v147 offset:1024
	ds_read_b128 v[164:167], v147 offset:2048
	ds_read_b128 v[168:171], v147 offset:3072
	v_add_u32_e32 v147, s44, v144
	ds_read_b128 v[172:175], v147
	ds_read_b128 v[176:179], v147 offset:1024
	ds_read_b128 v[180:183], v147 offset:2048
	ds_read_b128 v[184:187], v147 offset:3072
	s_add_u32 s16, s30, 0x160000
	s_addc_u32 s17, s31, 0
	s_mov_b32 m0, s8
	v_lshl_add_u64 v[236:237], s[16:17], 0, v[136:137]
	ds_read_b128 v[188:191], v146 offset:32768
	ds_read_b128 v[192:195], v146 offset:33792
	ds_read_b128 v[210:213], v146 offset:34816
	ds_read_b128 v[214:217], v146 offset:35840
	ds_read_b128 v[218:221], v146 offset:36864
	ds_read_b128 v[222:225], v146 offset:37888
	ds_read_b128 v[226:229], v146 offset:38912
	ds_read_b128 v[230:233], v146 offset:39936
	global_load_lds_dwordx4 v[236:237], off
	s_mov_b32 m0, s9
	v_lshl_add_u64 v[236:237], s[16:17], 0, v[132:133]
	global_load_lds_dwordx4 v[236:237], off
	s_waitcnt vmcnt(8)
	s_waitcnt lgkmcnt(0)
	s_barrier
	v_mfma_f32_16x16x32_bf16 v[126:129], v[148:151], v[188:191], v[126:129]
	v_mfma_f32_16x16x32_bf16 v[122:125], v[164:167], v[188:191], v[122:125]
	v_mfma_f32_16x16x32_bf16 v[118:121], v[148:151], v[210:213], v[118:121]
	v_mfma_f32_16x16x32_bf16 v[110:113], v[164:167], v[210:213], v[110:113]
	v_mfma_f32_16x16x32_bf16 v[102:105], v[148:151], v[218:221], v[102:105]
	v_mfma_f32_16x16x32_bf16 v[94:97], v[164:167], v[218:221], v[94:97]
	v_mfma_f32_16x16x32_bf16 v[82:85], v[148:151], v[226:229], v[82:85]
	v_mfma_f32_16x16x32_bf16 v[74:77], v[164:167], v[226:229], v[74:77]
	v_mfma_f32_16x16x32_bf16 v[126:129], v[160:163], v[192:195], v[126:129]
	v_mfma_f32_16x16x32_bf16 v[122:125], v[168:171], v[192:195], v[122:125]
	v_mfma_f32_16x16x32_bf16 v[118:121], v[160:163], v[214:217], v[118:121]
	v_mfma_f32_16x16x32_bf16 v[110:113], v[168:171], v[214:217], v[110:113]
	v_mfma_f32_16x16x32_bf16 v[102:105], v[160:163], v[222:225], v[102:105]
	v_mfma_f32_16x16x32_bf16 v[94:97], v[168:171], v[222:225], v[94:97]
	v_mfma_f32_16x16x32_bf16 v[82:85], v[160:163], v[230:233], v[82:85]
	v_mfma_f32_16x16x32_bf16 v[74:77], v[168:171], v[230:233], v[74:77]
	v_mfma_f32_16x16x32_bf16 v[114:117], v[172:175], v[188:191], v[114:117]
	v_mfma_f32_16x16x32_bf16 v[106:109], v[180:183], v[188:191], v[106:109]
	v_mfma_f32_16x16x32_bf16 v[98:101], v[172:175], v[210:213], v[98:101]
	v_mfma_f32_16x16x32_bf16 v[90:93], v[180:183], v[210:213], v[90:93]
	v_mfma_f32_16x16x32_bf16 v[86:89], v[172:175], v[218:221], v[86:89]
	v_mfma_f32_16x16x32_bf16 v[78:81], v[180:183], v[218:221], v[78:81]
	v_mfma_f32_16x16x32_bf16 v[70:73], v[172:175], v[226:229], v[70:73]
	v_mfma_f32_16x16x32_bf16 v[66:69], v[180:183], v[226:229], v[66:69]
	v_mfma_f32_16x16x32_bf16 v[114:117], v[176:179], v[192:195], v[114:117]
	v_mfma_f32_16x16x32_bf16 v[106:109], v[184:187], v[192:195], v[106:109]
	v_mfma_f32_16x16x32_bf16 v[98:101], v[176:179], v[214:217], v[98:101]
	v_mfma_f32_16x16x32_bf16 v[90:93], v[184:187], v[214:217], v[90:93]
	v_mfma_f32_16x16x32_bf16 v[86:89], v[176:179], v[222:225], v[86:89]
	v_mfma_f32_16x16x32_bf16 v[78:81], v[184:187], v[222:225], v[78:81]
	v_mfma_f32_16x16x32_bf16 v[70:73], v[176:179], v[230:233], v[70:73]
	v_mfma_f32_16x16x32_bf16 v[66:69], v[184:187], v[230:233], v[66:69]
	s_barrier
; #define PG8_STAGE(bufoff, gbase, voff) do { _Pragma("unroll") for (int _i = 0; _i < 2; ++_i) \
;         __builtin_amdgcn_global_load_lds((const unsigned*)((const char*)(gbase) + (voff)[_i]), (LAS unsigned*)(lds + (bufoff) + ldsw + _i * 8192), 16, 0, 0); } while (0)
; #define PG8_LDA(dst, b, h) do { _Pragma("unroll") for (int m = 0; m < 4; ++m) _Pragma("unroll") for (int k = 0; k < 2; ++k) dst[m][k] = *(const LAS bf16x8*)(lds + PG8_SA(b, h) + aoff + m * 2048 + k * 1024); } while (0)
; #define PG8_LDB(dst, b, h) do { _Pragma("unroll") for (int n = 0; n < 2; ++n) _Pragma("unroll") for (int k = 0; k < 2; ++k) dst[n][k] = *(const LAS bf16x8*)(lds + PG8_SB(b, h) + boff + n * 2048 + k * 1024); } while (0)
; #define PG8_MMA(ai, bj, At, Bt) do { __builtin_amdgcn_s_setprio(1); _Pragma("unroll") for (int m = 0; m < 4; ++m) _Pragma("unroll") for (int n = 0; n < 2; ++n) _Pragma("unroll") for (int k = 0; k < 2; ++k) \
;         acc[ai][bj][m][n] = __builtin_amdgcn_mfma_f32_16x16x32_bf16(Bt[n][k], At[m][k], acc[ai][bj][m][n], 0, 0, 0); __builtin_amdgcn_s_setprio(0); } while (0)
; #define PG8_WAIT_V(n) asm volatile("s_waitcnt vmcnt(" #n ")" ::: "memory")
; #define PG8_WAIT_L(n) asm volatile("s_waitcnt lgkmcnt(" #n ")" ::: "memory")
; #define PG8_BAR __builtin_amdgcn_s_barrier()
; #define PG8_SCHED __builtin_amdgcn_sched_barrier(0)
; template <class Epi, class Sched = StaticOrder, bool ALIGN_EPI = true>
; __device__ __forceinline__ void gemm_phase(LAS unsigned char* lds, const Gemm g, const Sched& S, const Epi& E) {
;     ...
;         for (int t = 0; t < nt; t += 2) {
;             const bool last = (t == nt - 2);
;             const char* a1 = cA + (size_t)(t + 1) * kstep;
;             const char* a2 = last ? nA : cA + (size_t)(t + 2) * kstep; const char* b2 = last ? nB : cB + (size_t)(t + 2) * kstep;
;             const char* a3 = a2 + kstep; const char* b3 = b2 + kstep;
;             PG8_LDB(B0, 0, 0); PG8_LDB(B1, 0, 1); PG8_SCHED; PG8_LDA(At, 0, 0); PG8_STAGE(PG8_SA(1, 1), a1 + hstep, voffA);
;     ...
;             PG8_LDA(At, 1, 1); PG8_STAGE(PG8_SB(1, 0), b3, voffB); PG8_STAGE(PG8_SB(1, 1), b3 + hstep, voffB); PG8_STAGE(PG8_SA(1, 0), a3, voffA);
;             PG8_WAIT_V(8); PG8_WAIT_L(0); PG8_BAR; PG8_MMA(1, 0, At, B0); PG8_MMA(1, 1, At, B1); PG8_BAR; PG8_SCHED;
	s_add_i32 s16, s33, s4
	v_lshl_add_u64 v[142:143], v[142:143], 0, s[34:35]
	s_mov_b32 m0, s16
	ds_read_b128 v[188:191], v146 offset:49152
	ds_read_b128 v[192:195], v146 offset:50176
	ds_read_b128 v[210:213], v146 offset:51200
	ds_read_b128 v[214:217], v146 offset:52224
	ds_read_b128 v[218:221], v146 offset:53248
	ds_read_b128 v[222:225], v146 offset:54272
	ds_read_b128 v[226:229], v146 offset:55296
	ds_read_b128 v[230:233], v146 offset:56320
	global_load_lds_dwordx4 v[142:143], off
	s_add_i32 m0, s16, 0x2000
	s_add_u32 s0, s0, 0x160080
	v_lshl_add_u64 v[142:143], v[152:153], 0, s[34:35]
	s_addc_u32 s1, s1, 0
	s_add_i32 s16, s44, s4
	global_load_lds_dwordx4 v[142:143], off
	s_mov_b32 m0, s16
	v_lshl_add_u64 v[142:143], s[0:1], 0, v[134:135]
	global_load_lds_dwordx4 v[142:143], off
	s_add_i32 m0, s16, 0x2000
	v_lshl_add_u64 v[142:143], s[0:1], 0, v[130:131]
	global_load_lds_dwordx4 v[142:143], off
	s_mov_b32 m0, s10
	v_lshl_add_u64 v[142:143], v[196:197], 0, s[34:35]
	global_load_lds_dwordx4 v[142:143], off
	s_mov_b32 m0, s11
	v_lshl_add_u64 v[142:143], v[234:235], 0, s[34:35]
	global_load_lds_dwordx4 v[142:143], off
	s_waitcnt vmcnt(8)
	s_waitcnt lgkmcnt(0)
	s_barrier
	v_mfma_f32_16x16x32_bf16 v[62:65], v[148:151], v[188:191], v[62:65]
	v_mfma_f32_16x16x32_bf16 v[58:61], v[164:167], v[188:191], v[58:61]
	v_mfma_f32_16x16x32_bf16 v[54:57], v[148:151], v[210:213], v[54:57]
	v_mfma_f32_16x16x32_bf16 v[46:49], v[164:167], v[210:213], v[46:49]
	v_mfma_f32_16x16x32_bf16 v[38:41], v[148:151], v[218:221], v[38:41]
	v_mfma_f32_16x16x32_bf16 v[30:33], v[164:167], v[218:221], v[30:33]
	v_mfma_f32_16x16x32_bf16 v[22:25], v[148:151], v[226:229], v[22:25]
	v_mfma_f32_16x16x32_bf16 v[14:17], v[164:167], v[226:229], v[14:17]
	v_mfma_f32_16x16x32_bf16 v[62:65], v[160:163], v[192:195], v[62:65]
	v_mfma_f32_16x16x32_bf16 v[58:61], v[168:171], v[192:195], v[58:61]
	v_mfma_f32_16x16x32_bf16 v[54:57], v[160:163], v[214:217], v[54:57]
	v_mfma_f32_16x16x32_bf16 v[46:49], v[168:171], v[214:217], v[46:49]
	v_mfma_f32_16x16x32_bf16 v[38:41], v[160:163], v[222:225], v[38:41]
	v_mfma_f32_16x16x32_bf16 v[30:33], v[168:171], v[222:225], v[30:33]
	v_mfma_f32_16x16x32_bf16 v[22:25], v[160:163], v[230:233], v[22:25]
	v_mfma_f32_16x16x32_bf16 v[14:17], v[168:171], v[230:233], v[14:17]
	v_mfma_f32_16x16x32_bf16 v[50:53], v[172:175], v[188:191], v[50:53]
	v_mfma_f32_16x16x32_bf16 v[42:45], v[180:183], v[188:191], v[42:45]
	v_mfma_f32_16x16x32_bf16 v[34:37], v[172:175], v[210:213], v[34:37]
	v_mfma_f32_16x16x32_bf16 v[26:29], v[180:183], v[210:213], v[26:29]
	v_mfma_f32_16x16x32_bf16 v[18:21], v[172:175], v[218:221], v[18:21]
	v_mfma_f32_16x16x32_bf16 v[10:13], v[180:183], v[218:221], v[10:13]
	v_mfma_f32_16x16x32_bf16 v[6:9], v[172:175], v[226:229], v[6:9]
	v_mfma_f32_16x16x32_bf16 v[2:5], v[180:183], v[226:229], v[2:5]
	v_mfma_f32_16x16x32_bf16 v[50:53], v[176:179], v[192:195], v[50:53]
	v_mfma_f32_16x16x32_bf16 v[42:45], v[184:187], v[192:195], v[42:45]
	v_mfma_f32_16x16x32_bf16 v[34:37], v[176:179], v[214:217], v[34:37]
	v_mfma_f32_16x16x32_bf16 v[26:29], v[184:187], v[214:217], v[26:29]
	v_mfma_f32_16x16x32_bf16 v[18:21], v[176:179], v[222:225], v[18:21]
	v_mfma_f32_16x16x32_bf16 v[10:13], v[184:187], v[222:225], v[10:13]
	v_mfma_f32_16x16x32_bf16 v[6:9], v[176:179], v[230:233], v[6:9]
	v_mfma_f32_16x16x32_bf16 v[2:5], v[184:187], v[230:233], v[2:5]
	s_barrier
	s_add_i32 s82, s82, 2
	s_add_u32 s79, s79, 0x100
	s_addc_u32 s92, s92, 0
	s_cmpk_gt_u32 s82, 0x55
	s_mov_b64 s[44:45], s[46:47]
	s_cbranch_scc0 .LBB0_370
.LBB0_370:
	s_add_u32 s46, s44, 0x100
	s_addc_u32 s47, s45, 0
	s_add_i32 s16, 0, 0x10000
	s_cmpk_eq_i32 s82, 0x54
	s_cselect_b32 s31, s37, s47
	s_cselect_b32 s30, s36, s46
	v_add_u32_e32 v142, s16, v144
	s_cselect_b32 s1, s43, s92
	s_cselect_b32 s0, s42, s79
	s_add_i32 s33, 0, 0x14000
	ds_read_b128 v[148:151], v142
	ds_read_b128 v[160:163], v142 offset:1024
	ds_read_b128 v[164:167], v142 offset:2048
	ds_read_b128 v[168:171], v142 offset:3072
	v_add_u32_e32 v142, s33, v144
	ds_read_b128 v[172:175], v142
	ds_read_b128 v[176:179], v142 offset:1024
	ds_read_b128 v[180:183], v142 offset:2048
	ds_read_b128 v[184:187], v142 offset:3072
	v_lshl_add_u64 v[142:143], s[44:45], 0, v[138:139]
	s_add_i32 m0, s6, 0xc000
	ds_read_b128 v[188:191], v146
	ds_read_b128 v[192:195], v146 offset:1024
	ds_read_b128 v[210:213], v146 offset:2048
	ds_read_b128 v[214:217], v146 offset:3072
	ds_read_b128 v[218:221], v146 offset:4096
	ds_read_b128 v[222:225], v146 offset:5120
	ds_read_b128 v[226:229], v146 offset:6144
	ds_read_b128 v[230:233], v146 offset:7168
	global_load_lds_dwordx4 v[142:143], off
	s_add_i32 m0, s6, 0xe000
	v_lshl_add_u64 v[142:143], s[44:45], 0, v[140:141]
	global_load_lds_dwordx4 v[142:143], off
	s_waitcnt vmcnt(8)
	s_waitcnt lgkmcnt(0)
	s_barrier
; #define PG8_STAGE(bufoff, gbase, voff) do { _Pragma("unroll") for (int _i = 0; _i < 2; ++_i) \
;         __builtin_amdgcn_global_load_lds((const unsigned*)((const char*)(gbase) + (voff)[_i]), (LAS unsigned*)(lds + (bufoff) + ldsw + _i * 8192), 16, 0, 0); } while (0)
; #define PG8_LDA(dst, b, h) do { _Pragma("unroll") for (int m = 0; m < 4; ++m) _Pragma("unroll") for (int k = 0; k < 2; ++k) dst[m][k] = *(const LAS bf16x8*)(lds + PG8_SA(b, h) + aoff + m * 2048 + k * 1024); } while (0)
; #define PG8_MMA(ai, bj, At, Bt) do { __builtin_amdgcn_s_setprio(1); _Pragma("unroll") for (int m = 0; m < 4; ++m) _Pragma("unroll") for (int n = 0; n < 2; ++n) _Pragma("unroll") for (int k = 0; k < 2; ++k) \
;         acc[ai][bj][m][n] = __builtin_amdgcn_mfma_f32_16x16x32_bf16(Bt[n][k], At[m][k], acc[ai][bj][m][n], 0, 0, 0); __builtin_amdgcn_s_setprio(0); } while (0)
; #define PG8_WAIT_V(n) asm volatile("s_waitcnt vmcnt(" #n ")" ::: "memory")
; #define PG8_WAIT_L(n) asm volatile("s_waitcnt lgkmcnt(" #n ")" ::: "memory")
; #define PG8_BAR __builtin_amdgcn_s_barrier()
; #define PG8_SCHED __builtin_amdgcn_sched_barrier(0)
; template <class Epi, class Sched = StaticOrder, bool ALIGN_EPI = true>
; __device__ __forceinline__ void gemm_phase(LAS unsigned char* lds, const Gemm g, const Sched& S, const Epi& E) {
;     ...
;             PG8_WAIT_V(8); PG8_WAIT_L(0); PG8_BAR; PG8_MMA(0, 0, At, B0); PG8_MMA(0, 1, At, B1); PG8_BAR; PG8_SCHED;
;             PG8_LDA(At, 0, 1); PG8_STAGE(PG8_SB(0, 0), b2, voffB); PG8_STAGE(PG8_SB(0, 1), b2 + hstep, voffB); PG8_STAGE(PG8_SA(0, 0), a2, voffA);
;             PG8_WAIT_V(8); PG8_WAIT_L(0); PG8_BAR; PG8_MMA(1, 0, At, B0); PG8_MMA(1, 1, At, B1); PG8_BAR; PG8_SCHED;
	v_mfma_f32_16x16x32_bf16 v[126:129], v[148:151], v[188:191], v[126:129]
	v_mfma_f32_16x16x32_bf16 v[122:125], v[164:167], v[188:191], v[122:125]
	v_mfma_f32_16x16x32_bf16 v[118:121], v[148:151], v[210:213], v[118:121]
	v_mfma_f32_16x16x32_bf16 v[110:113], v[164:167], v[210:213], v[110:113]
	v_mfma_f32_16x16x32_bf16 v[102:105], v[148:151], v[218:221], v[102:105]
	v_mfma_f32_16x16x32_bf16 v[94:97], v[164:167], v[218:221], v[94:97]
	v_mfma_f32_16x16x32_bf16 v[82:85], v[148:151], v[226:229], v[82:85]
	v_mfma_f32_16x16x32_bf16 v[74:77], v[164:167], v[226:229], v[74:77]
	v_mfma_f32_16x16x32_bf16 v[126:129], v[160:163], v[192:195], v[126:129]
	v_mfma_f32_16x16x32_bf16 v[122:125], v[168:171], v[192:195], v[122:125]
	v_mfma_f32_16x16x32_bf16 v[118:121], v[160:163], v[214:217], v[118:121]
	v_mfma_f32_16x16x32_bf16 v[110:113], v[168:171], v[214:217], v[110:113]
	v_mfma_f32_16x16x32_bf16 v[102:105], v[160:163], v[222:225], v[102:105]
	v_mfma_f32_16x16x32_bf16 v[94:97], v[168:171], v[222:225], v[94:97]
	v_mfma_f32_16x16x32_bf16 v[82:85], v[160:163], v[230:233], v[82:85]
	v_mfma_f32_16x16x32_bf16 v[74:77], v[168:171], v[230:233], v[74:77]
	v_mfma_f32_16x16x32_bf16 v[114:117], v[172:175], v[188:191], v[114:117]
	v_mfma_f32_16x16x32_bf16 v[106:109], v[180:183], v[188:191], v[106:109]
	v_mfma_f32_16x16x32_bf16 v[98:101], v[172:175], v[210:213], v[98:101]
	v_mfma_f32_16x16x32_bf16 v[90:93], v[180:183], v[210:213], v[90:93]
	v_mfma_f32_16x16x32_bf16 v[86:89], v[172:175], v[218:221], v[86:89]
	v_mfma_f32_16x16x32_bf16 v[78:81], v[180:183], v[218:221], v[78:81]
	v_mfma_f32_16x16x32_bf16 v[70:73], v[172:175], v[226:229], v[70:73]
	v_mfma_f32_16x16x32_bf16 v[66:69], v[180:183], v[226:229], v[66:69]
	v_mfma_f32_16x16x32_bf16 v[114:117], v[176:179], v[192:195], v[114:117]
	v_mfma_f32_16x16x32_bf16 v[106:109], v[184:187], v[192:195], v[106:109]
	v_mfma_f32_16x16x32_bf16 v[98:101], v[176:179], v[214:217], v[98:101]
	v_mfma_f32_16x16x32_bf16 v[90:93], v[184:187], v[214:217], v[90:93]
	v_mfma_f32_16x16x32_bf16 v[86:89], v[176:179], v[222:225], v[86:89]
	v_mfma_f32_16x16x32_bf16 v[78:81], v[184:187], v[222:225], v[78:81]
	v_mfma_f32_16x16x32_bf16 v[70:73], v[176:179], v[230:233], v[70:73]
	v_mfma_f32_16x16x32_bf16 v[66:69], v[184:187], v[230:233], v[66:69]
	s_barrier
	s_add_i32 s16, s16, s4
	v_lshl_add_u64 v[142:143], s[0:1], 0, v[134:135]
	s_mov_b32 m0, s16
	ds_read_b128 v[188:191], v146 offset:16384
	ds_read_b128 v[192:195], v146 offset:17408
	ds_read_b128 v[210:213], v146 offset:18432
	ds_read_b128 v[214:217], v146 offset:19456
	ds_read_b128 v[218:221], v146 offset:20480
	ds_read_b128 v[222:225], v146 offset:21504
	ds_read_b128 v[226:229], v146 offset:22528
	ds_read_b128 v[230:233], v146 offset:23552
	global_load_lds_dwordx4 v[142:143], off
	s_add_i32 m0, s16, 0x2000
	s_add_u32 s16, s0, 0x160000
	v_lshl_add_u64 v[152:153], s[0:1], 0, v[130:131]
	s_addc_u32 s17, s1, 0
	s_add_i32 s33, s33, s4
	global_load_lds_dwordx4 v[152:153], off
	v_lshl_add_u64 v[196:197], s[16:17], 0, v[134:135]
	s_mov_b32 m0, s33
	v_lshl_add_u64 v[234:235], s[30:31], 0, v[132:133]
	global_load_lds_dwordx4 v[196:197], off
	s_add_i32 m0, s33, 0x2000
	v_lshl_add_u64 v[196:197], s[16:17], 0, v[130:131]
	global_load_lds_dwordx4 v[196:197], off
	s_mov_b32 m0, s6
	v_lshl_add_u64 v[196:197], s[30:31], 0, v[136:137]
	global_load_lds_dwordx4 v[196:197], off
	s_mov_b32 m0, s7
	s_nop 0
	global_load_lds_dwordx4 v[234:235], off
	s_waitcnt vmcnt(8)
	s_waitcnt lgkmcnt(0)
	s_barrier
	v_mfma_f32_16x16x32_bf16 v[62:65], v[148:151], v[188:191], v[62:65]
	v_mfma_f32_16x16x32_bf16 v[58:61], v[164:167], v[188:191], v[58:61]
	v_mfma_f32_16x16x32_bf16 v[54:57], v[148:151], v[210:213], v[54:57]
	v_mfma_f32_16x16x32_bf16 v[46:49], v[164:167], v[210:213], v[46:49]
	v_mfma_f32_16x16x32_bf16 v[38:41], v[148:151], v[218:221], v[38:41]
	v_mfma_f32_16x16x32_bf16 v[30:33], v[164:167], v[218:221], v[30:33]
	v_mfma_f32_16x16x32_bf16 v[22:25], v[148:151], v[226:229], v[22:25]
	v_mfma_f32_16x16x32_bf16 v[14:17], v[164:167], v[226:229], v[14:17]
	v_mfma_f32_16x16x32_bf16 v[62:65], v[160:163], v[192:195], v[62:65]
	v_mfma_f32_16x16x32_bf16 v[58:61], v[168:171], v[192:195], v[58:61]
	v_mfma_f32_16x16x32_bf16 v[54:57], v[160:163], v[214:217], v[54:57]
	v_mfma_f32_16x16x32_bf16 v[46:49], v[168:171], v[214:217], v[46:49]
	v_mfma_f32_16x16x32_bf16 v[38:41], v[160:163], v[222:225], v[38:41]
	v_mfma_f32_16x16x32_bf16 v[30:33], v[168:171], v[222:225], v[30:33]
	v_mfma_f32_16x16x32_bf16 v[22:25], v[160:163], v[230:233], v[22:25]
	v_mfma_f32_16x16x32_bf16 v[14:17], v[168:171], v[230:233], v[14:17]
	v_mfma_f32_16x16x32_bf16 v[50:53], v[172:175], v[188:191], v[50:53]
	v_mfma_f32_16x16x32_bf16 v[42:45], v[180:183], v[188:191], v[42:45]
	v_mfma_f32_16x16x32_bf16 v[34:37], v[172:175], v[210:213], v[34:37]
	v_mfma_f32_16x16x32_bf16 v[26:29], v[180:183], v[210:213], v[26:29]
	v_mfma_f32_16x16x32_bf16 v[18:21], v[172:175], v[218:221], v[18:21]
	v_mfma_f32_16x16x32_bf16 v[10:13], v[180:183], v[218:221], v[10:13]
	v_mfma_f32_16x16x32_bf16 v[6:9], v[172:175], v[226:229], v[6:9]
	v_mfma_f32_16x16x32_bf16 v[2:5], v[180:183], v[226:229], v[2:5]
	v_mfma_f32_16x16x32_bf16 v[50:53], v[176:179], v[192:195], v[50:53]
	v_mfma_f32_16x16x32_bf16 v[42:45], v[184:187], v[192:195], v[42:45]
	v_mfma_f32_16x16x32_bf16 v[34:37], v[176:179], v[214:217], v[34:37]
	v_mfma_f32_16x16x32_bf16 v[26:29], v[184:187], v[214:217], v[26:29]
	v_mfma_f32_16x16x32_bf16 v[18:21], v[176:179], v[222:225], v[18:21]
	v_mfma_f32_16x16x32_bf16 v[10:13], v[184:187], v[222:225], v[10:13]
	v_mfma_f32_16x16x32_bf16 v[6:9], v[176:179], v[230:233], v[6:9]
	v_mfma_f32_16x16x32_bf16 v[2:5], v[184:187], v[230:233], v[2:5]
	s_barrier
; #define PG8_STAGE(bufoff, gbase, voff) do { _Pragma("unroll") for (int _i = 0; _i < 2; ++_i) \
;         __builtin_amdgcn_global_load_lds((const unsigned*)((const char*)(gbase) + (voff)[_i]), (LAS unsigned*)(lds + (bufoff) + ldsw + _i * 8192), 16, 0, 0); } while (0)
; #define PG8_LDA(dst, b, h) do { _Pragma("unroll") for (int m = 0; m < 4; ++m) _Pragma("unroll") for (int k = 0; k < 2; ++k) dst[m][k] = *(const LAS bf16x8*)(lds + PG8_SA(b, h) + aoff + m * 2048 + k * 1024); } while (0)
; #define PG8_LDB(dst, b, h) do { _Pragma("unroll") for (int n = 0; n < 2; ++n) _Pragma("unroll") for (int k = 0; k < 2; ++k) dst[n][k] = *(const LAS bf16x8*)(lds + PG8_SB(b, h) + boff + n * 2048 + k * 1024); } while (0)
; #define PG8_MMA(ai, bj, At, Bt) do { __builtin_amdgcn_s_setprio(1); _Pragma("unroll") for (int m = 0; m < 4; ++m) _Pragma("unroll") for (int n = 0; n < 2; ++n) _Pragma("unroll") for (int k = 0; k < 2; ++k) \
;         acc[ai][bj][m][n] = __builtin_amdgcn_mfma_f32_16x16x32_bf16(Bt[n][k], At[m][k], acc[ai][bj][m][n], 0, 0, 0); __builtin_amdgcn_s_setprio(0); } while (0)
; #define PG8_WAIT_V(n) asm volatile("s_waitcnt vmcnt(" #n ")" ::: "memory")
; #define PG8_WAIT_L(n) asm volatile("s_waitcnt lgkmcnt(" #n ")" ::: "memory")
; #define PG8_BAR __builtin_amdgcn_s_barrier()
; #define PG8_SCHED __builtin_amdgcn_sched_barrier(0)
; template <class Epi, class Sched = StaticOrder, bool ALIGN_EPI = true>
; __device__ __forceinline__ void gemm_phase(LAS unsigned char* lds, const Gemm g, const Sched& S, const Epi& E) {
;     ...
;             PG8_LDB(B0, 1, 0); PG8_LDB(B1, 1, 1); PG8_SCHED; PG8_LDA(At, 1, 0); PG8_STAGE(PG8_SA(0, 1), a2 + hstep, voffA);
;             PG8_WAIT_V(8); PG8_WAIT_L(0); PG8_BAR; PG8_MMA(0, 0, At, B0); PG8_MMA(0, 1, At, B1); PG8_BAR; PG8_SCHED;
;             PG8_LDA(At, 1, 1); PG8_STAGE(PG8_SB(1, 0), b3, voffB); PG8_STAGE(PG8_SB(1, 1), b3 + hstep, voffB); PG8_STAGE(PG8_SA(1, 0), a3, voffA);
;             PG8_WAIT_V(8); PG8_WAIT_L(0); PG8_BAR; PG8_MMA(1, 0, At, B0); PG8_MMA(1, 1, At, B1); PG8_BAR; PG8_SCHED;
	s_add_i32 s33, 0, 0x18000
	v_add_u32_e32 v147, s33, v144
	s_add_i32 s44, 0, 0x1c000
	ds_read_b128 v[148:151], v147
	ds_read_b128 v[160:163], v147 offset:1024
	ds_read_b128 v[164:167], v147 offset:2048
	ds_read_b128 v[168:171], v147 offset:3072
	v_add_u32_e32 v147, s44, v144
	ds_read_b128 v[172:175], v147
	ds_read_b128 v[176:179], v147 offset:1024
	ds_read_b128 v[180:183], v147 offset:2048
	ds_read_b128 v[184:187], v147 offset:3072
	s_add_u32 s16, s30, 0x160000
	s_addc_u32 s17, s31, 0
	s_mov_b32 m0, s8
	v_lshl_add_u64 v[236:237], s[16:17], 0, v[136:137]
	ds_read_b128 v[188:191], v146 offset:32768
	ds_read_b128 v[192:195], v146 offset:33792
	ds_read_b128 v[210:213], v146 offset:34816
	ds_read_b128 v[214:217], v146 offset:35840
	ds_read_b128 v[218:221], v146 offset:36864
	ds_read_b128 v[222:225], v146 offset:37888
	ds_read_b128 v[226:229], v146 offset:38912
	ds_read_b128 v[230:233], v146 offset:39936
	global_load_lds_dwordx4 v[236:237], off
	s_mov_b32 m0, s9
	v_lshl_add_u64 v[236:237], s[16:17], 0, v[132:133]
	global_load_lds_dwordx4 v[236:237], off
	s_waitcnt vmcnt(8)
	s_waitcnt lgkmcnt(0)
	s_barrier
	v_mfma_f32_16x16x32_bf16 v[126:129], v[148:151], v[188:191], v[126:129]
	v_mfma_f32_16x16x32_bf16 v[122:125], v[164:167], v[188:191], v[122:125]
	v_mfma_f32_16x16x32_bf16 v[118:121], v[148:151], v[210:213], v[118:121]
	v_mfma_f32_16x16x32_bf16 v[110:113], v[164:167], v[210:213], v[110:113]
	v_mfma_f32_16x16x32_bf16 v[102:105], v[148:151], v[218:221], v[102:105]
	v_mfma_f32_16x16x32_bf16 v[94:97], v[164:167], v[218:221], v[94:97]
	v_mfma_f32_16x16x32_bf16 v[82:85], v[148:151], v[226:229], v[82:85]
	v_mfma_f32_16x16x32_bf16 v[74:77], v[164:167], v[226:229], v[74:77]
	v_mfma_f32_16x16x32_bf16 v[126:129], v[160:163], v[192:195], v[126:129]
	v_mfma_f32_16x16x32_bf16 v[122:125], v[168:171], v[192:195], v[122:125]
	v_mfma_f32_16x16x32_bf16 v[118:121], v[160:163], v[214:217], v[118:121]
	v_mfma_f32_16x16x32_bf16 v[110:113], v[168:171], v[214:217], v[110:113]
	v_mfma_f32_16x16x32_bf16 v[102:105], v[160:163], v[222:225], v[102:105]
	v_mfma_f32_16x16x32_bf16 v[94:97], v[168:171], v[222:225], v[94:97]
	v_mfma_f32_16x16x32_bf16 v[82:85], v[160:163], v[230:233], v[82:85]
	v_mfma_f32_16x16x32_bf16 v[74:77], v[168:171], v[230:233], v[74:77]
	v_mfma_f32_16x16x32_bf16 v[114:117], v[172:175], v[188:191], v[114:117]
	v_mfma_f32_16x16x32_bf16 v[106:109], v[180:183], v[188:191], v[106:109]
	v_mfma_f32_16x16x32_bf16 v[98:101], v[172:175], v[210:213], v[98:101]
	v_mfma_f32_16x16x32_bf16 v[90:93], v[180:183], v[210:213], v[90:93]
	v_mfma_f32_16x16x32_bf16 v[86:89], v[172:175], v[218:221], v[86:89]
	v_mfma_f32_16x16x32_bf16 v[78:81], v[180:183], v[218:221], v[78:81]
	v_mfma_f32_16x16x32_bf16 v[70:73], v[172:175], v[226:229], v[70:73]
	v_mfma_f32_16x16x32_bf16 v[66:69], v[180:183], v[226:229], v[66:69]
	v_mfma_f32_16x16x32_bf16 v[114:117], v[176:179], v[192:195], v[114:117]
	v_mfma_f32_16x16x32_bf16 v[106:109], v[184:187], v[192:195], v[106:109]
	v_mfma_f32_16x16x32_bf16 v[98:101], v[176:179], v[214:217], v[98:101]
	v_mfma_f32_16x16x32_bf16 v[90:93], v[184:187], v[214:217], v[90:93]
	v_mfma_f32_16x16x32_bf16 v[86:89], v[176:179], v[222:225], v[86:89]
	v_mfma_f32_16x16x32_bf16 v[78:81], v[184:187], v[222:225], v[78:81]
	v_mfma_f32_16x16x32_bf16 v[70:73], v[176:179], v[230:233], v[70:73]
	v_mfma_f32_16x16x32_bf16 v[66:69], v[184:187], v[230:233], v[66:69]
	s_barrier
	s_add_i32 s16, s33, s4
	v_lshl_add_u64 v[142:143], v[142:143], 0, s[34:35]
	s_mov_b32 m0, s16
	ds_read_b128 v[188:191], v146 offset:49152
	ds_read_b128 v[192:195], v146 offset:50176
	ds_read_b128 v[210:213], v146 offset:51200
	ds_read_b128 v[214:217], v146 offset:52224
	ds_read_b128 v[218:221], v146 offset:53248
	ds_read_b128 v[222:225], v146 offset:54272
	ds_read_b128 v[226:229], v146 offset:55296
	ds_read_b128 v[230:233], v146 offset:56320
	global_load_lds_dwordx4 v[142:143], off
	s_add_i32 m0, s16, 0x2000
	s_add_u32 s0, s0, 0x160080
	v_lshl_add_u64 v[142:143], v[152:153], 0, s[34:35]
	s_addc_u32 s1, s1, 0
	s_add_i32 s16, s44, s4
	global_load_lds_dwordx4 v[142:143], off
	s_mov_b32 m0, s16
	v_lshl_add_u64 v[142:143], s[0:1], 0, v[134:135]
	global_load_lds_dwordx4 v[142:143], off
	s_add_i32 m0, s16, 0x2000
	v_lshl_add_u64 v[142:143], s[0:1], 0, v[130:131]
	global_load_lds_dwordx4 v[142:143], off
	s_mov_b32 m0, s10
	v_lshl_add_u64 v[142:143], v[196:197], 0, s[34:35]
	global_load_lds_dwordx4 v[142:143], off
	s_mov_b32 m0, s11
	v_lshl_add_u64 v[142:143], v[234:235], 0, s[34:35]
	global_load_lds_dwordx4 v[142:143], off
	s_waitcnt vmcnt(8)
	s_waitcnt lgkmcnt(0)
	s_barrier
	v_mfma_f32_16x16x32_bf16 v[62:65], v[148:151], v[188:191], v[62:65]
	v_mfma_f32_16x16x32_bf16 v[58:61], v[164:167], v[188:191], v[58:61]
	v_mfma_f32_16x16x32_bf16 v[54:57], v[148:151], v[210:213], v[54:57]
	v_mfma_f32_16x16x32_bf16 v[46:49], v[164:167], v[210:213], v[46:49]
	v_mfma_f32_16x16x32_bf16 v[38:41], v[148:151], v[218:221], v[38:41]
	v_mfma_f32_16x16x32_bf16 v[30:33], v[164:167], v[218:221], v[30:33]
	v_mfma_f32_16x16x32_bf16 v[22:25], v[148:151], v[226:229], v[22:25]
	v_mfma_f32_16x16x32_bf16 v[14:17], v[164:167], v[226:229], v[14:17]
	v_mfma_f32_16x16x32_bf16 v[62:65], v[160:163], v[192:195], v[62:65]
	v_mfma_f32_16x16x32_bf16 v[58:61], v[168:171], v[192:195], v[58:61]
	v_mfma_f32_16x16x32_bf16 v[54:57], v[160:163], v[214:217], v[54:57]
	v_mfma_f32_16x16x32_bf16 v[46:49], v[168:171], v[214:217], v[46:49]
	v_mfma_f32_16x16x32_bf16 v[38:41], v[160:163], v[222:225], v[38:41]
	v_mfma_f32_16x16x32_bf16 v[30:33], v[168:171], v[222:225], v[30:33]
	v_mfma_f32_16x16x32_bf16 v[22:25], v[160:163], v[230:233], v[22:25]
	v_mfma_f32_16x16x32_bf16 v[14:17], v[168:171], v[230:233], v[14:17]
	v_mfma_f32_16x16x32_bf16 v[50:53], v[172:175], v[188:191], v[50:53]
	v_mfma_f32_16x16x32_bf16 v[42:45], v[180:183], v[188:191], v[42:45]
	v_mfma_f32_16x16x32_bf16 v[34:37], v[172:175], v[210:213], v[34:37]
	v_mfma_f32_16x16x32_bf16 v[26:29], v[180:183], v[210:213], v[26:29]
	v_mfma_f32_16x16x32_bf16 v[18:21], v[172:175], v[218:221], v[18:21]
	v_mfma_f32_16x16x32_bf16 v[10:13], v[180:183], v[218:221], v[10:13]
	v_mfma_f32_16x16x32_bf16 v[6:9], v[172:175], v[226:229], v[6:9]
	v_mfma_f32_16x16x32_bf16 v[2:5], v[180:183], v[226:229], v[2:5]
	v_mfma_f32_16x16x32_bf16 v[50:53], v[176:179], v[192:195], v[50:53]
	v_mfma_f32_16x16x32_bf16 v[42:45], v[184:187], v[192:195], v[42:45]
	v_mfma_f32_16x16x32_bf16 v[34:37], v[176:179], v[214:217], v[34:37]
	v_mfma_f32_16x16x32_bf16 v[26:29], v[184:187], v[214:217], v[26:29]
	v_mfma_f32_16x16x32_bf16 v[18:21], v[176:179], v[222:225], v[18:21]
	v_mfma_f32_16x16x32_bf16 v[10:13], v[184:187], v[222:225], v[10:13]
	v_mfma_f32_16x16x32_bf16 v[6:9], v[176:179], v[230:233], v[6:9]
	v_mfma_f32_16x16x32_bf16 v[2:5], v[184:187], v[230:233], v[2:5]
	s_barrier
	s_add_i32 s82, s82, 2
	s_add_u32 s79, s79, 0x100
	s_addc_u32 s92, s92, 0
	s_cmpk_gt_u32 s82, 0x55
	s_mov_b64 s[44:45], s[46:47]
	s_cbranch_scc0 .LBB0_370

; #define PG8_STAGE(bufoff, gbase, voff) do { _Pragma("unroll") for (int _i = 0; _i < 2; ++_i) \
;         __builtin_amdgcn_global_load_lds((const unsigned*)((const char*)(gbase) + (voff)[_i]), (LAS unsigned*)(lds + (bufoff) + ldsw + _i * 8192), 16, 0, 0); } while (0)
; #define PG8_LDA(dst, b, h) do { _Pragma("unroll") for (int m = 0; m < 4; ++m) _Pragma("unroll") for (int k = 0; k < 2; ++k) dst[m][k] = *(const LAS bf16x8*)(lds + PG8_SA(b, h) + aoff + m * 2048 + k * 1024); } while (0)
; #define PG8_LDB(dst, b, h) do { _Pragma("unroll") for (int n = 0; n < 2; ++n) _Pragma("unroll") for (int k = 0; k < 2; ++k) dst[n][k] = *(const LAS bf16x8*)(lds + PG8_SB(b, h) + boff + n * 2048 + k * 1024); } while (0)
; #define PG8_MMA(ai, bj, At, Bt) do { __builtin_amdgcn_s_setprio(1); _Pragma("unroll") for (int m = 0; m < 4; ++m) _Pragma("unroll") for (int n = 0; n < 2; ++n) _Pragma("unroll") for (int k = 0; k < 2; ++k) \
;         acc[ai][bj][m][n] = __builtin_amdgcn_mfma_f32_16x16x32_bf16(Bt[n][k], At[m][k], acc[ai][bj][m][n], 0, 0, 0); __builtin_amdgcn_s_setprio(0); } while (0)
; #define PG8_WAIT_V(n) asm volatile("s_waitcnt vmcnt(" #n ")" ::: "memory")
; #define PG8_WAIT_L(n) asm volatile("s_waitcnt lgkmcnt(" #n ")" ::: "memory")
; #define PG8_BAR __builtin_amdgcn_s_barrier()
; #define PG8_SCHED __builtin_amdgcn_sched_barrier(0)
; template <class Epi, class Sched = StaticOrder, bool ALIGN_EPI = true>
; __device__ __forceinline__ void gemm_phase(LAS unsigned char* lds, const Gemm g, const Sched& S, const Epi& E) {
;     ...
;         for (int t = 0; t < nt; t += 2) {
;             const bool last = (t == nt - 2);
;             const char* a1 = cA + (size_t)(t + 1) * kstep;
;             const char* a2 = last ? nA : cA + (size_t)(t + 2) * kstep; const char* b2 = last ? nB : cB + (size_t)(t + 2) * kstep;
;             const char* a3 = a2 + kstep; const char* b3 = b2 + kstep;
;             PG8_LDB(B0, 0, 0); PG8_LDB(B1, 0, 1); PG8_SCHED; PG8_LDA(At, 0, 0); PG8_STAGE(PG8_SA(1, 1), a1 + hstep, voffA);
;             PG8_WAIT_V(8); PG8_WAIT_L(0); PG8_BAR; PG8_MMA(0, 0, At, B0); PG8_MMA(0, 1, At, B1); PG8_BAR; PG8_SCHED;
;             PG8_LDA(At, 0, 1); PG8_STAGE(PG8_SB(0, 0), b2, voffB); PG8_STAGE(PG8_SB(0, 1), b2 + hstep, voffB); PG8_STAGE(PG8_SA(0, 0), a2, voffA);
;             PG8_WAIT_V(8); PG8_WAIT_L(0); PG8_BAR; PG8_MMA(1, 0, At, B0); PG8_MMA(1, 1, At, B1); PG8_BAR; PG8_SCHED;
.Lmy_nb_392:
	s_add_u32 s46, s44, 0x100
	s_addc_u32 s47, s45, 0
	s_add_i32 s16, 0, 0x10000
	s_cmpk_eq_i32 s82, 0x54
	s_cselect_b32 s31, s37, s47
	s_cselect_b32 s30, s36, s46
	v_add_u32_e32 v152, s16, v135
	s_cselect_b32 s1, s43, s92
	s_cselect_b32 s0, s42, s79
	s_add_i32 s33, 0, 0x14000
	ds_read_b128 v[140:143], v152
	ds_read_b128 v[144:147], v152 offset:1024
	ds_read_b128 v[148:151], v152 offset:2048
	ds_read_b128 v[160:163], v152 offset:3072
	v_add_u32_e32 v152, s33, v135
	ds_read_b128 v[164:167], v152
	ds_read_b128 v[172:175], v152 offset:1024
	ds_read_b128 v[176:179], v152 offset:2048
	ds_read_b128 v[180:183], v152 offset:3072
	v_lshl_add_u64 v[152:153], s[44:45], 0, v[136:137]
	s_add_i32 m0, s6, 0xc000
	ds_read_b128 v[184:187], v170
	ds_read_b128 v[188:191], v170 offset:1024
	ds_read_b128 v[192:195], v170 offset:2048
	ds_read_b128 v[210:213], v170 offset:3072
	ds_read_b128 v[214:217], v170 offset:4096
	ds_read_b128 v[218:221], v170 offset:5120
	ds_read_b128 v[222:225], v170 offset:6144
	ds_read_b128 v[226:229], v170 offset:7168
	global_load_lds_dwordx4 v[152:153], off
	s_add_i32 m0, s6, 0xe000
	v_lshl_add_u64 v[152:153], s[44:45], 0, v[138:139]
	global_load_lds_dwordx4 v[152:153], off
	s_waitcnt vmcnt(8)
	s_waitcnt lgkmcnt(0)
	s_barrier
	v_mfma_f32_16x16x32_bf16 v[126:129], v[140:143], v[184:187], 0
	v_mfma_f32_16x16x32_bf16 v[122:125], v[148:151], v[184:187], 0
	v_mfma_f32_16x16x32_bf16 v[118:121], v[140:143], v[192:195], 0
	v_mfma_f32_16x16x32_bf16 v[106:109], v[148:151], v[192:195], 0
	v_mfma_f32_16x16x32_bf16 v[98:101], v[140:143], v[214:217], 0
	v_mfma_f32_16x16x32_bf16 v[90:93], v[148:151], v[214:217], 0
	v_mfma_f32_16x16x32_bf16 v[82:85], v[140:143], v[222:225], 0
	v_mfma_f32_16x16x32_bf16 v[74:77], v[148:151], v[222:225], 0
	v_mfma_f32_16x16x32_bf16 v[126:129], v[144:147], v[188:191], v[126:129]
	v_mfma_f32_16x16x32_bf16 v[122:125], v[160:163], v[188:191], v[122:125]
	v_mfma_f32_16x16x32_bf16 v[118:121], v[144:147], v[210:213], v[118:121]
	v_mfma_f32_16x16x32_bf16 v[106:109], v[160:163], v[210:213], v[106:109]
	v_mfma_f32_16x16x32_bf16 v[98:101], v[144:147], v[218:221], v[98:101]
	v_mfma_f32_16x16x32_bf16 v[90:93], v[160:163], v[218:221], v[90:93]
	v_mfma_f32_16x16x32_bf16 v[82:85], v[144:147], v[226:229], v[82:85]
	v_mfma_f32_16x16x32_bf16 v[74:77], v[160:163], v[226:229], v[74:77]
	v_mfma_f32_16x16x32_bf16 v[114:117], v[164:167], v[184:187], 0
	v_mfma_f32_16x16x32_bf16 v[110:113], v[176:179], v[184:187], 0
	v_mfma_f32_16x16x32_bf16 v[102:105], v[164:167], v[192:195], 0
	v_mfma_f32_16x16x32_bf16 v[94:97], v[176:179], v[192:195], 0
	v_mfma_f32_16x16x32_bf16 v[86:89], v[164:167], v[214:217], 0
	v_mfma_f32_16x16x32_bf16 v[78:81], v[176:179], v[214:217], 0
	v_mfma_f32_16x16x32_bf16 v[70:73], v[164:167], v[222:225], 0
	v_mfma_f32_16x16x32_bf16 v[66:69], v[176:179], v[222:225], 0
	v_mfma_f32_16x16x32_bf16 v[114:117], v[172:175], v[188:191], v[114:117]
	v_mfma_f32_16x16x32_bf16 v[110:113], v[180:183], v[188:191], v[110:113]
	v_mfma_f32_16x16x32_bf16 v[102:105], v[172:175], v[210:213], v[102:105]
	v_mfma_f32_16x16x32_bf16 v[94:97], v[180:183], v[210:213], v[94:97]
	v_mfma_f32_16x16x32_bf16 v[86:89], v[172:175], v[218:221], v[86:89]
	v_mfma_f32_16x16x32_bf16 v[78:81], v[180:183], v[218:221], v[78:81]
	v_mfma_f32_16x16x32_bf16 v[70:73], v[172:175], v[226:229], v[70:73]
	v_mfma_f32_16x16x32_bf16 v[66:69], v[180:183], v[226:229], v[66:69]
	s_barrier
	s_add_i32 s16, s16, s4
	v_lshl_add_u64 v[152:153], s[0:1], 0, v[132:133]
	s_mov_b32 m0, s16
	ds_read_b128 v[184:187], v170 offset:16384
	ds_read_b128 v[188:191], v170 offset:17408
	ds_read_b128 v[192:195], v170 offset:18432
	ds_read_b128 v[210:213], v170 offset:19456
	ds_read_b128 v[214:217], v170 offset:20480
	ds_read_b128 v[218:221], v170 offset:21504
	ds_read_b128 v[222:225], v170 offset:22528
	ds_read_b128 v[226:229], v170 offset:23552
	global_load_lds_dwordx4 v[152:153], off
	s_add_i32 m0, s16, 0x2000
	s_add_u32 s16, s0, 0x160000
	v_lshl_add_u64 v[168:169], s[0:1], 0, v[130:131]
	s_addc_u32 s17, s1, 0
	s_add_i32 s33, s33, s4
	global_load_lds_dwordx4 v[168:169], off
	v_lshl_add_u64 v[196:197], s[16:17], 0, v[132:133]
	s_mov_b32 m0, s33
	v_lshl_add_u64 v[230:231], s[30:31], 0, v[130:131]
	global_load_lds_dwordx4 v[196:197], off
	s_add_i32 m0, s33, 0x2000
	v_lshl_add_u64 v[196:197], s[16:17], 0, v[130:131]
	global_load_lds_dwordx4 v[196:197], off
	s_mov_b32 m0, s6
	v_lshl_add_u64 v[196:197], s[30:31], 0, v[132:133]
	global_load_lds_dwordx4 v[196:197], off
	s_mov_b32 m0, s7
	s_nop 0
	global_load_lds_dwordx4 v[230:231], off
	s_waitcnt vmcnt(8)
	s_waitcnt lgkmcnt(0)
	s_barrier
; #define PG8_STAGE(bufoff, gbase, voff) do { _Pragma("unroll") for (int _i = 0; _i < 2; ++_i) \
;         __builtin_amdgcn_global_load_lds((const unsigned*)((const char*)(gbase) + (voff)[_i]), (LAS unsigned*)(lds + (bufoff) + ldsw + _i * 8192), 16, 0, 0); } while (0)
; #define PG8_LDA(dst, b, h) do { _Pragma("unroll") for (int m = 0; m < 4; ++m) _Pragma("unroll") for (int k = 0; k < 2; ++k) dst[m][k] = *(const LAS bf16x8*)(lds + PG8_SA(b, h) + aoff + m * 2048 + k * 1024); } while (0)
; #define PG8_LDB(dst, b, h) do { _Pragma("unroll") for (int n = 0; n < 2; ++n) _Pragma("unroll") for (int k = 0; k < 2; ++k) dst[n][k] = *(const LAS bf16x8*)(lds + PG8_SB(b, h) + boff + n * 2048 + k * 1024); } while (0)
; #define PG8_MMA(ai, bj, At, Bt) do { __builtin_amdgcn_s_setprio(1); _Pragma("unroll") for (int m = 0; m < 4; ++m) _Pragma("unroll") for (int n = 0; n < 2; ++n) _Pragma("unroll") for (int k = 0; k < 2; ++k) \
;         acc[ai][bj][m][n] = __builtin_amdgcn_mfma_f32_16x16x32_bf16(Bt[n][k], At[m][k], acc[ai][bj][m][n], 0, 0, 0); __builtin_amdgcn_s_setprio(0); } while (0)
; #define PG8_WAIT_V(n) asm volatile("s_waitcnt vmcnt(" #n ")" ::: "memory")
; #define PG8_WAIT_L(n) asm volatile("s_waitcnt lgkmcnt(" #n ")" ::: "memory")
; #define PG8_BAR __builtin_amdgcn_s_barrier()
; #define PG8_SCHED __builtin_amdgcn_sched_barrier(0)
; template <class Epi, class Sched = StaticOrder, bool ALIGN_EPI = true>
; __device__ __forceinline__ void gemm_phase(LAS unsigned char* lds, const Gemm g, const Sched& S, const Epi& E) {
;     ...
;             PG8_WAIT_V(8); PG8_WAIT_L(0); PG8_BAR; PG8_MMA(1, 0, At, B0); PG8_MMA(1, 1, At, B1); PG8_BAR; PG8_SCHED;
;             PG8_LDB(B0, 1, 0); PG8_LDB(B1, 1, 1); PG8_SCHED; PG8_LDA(At, 1, 0); PG8_STAGE(PG8_SA(0, 1), a2 + hstep, voffA);
;             PG8_WAIT_V(8); PG8_WAIT_L(0); PG8_BAR; PG8_MMA(0, 0, At, B0); PG8_MMA(0, 1, At, B1); PG8_BAR; PG8_SCHED;
	v_mfma_f32_16x16x32_bf16 v[62:65], v[140:143], v[184:187], 0
	v_mfma_f32_16x16x32_bf16 v[58:61], v[148:151], v[184:187], 0
	v_mfma_f32_16x16x32_bf16 v[50:53], v[140:143], v[192:195], 0
	v_mfma_f32_16x16x32_bf16 v[42:45], v[148:151], v[192:195], 0
	v_mfma_f32_16x16x32_bf16 v[34:37], v[140:143], v[214:217], 0
	v_mfma_f32_16x16x32_bf16 v[26:29], v[148:151], v[214:217], 0
	v_mfma_f32_16x16x32_bf16 v[18:21], v[140:143], v[222:225], 0
	v_mfma_f32_16x16x32_bf16 v[10:13], v[148:151], v[222:225], 0
	v_mfma_f32_16x16x32_bf16 v[62:65], v[144:147], v[188:191], v[62:65]
	v_mfma_f32_16x16x32_bf16 v[58:61], v[160:163], v[188:191], v[58:61]
	v_mfma_f32_16x16x32_bf16 v[50:53], v[144:147], v[210:213], v[50:53]
	v_mfma_f32_16x16x32_bf16 v[42:45], v[160:163], v[210:213], v[42:45]
	v_mfma_f32_16x16x32_bf16 v[34:37], v[144:147], v[218:221], v[34:37]
	v_mfma_f32_16x16x32_bf16 v[26:29], v[160:163], v[218:221], v[26:29]
	v_mfma_f32_16x16x32_bf16 v[18:21], v[144:147], v[226:229], v[18:21]
	v_mfma_f32_16x16x32_bf16 v[10:13], v[160:163], v[226:229], v[10:13]
	v_mfma_f32_16x16x32_bf16 v[54:57], v[164:167], v[184:187], 0
	v_mfma_f32_16x16x32_bf16 v[46:49], v[176:179], v[184:187], 0
	v_mfma_f32_16x16x32_bf16 v[38:41], v[164:167], v[192:195], 0
	v_mfma_f32_16x16x32_bf16 v[30:33], v[176:179], v[192:195], 0
	v_mfma_f32_16x16x32_bf16 v[22:25], v[164:167], v[214:217], 0
	v_mfma_f32_16x16x32_bf16 v[14:17], v[176:179], v[214:217], 0
	v_mfma_f32_16x16x32_bf16 v[6:9], v[164:167], v[222:225], 0
	v_mfma_f32_16x16x32_bf16 v[2:5], v[176:179], v[222:225], 0
	v_mfma_f32_16x16x32_bf16 v[54:57], v[172:175], v[188:191], v[54:57]
	v_mfma_f32_16x16x32_bf16 v[46:49], v[180:183], v[188:191], v[46:49]
	v_mfma_f32_16x16x32_bf16 v[38:41], v[172:175], v[210:213], v[38:41]
	v_mfma_f32_16x16x32_bf16 v[30:33], v[180:183], v[210:213], v[30:33]
	v_mfma_f32_16x16x32_bf16 v[22:25], v[172:175], v[218:221], v[22:25]
	v_mfma_f32_16x16x32_bf16 v[14:17], v[180:183], v[218:221], v[14:17]
	v_mfma_f32_16x16x32_bf16 v[6:9], v[172:175], v[226:229], v[6:9]
	v_mfma_f32_16x16x32_bf16 v[2:5], v[180:183], v[226:229], v[2:5]
	s_barrier
	s_add_i32 s33, 0, 0x18000
	s_add_i32 s44, 0, 0x1c000
	v_add_u32_e32 v160, s33, v135
	v_add_u32_e32 v171, s44, v135
	ds_read_b128 v[140:143], v160
	ds_read_b128 v[144:147], v160 offset:1024
	ds_read_b128 v[148:151], v160 offset:2048
	ds_read_b128 v[160:163], v160 offset:3072
	ds_read_b128 v[164:167], v171
	ds_read_b128 v[172:175], v171 offset:1024
	ds_read_b128 v[176:179], v171 offset:2048
	ds_read_b128 v[180:183], v171 offset:3072
	s_add_u32 s16, s30, 0x160000
	s_addc_u32 s17, s31, 0
	s_mov_b32 m0, s8
	v_lshl_add_u64 v[232:233], s[16:17], 0, v[132:133]
	ds_read_b128 v[184:187], v170 offset:32768
	ds_read_b128 v[188:191], v170 offset:33792
	ds_read_b128 v[192:195], v170 offset:34816
	ds_read_b128 v[210:213], v170 offset:35840
	ds_read_b128 v[214:217], v170 offset:36864
	ds_read_b128 v[218:221], v170 offset:37888
	ds_read_b128 v[222:225], v170 offset:38912
	ds_read_b128 v[226:229], v170 offset:39936
	global_load_lds_dwordx4 v[232:233], off
	s_mov_b32 m0, s9
	v_lshl_add_u64 v[232:233], s[16:17], 0, v[130:131]
	global_load_lds_dwordx4 v[232:233], off
	s_waitcnt vmcnt(8)
	s_waitcnt lgkmcnt(0)
	s_barrier
	v_mfma_f32_16x16x32_bf16 v[126:129], v[140:143], v[184:187], v[126:129]
	v_mfma_f32_16x16x32_bf16 v[122:125], v[148:151], v[184:187], v[122:125]
	v_mfma_f32_16x16x32_bf16 v[118:121], v[140:143], v[192:195], v[118:121]
	v_mfma_f32_16x16x32_bf16 v[106:109], v[148:151], v[192:195], v[106:109]
	v_mfma_f32_16x16x32_bf16 v[98:101], v[140:143], v[214:217], v[98:101]
	v_mfma_f32_16x16x32_bf16 v[90:93], v[148:151], v[214:217], v[90:93]
	v_mfma_f32_16x16x32_bf16 v[82:85], v[140:143], v[222:225], v[82:85]
	v_mfma_f32_16x16x32_bf16 v[74:77], v[148:151], v[222:225], v[74:77]
	v_mfma_f32_16x16x32_bf16 v[126:129], v[144:147], v[188:191], v[126:129]
	v_mfma_f32_16x16x32_bf16 v[122:125], v[160:163], v[188:191], v[122:125]
	v_mfma_f32_16x16x32_bf16 v[118:121], v[144:147], v[210:213], v[118:121]
	v_mfma_f32_16x16x32_bf16 v[106:109], v[160:163], v[210:213], v[106:109]
	v_mfma_f32_16x16x32_bf16 v[98:101], v[144:147], v[218:221], v[98:101]
	v_mfma_f32_16x16x32_bf16 v[90:93], v[160:163], v[218:221], v[90:93]
	v_mfma_f32_16x16x32_bf16 v[82:85], v[144:147], v[226:229], v[82:85]
	v_mfma_f32_16x16x32_bf16 v[74:77], v[160:163], v[226:229], v[74:77]
	v_mfma_f32_16x16x32_bf16 v[114:117], v[164:167], v[184:187], v[114:117]
	v_mfma_f32_16x16x32_bf16 v[110:113], v[176:179], v[184:187], v[110:113]
	v_mfma_f32_16x16x32_bf16 v[102:105], v[164:167], v[192:195], v[102:105]
	v_mfma_f32_16x16x32_bf16 v[94:97], v[176:179], v[192:195], v[94:97]
	v_mfma_f32_16x16x32_bf16 v[86:89], v[164:167], v[214:217], v[86:89]
	v_mfma_f32_16x16x32_bf16 v[78:81], v[176:179], v[214:217], v[78:81]
	v_mfma_f32_16x16x32_bf16 v[70:73], v[164:167], v[222:225], v[70:73]
	v_mfma_f32_16x16x32_bf16 v[66:69], v[176:179], v[222:225], v[66:69]
	v_mfma_f32_16x16x32_bf16 v[114:117], v[172:175], v[188:191], v[114:117]
	v_mfma_f32_16x16x32_bf16 v[110:113], v[180:183], v[188:191], v[110:113]
	v_mfma_f32_16x16x32_bf16 v[102:105], v[172:175], v[210:213], v[102:105]
	v_mfma_f32_16x16x32_bf16 v[94:97], v[180:183], v[210:213], v[94:97]
	v_mfma_f32_16x16x32_bf16 v[86:89], v[172:175], v[218:221], v[86:89]
	v_mfma_f32_16x16x32_bf16 v[78:81], v[180:183], v[218:221], v[78:81]
	v_mfma_f32_16x16x32_bf16 v[70:73], v[172:175], v[226:229], v[70:73]
	v_mfma_f32_16x16x32_bf16 v[66:69], v[180:183], v[226:229], v[66:69]
	s_barrier
; #define PG8_STAGE(bufoff, gbase, voff) do { _Pragma("unroll") for (int _i = 0; _i < 2; ++_i) \
;         __builtin_amdgcn_global_load_lds((const unsigned*)((const char*)(gbase) + (voff)[_i]), (LAS unsigned*)(lds + (bufoff) + ldsw + _i * 8192), 16, 0, 0); } while (0)
; #define PG8_LDA(dst, b, h) do { _Pragma("unroll") for (int m = 0; m < 4; ++m) _Pragma("unroll") for (int k = 0; k < 2; ++k) dst[m][k] = *(const LAS bf16x8*)(lds + PG8_SA(b, h) + aoff + m * 2048 + k * 1024); } while (0)
; #define PG8_LDB(dst, b, h) do { _Pragma("unroll") for (int n = 0; n < 2; ++n) _Pragma("unroll") for (int k = 0; k < 2; ++k) dst[n][k] = *(const LAS bf16x8*)(lds + PG8_SB(b, h) + boff + n * 2048 + k * 1024); } while (0)
; #define PG8_MMA(ai, bj, At, Bt) do { __builtin_amdgcn_s_setprio(1); _Pragma("unroll") for (int m = 0; m < 4; ++m) _Pragma("unroll") for (int n = 0; n < 2; ++n) _Pragma("unroll") for (int k = 0; k < 2; ++k) \
;         acc[ai][bj][m][n] = __builtin_amdgcn_mfma_f32_16x16x32_bf16(Bt[n][k], At[m][k], acc[ai][bj][m][n], 0, 0, 0); __builtin_amdgcn_s_setprio(0); } while (0)
; #define PG8_WAIT_V(n) asm volatile("s_waitcnt vmcnt(" #n ")" ::: "memory")
; #define PG8_WAIT_L(n) asm volatile("s_waitcnt lgkmcnt(" #n ")" ::: "memory")
; #define PG8_BAR __builtin_amdgcn_s_barrier()
; #define PG8_SCHED __builtin_amdgcn_sched_barrier(0)
; template <class Epi, class Sched = StaticOrder, bool ALIGN_EPI = true>
; __device__ __forceinline__ void gemm_phase(LAS unsigned char* lds, const Gemm g, const Sched& S, const Epi& E) {
;     ...
;         for (int t = 0; t < nt; t += 2) {
;             const bool last = (t == nt - 2);
;             const char* a1 = cA + (size_t)(t + 1) * kstep;
;             const char* a2 = last ? nA : cA + (size_t)(t + 2) * kstep; const char* b2 = last ? nB : cB + (size_t)(t + 2) * kstep;
;             const char* a3 = a2 + kstep; const char* b3 = b2 + kstep;
;             PG8_LDB(B0, 0, 0); PG8_LDB(B1, 0, 1); PG8_SCHED; PG8_LDA(At, 0, 0); PG8_STAGE(PG8_SA(1, 1), a1 + hstep, voffA);
;     ...
;             PG8_LDA(At, 1, 1); PG8_STAGE(PG8_SB(1, 0), b3, voffB); PG8_STAGE(PG8_SB(1, 1), b3 + hstep, voffB); PG8_STAGE(PG8_SA(1, 0), a3, voffA);
;             PG8_WAIT_V(8); PG8_WAIT_L(0); PG8_BAR; PG8_MMA(1, 0, At, B0); PG8_MMA(1, 1, At, B1); PG8_BAR; PG8_SCHED;
	s_add_i32 s16, s33, s4
	v_lshl_add_u64 v[152:153], v[152:153], 0, s[34:35]
	s_mov_b32 m0, s16
	ds_read_b128 v[184:187], v170 offset:49152
	ds_read_b128 v[188:191], v170 offset:50176
	ds_read_b128 v[192:195], v170 offset:51200
	ds_read_b128 v[210:213], v170 offset:52224
	ds_read_b128 v[214:217], v170 offset:53248
	ds_read_b128 v[218:221], v170 offset:54272
	ds_read_b128 v[222:225], v170 offset:55296
	ds_read_b128 v[226:229], v170 offset:56320
	global_load_lds_dwordx4 v[152:153], off
	s_add_i32 m0, s16, 0x2000
	s_add_u32 s0, s0, 0x160080
	v_lshl_add_u64 v[152:153], v[168:169], 0, s[34:35]
	s_addc_u32 s1, s1, 0
	s_add_i32 s16, s44, s4
	global_load_lds_dwordx4 v[152:153], off
	s_mov_b32 m0, s16
	v_lshl_add_u64 v[152:153], s[0:1], 0, v[132:133]
	global_load_lds_dwordx4 v[152:153], off
	s_add_i32 m0, s16, 0x2000
	v_lshl_add_u64 v[152:153], s[0:1], 0, v[130:131]
	global_load_lds_dwordx4 v[152:153], off
	s_mov_b32 m0, s10
	v_lshl_add_u64 v[152:153], v[196:197], 0, s[34:35]
	global_load_lds_dwordx4 v[152:153], off
	s_mov_b32 m0, s11
	v_lshl_add_u64 v[152:153], v[230:231], 0, s[34:35]
	global_load_lds_dwordx4 v[152:153], off
	s_waitcnt vmcnt(8)
	s_waitcnt lgkmcnt(0)
	s_barrier
	v_mfma_f32_16x16x32_bf16 v[62:65], v[140:143], v[184:187], v[62:65]
	v_mfma_f32_16x16x32_bf16 v[58:61], v[148:151], v[184:187], v[58:61]
	v_mfma_f32_16x16x32_bf16 v[50:53], v[140:143], v[192:195], v[50:53]
	v_mfma_f32_16x16x32_bf16 v[42:45], v[148:151], v[192:195], v[42:45]
	v_mfma_f32_16x16x32_bf16 v[34:37], v[140:143], v[214:217], v[34:37]
	v_mfma_f32_16x16x32_bf16 v[26:29], v[148:151], v[214:217], v[26:29]
	v_mfma_f32_16x16x32_bf16 v[18:21], v[140:143], v[222:225], v[18:21]
	v_mfma_f32_16x16x32_bf16 v[10:13], v[148:151], v[222:225], v[10:13]
	v_mfma_f32_16x16x32_bf16 v[62:65], v[144:147], v[188:191], v[62:65]
	v_mfma_f32_16x16x32_bf16 v[58:61], v[160:163], v[188:191], v[58:61]
	v_mfma_f32_16x16x32_bf16 v[50:53], v[144:147], v[210:213], v[50:53]
	v_mfma_f32_16x16x32_bf16 v[42:45], v[160:163], v[210:213], v[42:45]
	v_mfma_f32_16x16x32_bf16 v[34:37], v[144:147], v[218:221], v[34:37]
	v_mfma_f32_16x16x32_bf16 v[26:29], v[160:163], v[218:221], v[26:29]
	v_mfma_f32_16x16x32_bf16 v[18:21], v[144:147], v[226:229], v[18:21]
	v_mfma_f32_16x16x32_bf16 v[10:13], v[160:163], v[226:229], v[10:13]
	v_mfma_f32_16x16x32_bf16 v[54:57], v[164:167], v[184:187], v[54:57]
	v_mfma_f32_16x16x32_bf16 v[46:49], v[176:179], v[184:187], v[46:49]
	v_mfma_f32_16x16x32_bf16 v[38:41], v[164:167], v[192:195], v[38:41]
	v_mfma_f32_16x16x32_bf16 v[30:33], v[176:179], v[192:195], v[30:33]
	v_mfma_f32_16x16x32_bf16 v[22:25], v[164:167], v[214:217], v[22:25]
	v_mfma_f32_16x16x32_bf16 v[14:17], v[176:179], v[214:217], v[14:17]
	v_mfma_f32_16x16x32_bf16 v[6:9], v[164:167], v[222:225], v[6:9]
	v_mfma_f32_16x16x32_bf16 v[2:5], v[176:179], v[222:225], v[2:5]
	v_mfma_f32_16x16x32_bf16 v[54:57], v[172:175], v[188:191], v[54:57]
	v_mfma_f32_16x16x32_bf16 v[46:49], v[180:183], v[188:191], v[46:49]
	v_mfma_f32_16x16x32_bf16 v[38:41], v[172:175], v[210:213], v[38:41]
	v_mfma_f32_16x16x32_bf16 v[30:33], v[180:183], v[210:213], v[30:33]
	v_mfma_f32_16x16x32_bf16 v[22:25], v[172:175], v[218:221], v[22:25]
	v_mfma_f32_16x16x32_bf16 v[14:17], v[180:183], v[218:221], v[14:17]
	v_mfma_f32_16x16x32_bf16 v[6:9], v[172:175], v[226:229], v[6:9]
	v_mfma_f32_16x16x32_bf16 v[2:5], v[180:183], v[226:229], v[2:5]
	s_barrier
	s_add_i32 s82, s82, 2
	s_add_u32 s79, s79, 0x100
	s_addc_u32 s92, s92, 0
	s_cmpk_gt_u32 s82, 0x55
	s_mov_b64 s[44:45], s[46:47]
	s_cbranch_scc0 .LBB0_392
.LBB0_392:
	s_add_u32 s46, s44, 0x100
	s_addc_u32 s47, s45, 0
	s_add_i32 s16, 0, 0x10000
	s_cmpk_eq_i32 s82, 0x54
	s_cselect_b32 s31, s37, s47
	s_cselect_b32 s30, s36, s46
	v_add_u32_e32 v152, s16, v135
	s_cselect_b32 s1, s43, s92
	s_cselect_b32 s0, s42, s79
	s_add_i32 s33, 0, 0x14000
	ds_read_b128 v[140:143], v152
	ds_read_b128 v[144:147], v152 offset:1024
	ds_read_b128 v[148:151], v152 offset:2048
	ds_read_b128 v[160:163], v152 offset:3072
	v_add_u32_e32 v152, s33, v135
	ds_read_b128 v[164:167], v152
	ds_read_b128 v[172:175], v152 offset:1024
	ds_read_b128 v[176:179], v152 offset:2048
	ds_read_b128 v[180:183], v152 offset:3072
	v_lshl_add_u64 v[152:153], s[44:45], 0, v[136:137]
	s_add_i32 m0, s6, 0xc000
	ds_read_b128 v[184:187], v170
	ds_read_b128 v[188:191], v170 offset:1024
	ds_read_b128 v[192:195], v170 offset:2048
	ds_read_b128 v[210:213], v170 offset:3072
	ds_read_b128 v[214:217], v170 offset:4096
	ds_read_b128 v[218:221], v170 offset:5120
	ds_read_b128 v[222:225], v170 offset:6144
	ds_read_b128 v[226:229], v170 offset:7168
	global_load_lds_dwordx4 v[152:153], off
	s_add_i32 m0, s6, 0xe000
	v_lshl_add_u64 v[152:153], s[44:45], 0, v[138:139]
	global_load_lds_dwordx4 v[152:153], off
	s_waitcnt vmcnt(8)
	s_waitcnt lgkmcnt(0)
	s_barrier
; #define PG8_STAGE(bufoff, gbase, voff) do { _Pragma("unroll") for (int _i = 0; _i < 2; ++_i) \
;         __builtin_amdgcn_global_load_lds((const unsigned*)((const char*)(gbase) + (voff)[_i]), (LAS unsigned*)(lds + (bufoff) + ldsw + _i * 8192), 16, 0, 0); } while (0)
; #define PG8_LDA(dst, b, h) do { _Pragma("unroll") for (int m = 0; m < 4; ++m) _Pragma("unroll") for (int k = 0; k < 2; ++k) dst[m][k] = *(const LAS bf16x8*)(lds + PG8_SA(b, h) + aoff + m * 2048 + k * 1024); } while (0)
; #define PG8_MMA(ai, bj, At, Bt) do { __builtin_amdgcn_s_setprio(1); _Pragma("unroll") for (int m = 0; m < 4; ++m) _Pragma("unroll") for (int n = 0; n < 2; ++n) _Pragma("unroll") for (int k = 0; k < 2; ++k) \
;         acc[ai][bj][m][n] = __builtin_amdgcn_mfma_f32_16x16x32_bf16(Bt[n][k], At[m][k], acc[ai][bj][m][n], 0, 0, 0); __builtin_amdgcn_s_setprio(0); } while (0)
; #define PG8_WAIT_V(n) asm volatile("s_waitcnt vmcnt(" #n ")" ::: "memory")
; #define PG8_WAIT_L(n) asm volatile("s_waitcnt lgkmcnt(" #n ")" ::: "memory")
; #define PG8_BAR __builtin_amdgcn_s_barrier()
; #define PG8_SCHED __builtin_amdgcn_sched_barrier(0)
; template <class Epi, class Sched = StaticOrder, bool ALIGN_EPI = true>
; __device__ __forceinline__ void gemm_phase(LAS unsigned char* lds, const Gemm g, const Sched& S, const Epi& E) {
;     ...
;             PG8_WAIT_V(8); PG8_WAIT_L(0); PG8_BAR; PG8_MMA(0, 0, At, B0); PG8_MMA(0, 1, At, B1); PG8_BAR; PG8_SCHED;
;             PG8_LDA(At, 0, 1); PG8_STAGE(PG8_SB(0, 0), b2, voffB); PG8_STAGE(PG8_SB(0, 1), b2 + hstep, voffB); PG8_STAGE(PG8_SA(0, 0), a2, voffA);
;             PG8_WAIT_V(8); PG8_WAIT_L(0); PG8_BAR; PG8_MMA(1, 0, At, B0); PG8_MMA(1, 1, At, B1); PG8_BAR; PG8_SCHED;
	v_mfma_f32_16x16x32_bf16 v[126:129], v[140:143], v[184:187], v[126:129]
	v_mfma_f32_16x16x32_bf16 v[122:125], v[148:151], v[184:187], v[122:125]
	v_mfma_f32_16x16x32_bf16 v[118:121], v[140:143], v[192:195], v[118:121]
	v_mfma_f32_16x16x32_bf16 v[106:109], v[148:151], v[192:195], v[106:109]
	v_mfma_f32_16x16x32_bf16 v[98:101], v[140:143], v[214:217], v[98:101]
	v_mfma_f32_16x16x32_bf16 v[90:93], v[148:151], v[214:217], v[90:93]
	v_mfma_f32_16x16x32_bf16 v[82:85], v[140:143], v[222:225], v[82:85]
	v_mfma_f32_16x16x32_bf16 v[74:77], v[148:151], v[222:225], v[74:77]
	v_mfma_f32_16x16x32_bf16 v[126:129], v[144:147], v[188:191], v[126:129]
	v_mfma_f32_16x16x32_bf16 v[122:125], v[160:163], v[188:191], v[122:125]
	v_mfma_f32_16x16x32_bf16 v[118:121], v[144:147], v[210:213], v[118:121]
	v_mfma_f32_16x16x32_bf16 v[106:109], v[160:163], v[210:213], v[106:109]
	v_mfma_f32_16x16x32_bf16 v[98:101], v[144:147], v[218:221], v[98:101]
	v_mfma_f32_16x16x32_bf16 v[90:93], v[160:163], v[218:221], v[90:93]
	v_mfma_f32_16x16x32_bf16 v[82:85], v[144:147], v[226:229], v[82:85]
	v_mfma_f32_16x16x32_bf16 v[74:77], v[160:163], v[226:229], v[74:77]
	v_mfma_f32_16x16x32_bf16 v[114:117], v[164:167], v[184:187], v[114:117]
	v_mfma_f32_16x16x32_bf16 v[110:113], v[176:179], v[184:187], v[110:113]
	v_mfma_f32_16x16x32_bf16 v[102:105], v[164:167], v[192:195], v[102:105]
	v_mfma_f32_16x16x32_bf16 v[94:97], v[176:179], v[192:195], v[94:97]
	v_mfma_f32_16x16x32_bf16 v[86:89], v[164:167], v[214:217], v[86:89]
	v_mfma_f32_16x16x32_bf16 v[78:81], v[176:179], v[214:217], v[78:81]
	v_mfma_f32_16x16x32_bf16 v[70:73], v[164:167], v[222:225], v[70:73]
	v_mfma_f32_16x16x32_bf16 v[66:69], v[176:179], v[222:225], v[66:69]
	v_mfma_f32_16x16x32_bf16 v[114:117], v[172:175], v[188:191], v[114:117]
	v_mfma_f32_16x16x32_bf16 v[110:113], v[180:183], v[188:191], v[110:113]
	v_mfma_f32_16x16x32_bf16 v[102:105], v[172:175], v[210:213], v[102:105]
	v_mfma_f32_16x16x32_bf16 v[94:97], v[180:183], v[210:213], v[94:97]
	v_mfma_f32_16x16x32_bf16 v[86:89], v[172:175], v[218:221], v[86:89]
	v_mfma_f32_16x16x32_bf16 v[78:81], v[180:183], v[218:221], v[78:81]
	v_mfma_f32_16x16x32_bf16 v[70:73], v[172:175], v[226:229], v[70:73]
	v_mfma_f32_16x16x32_bf16 v[66:69], v[180:183], v[226:229], v[66:69]
	s_barrier
	s_add_i32 s16, s16, s4
	v_lshl_add_u64 v[152:153], s[0:1], 0, v[132:133]
	s_mov_b32 m0, s16
	ds_read_b128 v[184:187], v170 offset:16384
	ds_read_b128 v[188:191], v170 offset:17408
	ds_read_b128 v[192:195], v170 offset:18432
	ds_read_b128 v[210:213], v170 offset:19456
	ds_read_b128 v[214:217], v170 offset:20480
	ds_read_b128 v[218:221], v170 offset:21504
	ds_read_b128 v[222:225], v170 offset:22528
	ds_read_b128 v[226:229], v170 offset:23552
	global_load_lds_dwordx4 v[152:153], off
	s_add_i32 m0, s16, 0x2000
	s_add_u32 s16, s0, 0x160000
	v_lshl_add_u64 v[168:169], s[0:1], 0, v[130:131]
	s_addc_u32 s17, s1, 0
	s_add_i32 s33, s33, s4
	global_load_lds_dwordx4 v[168:169], off
	v_lshl_add_u64 v[196:197], s[16:17], 0, v[132:133]
	s_mov_b32 m0, s33
	v_lshl_add_u64 v[230:231], s[30:31], 0, v[130:131]
	global_load_lds_dwordx4 v[196:197], off
	s_add_i32 m0, s33, 0x2000
	v_lshl_add_u64 v[196:197], s[16:17], 0, v[130:131]
	global_load_lds_dwordx4 v[196:197], off
	s_mov_b32 m0, s6
	v_lshl_add_u64 v[196:197], s[30:31], 0, v[132:133]
	global_load_lds_dwordx4 v[196:197], off
	s_mov_b32 m0, s7
	s_nop 0
	global_load_lds_dwordx4 v[230:231], off
	s_waitcnt vmcnt(8)
	s_waitcnt lgkmcnt(0)
	s_barrier
	v_mfma_f32_16x16x32_bf16 v[62:65], v[140:143], v[184:187], v[62:65]
	v_mfma_f32_16x16x32_bf16 v[58:61], v[148:151], v[184:187], v[58:61]
	v_mfma_f32_16x16x32_bf16 v[50:53], v[140:143], v[192:195], v[50:53]
	v_mfma_f32_16x16x32_bf16 v[42:45], v[148:151], v[192:195], v[42:45]
	v_mfma_f32_16x16x32_bf16 v[34:37], v[140:143], v[214:217], v[34:37]
	v_mfma_f32_16x16x32_bf16 v[26:29], v[148:151], v[214:217], v[26:29]
	v_mfma_f32_16x16x32_bf16 v[18:21], v[140:143], v[222:225], v[18:21]
	v_mfma_f32_16x16x32_bf16 v[10:13], v[148:151], v[222:225], v[10:13]
	v_mfma_f32_16x16x32_bf16 v[62:65], v[144:147], v[188:191], v[62:65]
	v_mfma_f32_16x16x32_bf16 v[58:61], v[160:163], v[188:191], v[58:61]
	v_mfma_f32_16x16x32_bf16 v[50:53], v[144:147], v[210:213], v[50:53]
	v_mfma_f32_16x16x32_bf16 v[42:45], v[160:163], v[210:213], v[42:45]
	v_mfma_f32_16x16x32_bf16 v[34:37], v[144:147], v[218:221], v[34:37]
	v_mfma_f32_16x16x32_bf16 v[26:29], v[160:163], v[218:221], v[26:29]
	v_mfma_f32_16x16x32_bf16 v[18:21], v[144:147], v[226:229], v[18:21]
	v_mfma_f32_16x16x32_bf16 v[10:13], v[160:163], v[226:229], v[10:13]
	v_mfma_f32_16x16x32_bf16 v[54:57], v[164:167], v[184:187], v[54:57]
	v_mfma_f32_16x16x32_bf16 v[46:49], v[176:179], v[184:187], v[46:49]
	v_mfma_f32_16x16x32_bf16 v[38:41], v[164:167], v[192:195], v[38:41]
	v_mfma_f32_16x16x32_bf16 v[30:33], v[176:179], v[192:195], v[30:33]
	v_mfma_f32_16x16x32_bf16 v[22:25], v[164:167], v[214:217], v[22:25]
	v_mfma_f32_16x16x32_bf16 v[14:17], v[176:179], v[214:217], v[14:17]
	v_mfma_f32_16x16x32_bf16 v[6:9], v[164:167], v[222:225], v[6:9]
	v_mfma_f32_16x16x32_bf16 v[2:5], v[176:179], v[222:225], v[2:5]
	v_mfma_f32_16x16x32_bf16 v[54:57], v[172:175], v[188:191], v[54:57]
	v_mfma_f32_16x16x32_bf16 v[46:49], v[180:183], v[188:191], v[46:49]
	v_mfma_f32_16x16x32_bf16 v[38:41], v[172:175], v[210:213], v[38:41]
	v_mfma_f32_16x16x32_bf16 v[30:33], v[180:183], v[210:213], v[30:33]
	v_mfma_f32_16x16x32_bf16 v[22:25], v[172:175], v[218:221], v[22:25]
	v_mfma_f32_16x16x32_bf16 v[14:17], v[180:183], v[218:221], v[14:17]
	v_mfma_f32_16x16x32_bf16 v[6:9], v[172:175], v[226:229], v[6:9]
	v_mfma_f32_16x16x32_bf16 v[2:5], v[180:183], v[226:229], v[2:5]
	s_barrier
; #define PG8_STAGE(bufoff, gbase, voff) do { _Pragma("unroll") for (int _i = 0; _i < 2; ++_i) \
;         __builtin_amdgcn_global_load_lds((const unsigned*)((const char*)(gbase) + (voff)[_i]), (LAS unsigned*)(lds + (bufoff) + ldsw + _i * 8192), 16, 0, 0); } while (0)
; #define PG8_LDA(dst, b, h) do { _Pragma("unroll") for (int m = 0; m < 4; ++m) _Pragma("unroll") for (int k = 0; k < 2; ++k) dst[m][k] = *(const LAS bf16x8*)(lds + PG8_SA(b, h) + aoff + m * 2048 + k * 1024); } while (0)
; #define PG8_LDB(dst, b, h) do { _Pragma("unroll") for (int n = 0; n < 2; ++n) _Pragma("unroll") for (int k = 0; k < 2; ++k) dst[n][k] = *(const LAS bf16x8*)(lds + PG8_SB(b, h) + boff + n * 2048 + k * 1024); } while (0)
; #define PG8_MMA(ai, bj, At, Bt) do { __builtin_amdgcn_s_setprio(1); _Pragma("unroll") for (int m = 0; m < 4; ++m) _Pragma("unroll") for (int n = 0; n < 2; ++n) _Pragma("unroll") for (int k = 0; k < 2; ++k) \
;         acc[ai][bj][m][n] = __builtin_amdgcn_mfma_f32_16x16x32_bf16(Bt[n][k], At[m][k], acc[ai][bj][m][n], 0, 0, 0); __builtin_amdgcn_s_setprio(0); } while (0)
; #define PG8_WAIT_V(n) asm volatile("s_waitcnt vmcnt(" #n ")" ::: "memory")
; #define PG8_WAIT_L(n) asm volatile("s_waitcnt lgkmcnt(" #n ")" ::: "memory")
; #define PG8_BAR __builtin_amdgcn_s_barrier()
; #define PG8_SCHED __builtin_amdgcn_sched_barrier(0)
; template <class Epi, class Sched = StaticOrder, bool ALIGN_EPI = true>
; __device__ __forceinline__ void gemm_phase(LAS unsigned char* lds, const Gemm g, const Sched& S, const Epi& E) {
;     ...
;             PG8_LDB(B0, 1, 0); PG8_LDB(B1, 1, 1); PG8_SCHED; PG8_LDA(At, 1, 0); PG8_STAGE(PG8_SA(0, 1), a2 + hstep, voffA);
;             PG8_WAIT_V(8); PG8_WAIT_L(0); PG8_BAR; PG8_MMA(0, 0, At, B0); PG8_MMA(0, 1, At, B1); PG8_BAR; PG8_SCHED;
;             PG8_LDA(At, 1, 1); PG8_STAGE(PG8_SB(1, 0), b3, voffB); PG8_STAGE(PG8_SB(1, 1), b3 + hstep, voffB); PG8_STAGE(PG8_SA(1, 0), a3, voffA);
;             PG8_WAIT_V(8); PG8_WAIT_L(0); PG8_BAR; PG8_MMA(1, 0, At, B0); PG8_MMA(1, 1, At, B1); PG8_BAR; PG8_SCHED;
	s_add_i32 s33, 0, 0x18000
	s_add_i32 s44, 0, 0x1c000
	v_add_u32_e32 v160, s33, v135
	v_add_u32_e32 v171, s44, v135
	ds_read_b128 v[140:143], v160
	ds_read_b128 v[144:147], v160 offset:1024
	ds_read_b128 v[148:151], v160 offset:2048
	ds_read_b128 v[160:163], v160 offset:3072
	ds_read_b128 v[164:167], v171
	ds_read_b128 v[172:175], v171 offset:1024
	ds_read_b128 v[176:179], v171 offset:2048
	ds_read_b128 v[180:183], v171 offset:3072
	s_add_u32 s16, s30, 0x160000
	s_addc_u32 s17, s31, 0
	s_mov_b32 m0, s8
	v_lshl_add_u64 v[232:233], s[16:17], 0, v[132:133]
	ds_read_b128 v[184:187], v170 offset:32768
	ds_read_b128 v[188:191], v170 offset:33792
	ds_read_b128 v[192:195], v170 offset:34816
	ds_read_b128 v[210:213], v170 offset:35840
	ds_read_b128 v[214:217], v170 offset:36864
	ds_read_b128 v[218:221], v170 offset:37888
	ds_read_b128 v[222:225], v170 offset:38912
	ds_read_b128 v[226:229], v170 offset:39936
	global_load_lds_dwordx4 v[232:233], off
	s_mov_b32 m0, s9
	v_lshl_add_u64 v[232:233], s[16:17], 0, v[130:131]
	global_load_lds_dwordx4 v[232:233], off
	s_waitcnt vmcnt(8)
	s_waitcnt lgkmcnt(0)
	s_barrier
	v_mfma_f32_16x16x32_bf16 v[126:129], v[140:143], v[184:187], v[126:129]
	v_mfma_f32_16x16x32_bf16 v[122:125], v[148:151], v[184:187], v[122:125]
	v_mfma_f32_16x16x32_bf16 v[118:121], v[140:143], v[192:195], v[118:121]
	v_mfma_f32_16x16x32_bf16 v[106:109], v[148:151], v[192:195], v[106:109]
	v_mfma_f32_16x16x32_bf16 v[98:101], v[140:143], v[214:217], v[98:101]
	v_mfma_f32_16x16x32_bf16 v[90:93], v[148:151], v[214:217], v[90:93]
	v_mfma_f32_16x16x32_bf16 v[82:85], v[140:143], v[222:225], v[82:85]
	v_mfma_f32_16x16x32_bf16 v[74:77], v[148:151], v[222:225], v[74:77]
	v_mfma_f32_16x16x32_bf16 v[126:129], v[144:147], v[188:191], v[126:129]
	v_mfma_f32_16x16x32_bf16 v[122:125], v[160:163], v[188:191], v[122:125]
	v_mfma_f32_16x16x32_bf16 v[118:121], v[144:147], v[210:213], v[118:121]
	v_mfma_f32_16x16x32_bf16 v[106:109], v[160:163], v[210:213], v[106:109]
	v_mfma_f32_16x16x32_bf16 v[98:101], v[144:147], v[218:221], v[98:101]
	v_mfma_f32_16x16x32_bf16 v[90:93], v[160:163], v[218:221], v[90:93]
	v_mfma_f32_16x16x32_bf16 v[82:85], v[144:147], v[226:229], v[82:85]
	v_mfma_f32_16x16x32_bf16 v[74:77], v[160:163], v[226:229], v[74:77]
	v_mfma_f32_16x16x32_bf16 v[114:117], v[164:167], v[184:187], v[114:117]
	v_mfma_f32_16x16x32_bf16 v[110:113], v[176:179], v[184:187], v[110:113]
	v_mfma_f32_16x16x32_bf16 v[102:105], v[164:167], v[192:195], v[102:105]
	v_mfma_f32_16x16x32_bf16 v[94:97], v[176:179], v[192:195], v[94:97]
	v_mfma_f32_16x16x32_bf16 v[86:89], v[164:167], v[214:217], v[86:89]
	v_mfma_f32_16x16x32_bf16 v[78:81], v[176:179], v[214:217], v[78:81]
	v_mfma_f32_16x16x32_bf16 v[70:73], v[164:167], v[222:225], v[70:73]
	v_mfma_f32_16x16x32_bf16 v[66:69], v[176:179], v[222:225], v[66:69]
	v_mfma_f32_16x16x32_bf16 v[114:117], v[172:175], v[188:191], v[114:117]
	v_mfma_f32_16x16x32_bf16 v[110:113], v[180:183], v[188:191], v[110:113]
	v_mfma_f32_16x16x32_bf16 v[102:105], v[172:175], v[210:213], v[102:105]
	v_mfma_f32_16x16x32_bf16 v[94:97], v[180:183], v[210:213], v[94:97]
	v_mfma_f32_16x16x32_bf16 v[86:89], v[172:175], v[218:221], v[86:89]
	v_mfma_f32_16x16x32_bf16 v[78:81], v[180:183], v[218:221], v[78:81]
	v_mfma_f32_16x16x32_bf16 v[70:73], v[172:175], v[226:229], v[70:73]
	v_mfma_f32_16x16x32_bf16 v[66:69], v[180:183], v[226:229], v[66:69]
	s_barrier
	s_add_i32 s16, s33, s4
	v_lshl_add_u64 v[152:153], v[152:153], 0, s[34:35]
	s_mov_b32 m0, s16
	ds_read_b128 v[184:187], v170 offset:49152
	ds_read_b128 v[188:191], v170 offset:50176
	ds_read_b128 v[192:195], v170 offset:51200
	ds_read_b128 v[210:213], v170 offset:52224
	ds_read_b128 v[214:217], v170 offset:53248
	ds_read_b128 v[218:221], v170 offset:54272
	ds_read_b128 v[222:225], v170 offset:55296
	ds_read_b128 v[226:229], v170 offset:56320
	global_load_lds_dwordx4 v[152:153], off
	s_add_i32 m0, s16, 0x2000
	s_add_u32 s0, s0, 0x160080
	v_lshl_add_u64 v[152:153], v[168:169], 0, s[34:35]
	s_addc_u32 s1, s1, 0
	s_add_i32 s16, s44, s4
	global_load_lds_dwordx4 v[152:153], off
	s_mov_b32 m0, s16
	v_lshl_add_u64 v[152:153], s[0:1], 0, v[132:133]
	global_load_lds_dwordx4 v[152:153], off
	s_add_i32 m0, s16, 0x2000
	v_lshl_add_u64 v[152:153], s[0:1], 0, v[130:131]
	global_load_lds_dwordx4 v[152:153], off
	s_mov_b32 m0, s10
	v_lshl_add_u64 v[152:153], v[196:197], 0, s[34:35]
	global_load_lds_dwordx4 v[152:153], off
	s_mov_b32 m0, s11
	v_lshl_add_u64 v[152:153], v[230:231], 0, s[34:35]
	global_load_lds_dwordx4 v[152:153], off
	s_waitcnt vmcnt(8)
	s_waitcnt lgkmcnt(0)
	s_barrier
	v_mfma_f32_16x16x32_bf16 v[62:65], v[140:143], v[184:187], v[62:65]
	v_mfma_f32_16x16x32_bf16 v[58:61], v[148:151], v[184:187], v[58:61]
	v_mfma_f32_16x16x32_bf16 v[50:53], v[140:143], v[192:195], v[50:53]
	v_mfma_f32_16x16x32_bf16 v[42:45], v[148:151], v[192:195], v[42:45]
	v_mfma_f32_16x16x32_bf16 v[34:37], v[140:143], v[214:217], v[34:37]
	v_mfma_f32_16x16x32_bf16 v[26:29], v[148:151], v[214:217], v[26:29]
	v_mfma_f32_16x16x32_bf16 v[18:21], v[140:143], v[222:225], v[18:21]
	v_mfma_f32_16x16x32_bf16 v[10:13], v[148:151], v[222:225], v[10:13]
	v_mfma_f32_16x16x32_bf16 v[62:65], v[144:147], v[188:191], v[62:65]
	v_mfma_f32_16x16x32_bf16 v[58:61], v[160:163], v[188:191], v[58:61]
	v_mfma_f32_16x16x32_bf16 v[50:53], v[144:147], v[210:213], v[50:53]
	v_mfma_f32_16x16x32_bf16 v[42:45], v[160:163], v[210:213], v[42:45]
	v_mfma_f32_16x16x32_bf16 v[34:37], v[144:147], v[218:221], v[34:37]
	v_mfma_f32_16x16x32_bf16 v[26:29], v[160:163], v[218:221], v[26:29]
	v_mfma_f32_16x16x32_bf16 v[18:21], v[144:147], v[226:229], v[18:21]
	v_mfma_f32_16x16x32_bf16 v[10:13], v[160:163], v[226:229], v[10:13]
	v_mfma_f32_16x16x32_bf16 v[54:57], v[164:167], v[184:187], v[54:57]
	v_mfma_f32_16x16x32_bf16 v[46:49], v[176:179], v[184:187], v[46:49]
	v_mfma_f32_16x16x32_bf16 v[38:41], v[164:167], v[192:195], v[38:41]
	v_mfma_f32_16x16x32_bf16 v[30:33], v[176:179], v[192:195], v[30:33]
	v_mfma_f32_16x16x32_bf16 v[22:25], v[164:167], v[214:217], v[22:25]
	v_mfma_f32_16x16x32_bf16 v[14:17], v[176:179], v[214:217], v[14:17]
	v_mfma_f32_16x16x32_bf16 v[6:9], v[164:167], v[222:225], v[6:9]
	v_mfma_f32_16x16x32_bf16 v[2:5], v[176:179], v[222:225], v[2:5]
	v_mfma_f32_16x16x32_bf16 v[54:57], v[172:175], v[188:191], v[54:57]
	v_mfma_f32_16x16x32_bf16 v[46:49], v[180:183], v[188:191], v[46:49]
	v_mfma_f32_16x16x32_bf16 v[38:41], v[172:175], v[210:213], v[38:41]
	v_mfma_f32_16x16x32_bf16 v[30:33], v[180:183], v[210:213], v[30:33]
	v_mfma_f32_16x16x32_bf16 v[22:25], v[172:175], v[218:221], v[22:25]
	v_mfma_f32_16x16x32_bf16 v[14:17], v[180:183], v[218:221], v[14:17]
	v_mfma_f32_16x16x32_bf16 v[6:9], v[172:175], v[226:229], v[6:9]
	v_mfma_f32_16x16x32_bf16 v[2:5], v[180:183], v[226:229], v[2:5]
	s_barrier
	s_add_i32 s82, s82, 2
	s_add_u32 s79, s79, 0x100
	s_addc_u32 s92, s92, 0
	s_cmpk_gt_u32 s82, 0x55
	s_mov_b64 s[44:45], s[46:47]
	s_cbranch_scc0 .LBB0_392

; #define PG8_STAGE(bufoff, gbase, voff) do { _Pragma("unroll") for (int _i = 0; _i < 2; ++_i) \
;         __builtin_amdgcn_global_load_lds((const unsigned*)((const char*)(gbase) + (voff)[_i]), (LAS unsigned*)(lds + (bufoff) + ldsw + _i * 8192), 16, 0, 0); } while (0)
; #define PG8_LDA(dst, b, h) do { _Pragma("unroll") for (int m = 0; m < 4; ++m) _Pragma("unroll") for (int k = 0; k < 2; ++k) dst[m][k] = *(const LAS bf16x8*)(lds + PG8_SA(b, h) + aoff + m * 2048 + k * 1024); } while (0)
; #define PG8_LDB(dst, b, h) do { _Pragma("unroll") for (int n = 0; n < 2; ++n) _Pragma("unroll") for (int k = 0; k < 2; ++k) dst[n][k] = *(const LAS bf16x8*)(lds + PG8_SB(b, h) + boff + n * 2048 + k * 1024); } while (0)
; #define PG8_MMA(ai, bj, At, Bt) do { __builtin_amdgcn_s_setprio(1); _Pragma("unroll") for (int m = 0; m < 4; ++m) _Pragma("unroll") for (int n = 0; n < 2; ++n) _Pragma("unroll") for (int k = 0; k < 2; ++k) \
;         acc[ai][bj][m][n] = __builtin_amdgcn_mfma_f32_16x16x32_bf16(Bt[n][k], At[m][k], acc[ai][bj][m][n], 0, 0, 0); __builtin_amdgcn_s_setprio(0); } while (0)
; #define PG8_WAIT_V(n) asm volatile("s_waitcnt vmcnt(" #n ")" ::: "memory")
; #define PG8_WAIT_L(n) asm volatile("s_waitcnt lgkmcnt(" #n ")" ::: "memory")
; #define PG8_BAR __builtin_amdgcn_s_barrier()
; #define PG8_SCHED __builtin_amdgcn_sched_barrier(0)
; template <class Epi, class Sched = StaticOrder, bool ALIGN_EPI = true>
; __device__ __forceinline__ void gemm_phase(LAS unsigned char* lds, const Gemm g, const Sched& S, const Epi& E) {
;     ...
;         for (int t = 0; t < nt; t += 2) {
;             const bool last = (t == nt - 2);
;             const char* a1 = cA + (size_t)(t + 1) * kstep;
;             const char* a2 = last ? nA : cA + (size_t)(t + 2) * kstep; const char* b2 = last ? nB : cB + (size_t)(t + 2) * kstep;
;             const char* a3 = a2 + kstep; const char* b3 = b2 + kstep;
;             PG8_LDB(B0, 0, 0); PG8_LDB(B1, 0, 1); PG8_SCHED; PG8_LDA(At, 0, 0); PG8_STAGE(PG8_SA(1, 1), a1 + hstep, voffA);
;             PG8_WAIT_V(8); PG8_WAIT_L(0); PG8_BAR; PG8_MMA(0, 0, At, B0); PG8_MMA(0, 1, At, B1); PG8_BAR; PG8_SCHED;
;             PG8_LDA(At, 0, 1); PG8_STAGE(PG8_SB(0, 0), b2, voffB); PG8_STAGE(PG8_SB(0, 1), b2 + hstep, voffB); PG8_STAGE(PG8_SA(0, 0), a2, voffA);
;             PG8_WAIT_V(8); PG8_WAIT_L(0); PG8_BAR; PG8_MMA(1, 0, At, B0); PG8_MMA(1, 1, At, B1); PG8_BAR; PG8_SCHED;
.Lmy_nb_467:
	s_add_u32 s16, s44, 0xfff80080
	s_addc_u32 s17, s45, -1
	s_add_i32 s83, 0, 0x10000
	s_cmp_eq_u32 s82, 28
	s_cselect_b32 s49, s10, s17
	s_cselect_b32 s48, s11, s16
	v_add_u32_e32 v142, s83, v144
	s_cselect_b32 s47, s21, vcc_hi
	s_cselect_b32 s46, s31, vcc_lo
	s_add_i32 s33, 0, 0x14000
	ds_read_b128 v[148:151], v142
	ds_read_b128 v[160:163], v142 offset:1024
	ds_read_b128 v[164:167], v142 offset:2048
	ds_read_b128 v[168:171], v142 offset:3072
	v_add_u32_e32 v142, s33, v144
	ds_read_b128 v[172:175], v142
	ds_read_b128 v[176:179], v142 offset:1024
	ds_read_b128 v[180:183], v142 offset:2048
	ds_read_b128 v[184:187], v142 offset:3072
	v_lshl_add_u64 v[142:143], s[44:45], 0, v[138:139]
	s_add_i32 m0, s23, 0xc000
	ds_read_b128 v[188:191], v146
	ds_read_b128 v[192:195], v146 offset:1024
	ds_read_b128 v[210:213], v146 offset:2048
	ds_read_b128 v[214:217], v146 offset:3072
	ds_read_b128 v[218:221], v146 offset:4096
	ds_read_b128 v[222:225], v146 offset:5120
	ds_read_b128 v[226:229], v146 offset:6144
	ds_read_b128 v[230:233], v146 offset:7168
	global_load_lds_dwordx4 v[142:143], off
	s_add_i32 m0, s23, 0xe000
	v_lshl_add_u64 v[142:143], s[44:45], 0, v[140:141]
	global_load_lds_dwordx4 v[142:143], off
	s_waitcnt vmcnt(8)
	s_waitcnt lgkmcnt(0)
	s_barrier
	v_mfma_f32_16x16x32_bf16 v[126:129], v[148:151], v[188:191], 0
	v_mfma_f32_16x16x32_bf16 v[118:121], v[164:167], v[188:191], 0
	v_mfma_f32_16x16x32_bf16 v[110:113], v[148:151], v[210:213], 0
	v_mfma_f32_16x16x32_bf16 v[102:105], v[164:167], v[210:213], 0
	v_mfma_f32_16x16x32_bf16 v[94:97], v[148:151], v[218:221], 0
	v_mfma_f32_16x16x32_bf16 v[86:89], v[164:167], v[218:221], 0
	v_mfma_f32_16x16x32_bf16 v[78:81], v[148:151], v[226:229], 0
	v_mfma_f32_16x16x32_bf16 v[70:73], v[164:167], v[226:229], 0
	v_mfma_f32_16x16x32_bf16 v[126:129], v[160:163], v[192:195], v[126:129]
	v_mfma_f32_16x16x32_bf16 v[118:121], v[168:171], v[192:195], v[118:121]
	v_mfma_f32_16x16x32_bf16 v[110:113], v[160:163], v[214:217], v[110:113]
	v_mfma_f32_16x16x32_bf16 v[102:105], v[168:171], v[214:217], v[102:105]
	v_mfma_f32_16x16x32_bf16 v[94:97], v[160:163], v[222:225], v[94:97]
	v_mfma_f32_16x16x32_bf16 v[86:89], v[168:171], v[222:225], v[86:89]
	v_mfma_f32_16x16x32_bf16 v[78:81], v[160:163], v[230:233], v[78:81]
	v_mfma_f32_16x16x32_bf16 v[70:73], v[168:171], v[230:233], v[70:73]
	v_mfma_f32_16x16x32_bf16 v[122:125], v[172:175], v[188:191], 0
	v_mfma_f32_16x16x32_bf16 v[114:117], v[180:183], v[188:191], 0
	v_mfma_f32_16x16x32_bf16 v[106:109], v[172:175], v[210:213], 0
	v_mfma_f32_16x16x32_bf16 v[98:101], v[180:183], v[210:213], 0
	v_mfma_f32_16x16x32_bf16 v[90:93], v[172:175], v[218:221], 0
	v_mfma_f32_16x16x32_bf16 v[82:85], v[180:183], v[218:221], 0
	v_mfma_f32_16x16x32_bf16 v[74:77], v[172:175], v[226:229], 0
	v_mfma_f32_16x16x32_bf16 v[66:69], v[180:183], v[226:229], 0
	v_mfma_f32_16x16x32_bf16 v[122:125], v[176:179], v[192:195], v[122:125]
	v_mfma_f32_16x16x32_bf16 v[114:117], v[184:187], v[192:195], v[114:117]
	v_mfma_f32_16x16x32_bf16 v[106:109], v[176:179], v[214:217], v[106:109]
	v_mfma_f32_16x16x32_bf16 v[98:101], v[184:187], v[214:217], v[98:101]
	v_mfma_f32_16x16x32_bf16 v[90:93], v[176:179], v[222:225], v[90:93]
	v_mfma_f32_16x16x32_bf16 v[82:85], v[184:187], v[222:225], v[82:85]
	v_mfma_f32_16x16x32_bf16 v[74:77], v[176:179], v[230:233], v[74:77]
	v_mfma_f32_16x16x32_bf16 v[66:69], v[184:187], v[230:233], v[66:69]
	s_barrier
	s_add_i32 s16, s83, s92
	v_lshl_add_u64 v[142:143], s[46:47], 0, v[134:135]
	s_mov_b32 m0, s16
	ds_read_b128 v[188:191], v146 offset:16384
	ds_read_b128 v[192:195], v146 offset:17408
	ds_read_b128 v[210:213], v146 offset:18432
	ds_read_b128 v[214:217], v146 offset:19456
	ds_read_b128 v[218:221], v146 offset:20480
	ds_read_b128 v[222:225], v146 offset:21504
	ds_read_b128 v[226:229], v146 offset:22528
	ds_read_b128 v[230:233], v146 offset:23552
	global_load_lds_dwordx4 v[142:143], off
	s_add_i32 m0, s16, 0x2000
	s_add_u32 s16, s46, 0x80000
	v_lshl_add_u64 v[152:153], s[46:47], 0, v[130:131]
	s_addc_u32 s17, s47, 0
	s_add_i32 s33, s33, s92
	global_load_lds_dwordx4 v[152:153], off
	v_lshl_add_u64 v[196:197], s[16:17], 0, v[134:135]
	s_mov_b32 m0, s33
	v_lshl_add_u64 v[234:235], s[48:49], 0, v[132:133]
	global_load_lds_dwordx4 v[196:197], off
	s_add_i32 m0, s33, 0x2000
	v_lshl_add_u64 v[196:197], s[16:17], 0, v[130:131]
	global_load_lds_dwordx4 v[196:197], off
	s_mov_b32 m0, s23
	v_lshl_add_u64 v[196:197], s[48:49], 0, v[136:137]
	global_load_lds_dwordx4 v[196:197], off
	s_mov_b32 m0, s4
	s_nop 0
	global_load_lds_dwordx4 v[234:235], off
	s_waitcnt vmcnt(8)
	s_waitcnt lgkmcnt(0)
	s_barrier
; #define PG8_STAGE(bufoff, gbase, voff) do { _Pragma("unroll") for (int _i = 0; _i < 2; ++_i) \
;         __builtin_amdgcn_global_load_lds((const unsigned*)((const char*)(gbase) + (voff)[_i]), (LAS unsigned*)(lds + (bufoff) + ldsw + _i * 8192), 16, 0, 0); } while (0)
; #define PG8_LDA(dst, b, h) do { _Pragma("unroll") for (int m = 0; m < 4; ++m) _Pragma("unroll") for (int k = 0; k < 2; ++k) dst[m][k] = *(const LAS bf16x8*)(lds + PG8_SA(b, h) + aoff + m * 2048 + k * 1024); } while (0)
; #define PG8_LDB(dst, b, h) do { _Pragma("unroll") for (int n = 0; n < 2; ++n) _Pragma("unroll") for (int k = 0; k < 2; ++k) dst[n][k] = *(const LAS bf16x8*)(lds + PG8_SB(b, h) + boff + n * 2048 + k * 1024); } while (0)
; #define PG8_MMA(ai, bj, At, Bt) do { __builtin_amdgcn_s_setprio(1); _Pragma("unroll") for (int m = 0; m < 4; ++m) _Pragma("unroll") for (int n = 0; n < 2; ++n) _Pragma("unroll") for (int k = 0; k < 2; ++k) \
;         acc[ai][bj][m][n] = __builtin_amdgcn_mfma_f32_16x16x32_bf16(Bt[n][k], At[m][k], acc[ai][bj][m][n], 0, 0, 0); __builtin_amdgcn_s_setprio(0); } while (0)
; #define PG8_WAIT_V(n) asm volatile("s_waitcnt vmcnt(" #n ")" ::: "memory")
; #define PG8_WAIT_L(n) asm volatile("s_waitcnt lgkmcnt(" #n ")" ::: "memory")
; #define PG8_BAR __builtin_amdgcn_s_barrier()
; #define PG8_SCHED __builtin_amdgcn_sched_barrier(0)
; template <class Epi, class Sched = StaticOrder, bool ALIGN_EPI = true>
; __device__ __forceinline__ void gemm_phase(LAS unsigned char* lds, const Gemm g, const Sched& S, const Epi& E) {
;     ...
;             PG8_WAIT_V(8); PG8_WAIT_L(0); PG8_BAR; PG8_MMA(1, 0, At, B0); PG8_MMA(1, 1, At, B1); PG8_BAR; PG8_SCHED;
;             PG8_LDB(B0, 1, 0); PG8_LDB(B1, 1, 1); PG8_SCHED; PG8_LDA(At, 1, 0); PG8_STAGE(PG8_SA(0, 1), a2 + hstep, voffA);
;             PG8_WAIT_V(8); PG8_WAIT_L(0); PG8_BAR; PG8_MMA(0, 0, At, B0); PG8_MMA(0, 1, At, B1); PG8_BAR; PG8_SCHED;
	v_mfma_f32_16x16x32_bf16 v[62:65], v[148:151], v[188:191], 0
	v_mfma_f32_16x16x32_bf16 v[54:57], v[164:167], v[188:191], 0
	v_mfma_f32_16x16x32_bf16 v[46:49], v[148:151], v[210:213], 0
	v_mfma_f32_16x16x32_bf16 v[38:41], v[164:167], v[210:213], 0
	v_mfma_f32_16x16x32_bf16 v[30:33], v[148:151], v[218:221], 0
	v_mfma_f32_16x16x32_bf16 v[22:25], v[164:167], v[218:221], 0
	v_mfma_f32_16x16x32_bf16 v[14:17], v[148:151], v[226:229], 0
	v_mfma_f32_16x16x32_bf16 v[6:9], v[164:167], v[226:229], 0
	v_mfma_f32_16x16x32_bf16 v[62:65], v[160:163], v[192:195], v[62:65]
	v_mfma_f32_16x16x32_bf16 v[54:57], v[168:171], v[192:195], v[54:57]
	v_mfma_f32_16x16x32_bf16 v[46:49], v[160:163], v[214:217], v[46:49]
	v_mfma_f32_16x16x32_bf16 v[38:41], v[168:171], v[214:217], v[38:41]
	v_mfma_f32_16x16x32_bf16 v[30:33], v[160:163], v[222:225], v[30:33]
	v_mfma_f32_16x16x32_bf16 v[22:25], v[168:171], v[222:225], v[22:25]
	v_mfma_f32_16x16x32_bf16 v[14:17], v[160:163], v[230:233], v[14:17]
	v_mfma_f32_16x16x32_bf16 v[6:9], v[168:171], v[230:233], v[6:9]
	v_mfma_f32_16x16x32_bf16 v[58:61], v[172:175], v[188:191], 0
	v_mfma_f32_16x16x32_bf16 v[50:53], v[180:183], v[188:191], 0
	v_mfma_f32_16x16x32_bf16 v[42:45], v[172:175], v[210:213], 0
	v_mfma_f32_16x16x32_bf16 v[34:37], v[180:183], v[210:213], 0
	v_mfma_f32_16x16x32_bf16 v[26:29], v[172:175], v[218:221], 0
	v_mfma_f32_16x16x32_bf16 v[18:21], v[180:183], v[218:221], 0
	v_mfma_f32_16x16x32_bf16 v[10:13], v[172:175], v[226:229], 0
	v_mfma_f32_16x16x32_bf16 v[2:5], v[180:183], v[226:229], 0
	v_mfma_f32_16x16x32_bf16 v[58:61], v[176:179], v[192:195], v[58:61]
	v_mfma_f32_16x16x32_bf16 v[50:53], v[184:187], v[192:195], v[50:53]
	v_mfma_f32_16x16x32_bf16 v[42:45], v[176:179], v[214:217], v[42:45]
	v_mfma_f32_16x16x32_bf16 v[34:37], v[184:187], v[214:217], v[34:37]
	v_mfma_f32_16x16x32_bf16 v[26:29], v[176:179], v[222:225], v[26:29]
	v_mfma_f32_16x16x32_bf16 v[18:21], v[184:187], v[222:225], v[18:21]
	v_mfma_f32_16x16x32_bf16 v[10:13], v[176:179], v[230:233], v[10:13]
	v_mfma_f32_16x16x32_bf16 v[2:5], v[184:187], v[230:233], v[2:5]
	s_barrier
	s_add_i32 s33, 0, 0x18000
	v_add_u32_e32 v147, s33, v144
	s_add_i32 s83, 0, 0x1c000
	ds_read_b128 v[148:151], v147
	ds_read_b128 v[160:163], v147 offset:1024
	ds_read_b128 v[164:167], v147 offset:2048
	ds_read_b128 v[168:171], v147 offset:3072
	v_add_u32_e32 v147, s83, v144
	ds_read_b128 v[172:175], v147
	ds_read_b128 v[176:179], v147 offset:1024
	ds_read_b128 v[180:183], v147 offset:2048
	ds_read_b128 v[184:187], v147 offset:3072
	s_add_u32 s16, s48, 0x80000
	s_addc_u32 s17, s49, 0
	s_mov_b32 m0, s5
	v_lshl_add_u64 v[236:237], s[16:17], 0, v[136:137]
	ds_read_b128 v[188:191], v146 offset:32768
	ds_read_b128 v[192:195], v146 offset:33792
	ds_read_b128 v[210:213], v146 offset:34816
	ds_read_b128 v[214:217], v146 offset:35840
	ds_read_b128 v[218:221], v146 offset:36864
	ds_read_b128 v[222:225], v146 offset:37888
	ds_read_b128 v[226:229], v146 offset:38912
	ds_read_b128 v[230:233], v146 offset:39936
	global_load_lds_dwordx4 v[236:237], off
	s_mov_b32 m0, s6
	v_lshl_add_u64 v[236:237], s[16:17], 0, v[132:133]
	global_load_lds_dwordx4 v[236:237], off
	s_waitcnt vmcnt(8)
	s_waitcnt lgkmcnt(0)
	s_barrier
	v_mfma_f32_16x16x32_bf16 v[126:129], v[148:151], v[188:191], v[126:129]
	v_mfma_f32_16x16x32_bf16 v[118:121], v[164:167], v[188:191], v[118:121]
	v_mfma_f32_16x16x32_bf16 v[110:113], v[148:151], v[210:213], v[110:113]
	v_mfma_f32_16x16x32_bf16 v[102:105], v[164:167], v[210:213], v[102:105]
	v_mfma_f32_16x16x32_bf16 v[94:97], v[148:151], v[218:221], v[94:97]
	v_mfma_f32_16x16x32_bf16 v[86:89], v[164:167], v[218:221], v[86:89]
	v_mfma_f32_16x16x32_bf16 v[78:81], v[148:151], v[226:229], v[78:81]
	v_mfma_f32_16x16x32_bf16 v[70:73], v[164:167], v[226:229], v[70:73]
	v_mfma_f32_16x16x32_bf16 v[126:129], v[160:163], v[192:195], v[126:129]
	v_mfma_f32_16x16x32_bf16 v[118:121], v[168:171], v[192:195], v[118:121]
	v_mfma_f32_16x16x32_bf16 v[110:113], v[160:163], v[214:217], v[110:113]
	v_mfma_f32_16x16x32_bf16 v[102:105], v[168:171], v[214:217], v[102:105]
	v_mfma_f32_16x16x32_bf16 v[94:97], v[160:163], v[222:225], v[94:97]
	v_mfma_f32_16x16x32_bf16 v[86:89], v[168:171], v[222:225], v[86:89]
	v_mfma_f32_16x16x32_bf16 v[78:81], v[160:163], v[230:233], v[78:81]
	v_mfma_f32_16x16x32_bf16 v[70:73], v[168:171], v[230:233], v[70:73]
	v_mfma_f32_16x16x32_bf16 v[122:125], v[172:175], v[188:191], v[122:125]
	v_mfma_f32_16x16x32_bf16 v[114:117], v[180:183], v[188:191], v[114:117]
	v_mfma_f32_16x16x32_bf16 v[106:109], v[172:175], v[210:213], v[106:109]
	v_mfma_f32_16x16x32_bf16 v[98:101], v[180:183], v[210:213], v[98:101]
	v_mfma_f32_16x16x32_bf16 v[90:93], v[172:175], v[218:221], v[90:93]
	v_mfma_f32_16x16x32_bf16 v[82:85], v[180:183], v[218:221], v[82:85]
	v_mfma_f32_16x16x32_bf16 v[74:77], v[172:175], v[226:229], v[74:77]
	v_mfma_f32_16x16x32_bf16 v[66:69], v[180:183], v[226:229], v[66:69]
	v_mfma_f32_16x16x32_bf16 v[122:125], v[176:179], v[192:195], v[122:125]
	v_mfma_f32_16x16x32_bf16 v[114:117], v[184:187], v[192:195], v[114:117]
	v_mfma_f32_16x16x32_bf16 v[106:109], v[176:179], v[214:217], v[106:109]
	v_mfma_f32_16x16x32_bf16 v[98:101], v[184:187], v[214:217], v[98:101]
	v_mfma_f32_16x16x32_bf16 v[90:93], v[176:179], v[222:225], v[90:93]
	v_mfma_f32_16x16x32_bf16 v[82:85], v[184:187], v[222:225], v[82:85]
	v_mfma_f32_16x16x32_bf16 v[74:77], v[176:179], v[230:233], v[74:77]
	v_mfma_f32_16x16x32_bf16 v[66:69], v[184:187], v[230:233], v[66:69]
	s_barrier
; #define PG8_STAGE(bufoff, gbase, voff) do { _Pragma("unroll") for (int _i = 0; _i < 2; ++_i) \
;         __builtin_amdgcn_global_load_lds((const unsigned*)((const char*)(gbase) + (voff)[_i]), (LAS unsigned*)(lds + (bufoff) + ldsw + _i * 8192), 16, 0, 0); } while (0)
; #define PG8_LDA(dst, b, h) do { _Pragma("unroll") for (int m = 0; m < 4; ++m) _Pragma("unroll") for (int k = 0; k < 2; ++k) dst[m][k] = *(const LAS bf16x8*)(lds + PG8_SA(b, h) + aoff + m * 2048 + k * 1024); } while (0)
; #define PG8_LDB(dst, b, h) do { _Pragma("unroll") for (int n = 0; n < 2; ++n) _Pragma("unroll") for (int k = 0; k < 2; ++k) dst[n][k] = *(const LAS bf16x8*)(lds + PG8_SB(b, h) + boff + n * 2048 + k * 1024); } while (0)
; #define PG8_MMA(ai, bj, At, Bt) do { __builtin_amdgcn_s_setprio(1); _Pragma("unroll") for (int m = 0; m < 4; ++m) _Pragma("unroll") for (int n = 0; n < 2; ++n) _Pragma("unroll") for (int k = 0; k < 2; ++k) \
;         acc[ai][bj][m][n] = __builtin_amdgcn_mfma_f32_16x16x32_bf16(Bt[n][k], At[m][k], acc[ai][bj][m][n], 0, 0, 0); __builtin_amdgcn_s_setprio(0); } while (0)
; #define PG8_WAIT_V(n) asm volatile("s_waitcnt vmcnt(" #n ")" ::: "memory")
; #define PG8_WAIT_L(n) asm volatile("s_waitcnt lgkmcnt(" #n ")" ::: "memory")
; #define PG8_BAR __builtin_amdgcn_s_barrier()
; #define PG8_SCHED __builtin_amdgcn_sched_barrier(0)
; template <class Epi, class Sched = StaticOrder, bool ALIGN_EPI = true>
; __device__ __forceinline__ void gemm_phase(LAS unsigned char* lds, const Gemm g, const Sched& S, const Epi& E) {
;     ...
;         for (int t = 0; t < nt; t += 2) {
;             const bool last = (t == nt - 2);
;             const char* a1 = cA + (size_t)(t + 1) * kstep;
;             const char* a2 = last ? nA : cA + (size_t)(t + 2) * kstep; const char* b2 = last ? nB : cB + (size_t)(t + 2) * kstep;
;             const char* a3 = a2 + kstep; const char* b3 = b2 + kstep;
;             PG8_LDB(B0, 0, 0); PG8_LDB(B1, 0, 1); PG8_SCHED; PG8_LDA(At, 0, 0); PG8_STAGE(PG8_SA(1, 1), a1 + hstep, voffA);
;     ...
;             PG8_LDA(At, 1, 1); PG8_STAGE(PG8_SB(1, 0), b3, voffB); PG8_STAGE(PG8_SB(1, 1), b3 + hstep, voffB); PG8_STAGE(PG8_SA(1, 0), a3, voffA);
;             PG8_WAIT_V(8); PG8_WAIT_L(0); PG8_BAR; PG8_MMA(1, 0, At, B0); PG8_MMA(1, 1, At, B1); PG8_BAR; PG8_SCHED;
	s_add_i32 s16, s33, s92
	v_lshl_add_u64 v[142:143], v[142:143], 0, s[34:35]
	s_mov_b32 m0, s16
	ds_read_b128 v[188:191], v146 offset:49152
	ds_read_b128 v[192:195], v146 offset:50176
	ds_read_b128 v[210:213], v146 offset:51200
	ds_read_b128 v[214:217], v146 offset:52224
	ds_read_b128 v[218:221], v146 offset:53248
	ds_read_b128 v[222:225], v146 offset:54272
	ds_read_b128 v[226:229], v146 offset:55296
	ds_read_b128 v[230:233], v146 offset:56320
	global_load_lds_dwordx4 v[142:143], off
	s_add_i32 m0, s16, 0x2000
	s_add_u32 s16, s46, 0x80080
	v_lshl_add_u64 v[142:143], v[152:153], 0, s[34:35]
	s_addc_u32 s17, s47, 0
	s_add_i32 s33, s83, s92
	global_load_lds_dwordx4 v[142:143], off
	s_mov_b32 m0, s33
	v_lshl_add_u64 v[142:143], s[16:17], 0, v[134:135]
	global_load_lds_dwordx4 v[142:143], off
	s_add_i32 m0, s33, 0x2000
	v_lshl_add_u64 v[142:143], s[16:17], 0, v[130:131]
	global_load_lds_dwordx4 v[142:143], off
	s_mov_b32 m0, s7
	v_lshl_add_u64 v[142:143], v[196:197], 0, s[34:35]
	global_load_lds_dwordx4 v[142:143], off
	s_mov_b32 m0, s8
	v_lshl_add_u64 v[142:143], v[234:235], 0, s[34:35]
	global_load_lds_dwordx4 v[142:143], off
	s_waitcnt vmcnt(8)
	s_waitcnt lgkmcnt(0)
	s_barrier
	v_mfma_f32_16x16x32_bf16 v[62:65], v[148:151], v[188:191], v[62:65]
	v_mfma_f32_16x16x32_bf16 v[54:57], v[164:167], v[188:191], v[54:57]
	v_mfma_f32_16x16x32_bf16 v[46:49], v[148:151], v[210:213], v[46:49]
	v_mfma_f32_16x16x32_bf16 v[38:41], v[164:167], v[210:213], v[38:41]
	v_mfma_f32_16x16x32_bf16 v[30:33], v[148:151], v[218:221], v[30:33]
	v_mfma_f32_16x16x32_bf16 v[22:25], v[164:167], v[218:221], v[22:25]
	v_mfma_f32_16x16x32_bf16 v[14:17], v[148:151], v[226:229], v[14:17]
	v_mfma_f32_16x16x32_bf16 v[6:9], v[164:167], v[226:229], v[6:9]
	v_mfma_f32_16x16x32_bf16 v[62:65], v[160:163], v[192:195], v[62:65]
	v_mfma_f32_16x16x32_bf16 v[54:57], v[168:171], v[192:195], v[54:57]
	v_mfma_f32_16x16x32_bf16 v[46:49], v[160:163], v[214:217], v[46:49]
	v_mfma_f32_16x16x32_bf16 v[38:41], v[168:171], v[214:217], v[38:41]
	v_mfma_f32_16x16x32_bf16 v[30:33], v[160:163], v[222:225], v[30:33]
	v_mfma_f32_16x16x32_bf16 v[22:25], v[168:171], v[222:225], v[22:25]
	v_mfma_f32_16x16x32_bf16 v[14:17], v[160:163], v[230:233], v[14:17]
	v_mfma_f32_16x16x32_bf16 v[6:9], v[168:171], v[230:233], v[6:9]
	v_mfma_f32_16x16x32_bf16 v[58:61], v[172:175], v[188:191], v[58:61]
	v_mfma_f32_16x16x32_bf16 v[50:53], v[180:183], v[188:191], v[50:53]
	v_mfma_f32_16x16x32_bf16 v[42:45], v[172:175], v[210:213], v[42:45]
	v_mfma_f32_16x16x32_bf16 v[34:37], v[180:183], v[210:213], v[34:37]
	v_mfma_f32_16x16x32_bf16 v[26:29], v[172:175], v[218:221], v[26:29]
	v_mfma_f32_16x16x32_bf16 v[18:21], v[180:183], v[218:221], v[18:21]
	v_mfma_f32_16x16x32_bf16 v[10:13], v[172:175], v[226:229], v[10:13]
	v_mfma_f32_16x16x32_bf16 v[2:5], v[180:183], v[226:229], v[2:5]
	v_mfma_f32_16x16x32_bf16 v[58:61], v[176:179], v[192:195], v[58:61]
	v_mfma_f32_16x16x32_bf16 v[50:53], v[184:187], v[192:195], v[50:53]
	v_mfma_f32_16x16x32_bf16 v[42:45], v[176:179], v[214:217], v[42:45]
	v_mfma_f32_16x16x32_bf16 v[34:37], v[184:187], v[214:217], v[34:37]
	v_mfma_f32_16x16x32_bf16 v[26:29], v[176:179], v[222:225], v[26:29]
	v_mfma_f32_16x16x32_bf16 v[18:21], v[184:187], v[222:225], v[18:21]
	v_mfma_f32_16x16x32_bf16 v[10:13], v[176:179], v[230:233], v[10:13]
	v_mfma_f32_16x16x32_bf16 v[2:5], v[184:187], v[230:233], v[2:5]
	s_barrier
	s_add_i32 s82, s82, 2
	s_add_u32 s44, s44, 0x100
	s_addc_u32 s45, s45, 0
	s_add_u32 vcc_lo, vcc_lo, 0x100
	s_addc_u32 vcc_hi, vcc_hi, 0
	s_cmp_gt_u32 s82, 29
	s_cbranch_scc0 .LBB0_467
.LBB0_467:
	s_add_u32 s16, s44, 0xfff80080
	s_addc_u32 s17, s45, -1
	s_add_i32 s83, 0, 0x10000
	s_cmp_eq_u32 s82, 28
	s_cselect_b32 s49, s10, s17
	s_cselect_b32 s48, s11, s16
	v_add_u32_e32 v142, s83, v144
	s_cselect_b32 s47, s21, vcc_hi
	s_cselect_b32 s46, s31, vcc_lo
	s_add_i32 s33, 0, 0x14000
	ds_read_b128 v[148:151], v142
	ds_read_b128 v[160:163], v142 offset:1024
	ds_read_b128 v[164:167], v142 offset:2048
	ds_read_b128 v[168:171], v142 offset:3072
	v_add_u32_e32 v142, s33, v144
	ds_read_b128 v[172:175], v142
	ds_read_b128 v[176:179], v142 offset:1024
	ds_read_b128 v[180:183], v142 offset:2048
	ds_read_b128 v[184:187], v142 offset:3072
	v_lshl_add_u64 v[142:143], s[44:45], 0, v[138:139]
	s_add_i32 m0, s23, 0xc000
	ds_read_b128 v[188:191], v146
	ds_read_b128 v[192:195], v146 offset:1024
	ds_read_b128 v[210:213], v146 offset:2048
	ds_read_b128 v[214:217], v146 offset:3072
	ds_read_b128 v[218:221], v146 offset:4096
	ds_read_b128 v[222:225], v146 offset:5120
	ds_read_b128 v[226:229], v146 offset:6144
	ds_read_b128 v[230:233], v146 offset:7168
	global_load_lds_dwordx4 v[142:143], off
	s_add_i32 m0, s23, 0xe000
	v_lshl_add_u64 v[142:143], s[44:45], 0, v[140:141]
	global_load_lds_dwordx4 v[142:143], off
	s_waitcnt vmcnt(8)
	s_waitcnt lgkmcnt(0)
	s_barrier
; #define PG8_STAGE(bufoff, gbase, voff) do { _Pragma("unroll") for (int _i = 0; _i < 2; ++_i) \
;         __builtin_amdgcn_global_load_lds((const unsigned*)((const char*)(gbase) + (voff)[_i]), (LAS unsigned*)(lds + (bufoff) + ldsw + _i * 8192), 16, 0, 0); } while (0)
; #define PG8_LDA(dst, b, h) do { _Pragma("unroll") for (int m = 0; m < 4; ++m) _Pragma("unroll") for (int k = 0; k < 2; ++k) dst[m][k] = *(const LAS bf16x8*)(lds + PG8_SA(b, h) + aoff + m * 2048 + k * 1024); } while (0)
; #define PG8_MMA(ai, bj, At, Bt) do { __builtin_amdgcn_s_setprio(1); _Pragma("unroll") for (int m = 0; m < 4; ++m) _Pragma("unroll") for (int n = 0; n < 2; ++n) _Pragma("unroll") for (int k = 0; k < 2; ++k) \
;         acc[ai][bj][m][n] = __builtin_amdgcn_mfma_f32_16x16x32_bf16(Bt[n][k], At[m][k], acc[ai][bj][m][n], 0, 0, 0); __builtin_amdgcn_s_setprio(0); } while (0)
; #define PG8_WAIT_V(n) asm volatile("s_waitcnt vmcnt(" #n ")" ::: "memory")
; #define PG8_WAIT_L(n) asm volatile("s_waitcnt lgkmcnt(" #n ")" ::: "memory")
; #define PG8_BAR __builtin_amdgcn_s_barrier()
; #define PG8_SCHED __builtin_amdgcn_sched_barrier(0)
; template <class Epi, class Sched = StaticOrder, bool ALIGN_EPI = true>
; __device__ __forceinline__ void gemm_phase(LAS unsigned char* lds, const Gemm g, const Sched& S, const Epi& E) {
;     ...
;             PG8_WAIT_V(8); PG8_WAIT_L(0); PG8_BAR; PG8_MMA(0, 0, At, B0); PG8_MMA(0, 1, At, B1); PG8_BAR; PG8_SCHED;
;             PG8_LDA(At, 0, 1); PG8_STAGE(PG8_SB(0, 0), b2, voffB); PG8_STAGE(PG8_SB(0, 1), b2 + hstep, voffB); PG8_STAGE(PG8_SA(0, 0), a2, voffA);
;             PG8_WAIT_V(8); PG8_WAIT_L(0); PG8_BAR; PG8_MMA(1, 0, At, B0); PG8_MMA(1, 1, At, B1); PG8_BAR; PG8_SCHED;
	v_mfma_f32_16x16x32_bf16 v[126:129], v[148:151], v[188:191], v[126:129]
	v_mfma_f32_16x16x32_bf16 v[118:121], v[164:167], v[188:191], v[118:121]
	v_mfma_f32_16x16x32_bf16 v[110:113], v[148:151], v[210:213], v[110:113]
	v_mfma_f32_16x16x32_bf16 v[102:105], v[164:167], v[210:213], v[102:105]
	v_mfma_f32_16x16x32_bf16 v[94:97], v[148:151], v[218:221], v[94:97]
	v_mfma_f32_16x16x32_bf16 v[86:89], v[164:167], v[218:221], v[86:89]
	v_mfma_f32_16x16x32_bf16 v[78:81], v[148:151], v[226:229], v[78:81]
	v_mfma_f32_16x16x32_bf16 v[70:73], v[164:167], v[226:229], v[70:73]
	v_mfma_f32_16x16x32_bf16 v[126:129], v[160:163], v[192:195], v[126:129]
	v_mfma_f32_16x16x32_bf16 v[118:121], v[168:171], v[192:195], v[118:121]
	v_mfma_f32_16x16x32_bf16 v[110:113], v[160:163], v[214:217], v[110:113]
	v_mfma_f32_16x16x32_bf16 v[102:105], v[168:171], v[214:217], v[102:105]
	v_mfma_f32_16x16x32_bf16 v[94:97], v[160:163], v[222:225], v[94:97]
	v_mfma_f32_16x16x32_bf16 v[86:89], v[168:171], v[222:225], v[86:89]
	v_mfma_f32_16x16x32_bf16 v[78:81], v[160:163], v[230:233], v[78:81]
	v_mfma_f32_16x16x32_bf16 v[70:73], v[168:171], v[230:233], v[70:73]
	v_mfma_f32_16x16x32_bf16 v[122:125], v[172:175], v[188:191], v[122:125]
	v_mfma_f32_16x16x32_bf16 v[114:117], v[180:183], v[188:191], v[114:117]
	v_mfma_f32_16x16x32_bf16 v[106:109], v[172:175], v[210:213], v[106:109]
	v_mfma_f32_16x16x32_bf16 v[98:101], v[180:183], v[210:213], v[98:101]
	v_mfma_f32_16x16x32_bf16 v[90:93], v[172:175], v[218:221], v[90:93]
	v_mfma_f32_16x16x32_bf16 v[82:85], v[180:183], v[218:221], v[82:85]
	v_mfma_f32_16x16x32_bf16 v[74:77], v[172:175], v[226:229], v[74:77]
	v_mfma_f32_16x16x32_bf16 v[66:69], v[180:183], v[226:229], v[66:69]
	v_mfma_f32_16x16x32_bf16 v[122:125], v[176:179], v[192:195], v[122:125]
	v_mfma_f32_16x16x32_bf16 v[114:117], v[184:187], v[192:195], v[114:117]
	v_mfma_f32_16x16x32_bf16 v[106:109], v[176:179], v[214:217], v[106:109]
	v_mfma_f32_16x16x32_bf16 v[98:101], v[184:187], v[214:217], v[98:101]
	v_mfma_f32_16x16x32_bf16 v[90:93], v[176:179], v[222:225], v[90:93]
	v_mfma_f32_16x16x32_bf16 v[82:85], v[184:187], v[222:225], v[82:85]
	v_mfma_f32_16x16x32_bf16 v[74:77], v[176:179], v[230:233], v[74:77]
	v_mfma_f32_16x16x32_bf16 v[66:69], v[184:187], v[230:233], v[66:69]
	s_barrier
	s_add_i32 s16, s83, s92
	v_lshl_add_u64 v[142:143], s[46:47], 0, v[134:135]
	s_mov_b32 m0, s16
	ds_read_b128 v[188:191], v146 offset:16384
	ds_read_b128 v[192:195], v146 offset:17408
	ds_read_b128 v[210:213], v146 offset:18432
	ds_read_b128 v[214:217], v146 offset:19456
	ds_read_b128 v[218:221], v146 offset:20480
	ds_read_b128 v[222:225], v146 offset:21504
	ds_read_b128 v[226:229], v146 offset:22528
	ds_read_b128 v[230:233], v146 offset:23552
	global_load_lds_dwordx4 v[142:143], off
	s_add_i32 m0, s16, 0x2000
	s_add_u32 s16, s46, 0x80000
	v_lshl_add_u64 v[152:153], s[46:47], 0, v[130:131]
	s_addc_u32 s17, s47, 0
	s_add_i32 s33, s33, s92
	global_load_lds_dwordx4 v[152:153], off
	v_lshl_add_u64 v[196:197], s[16:17], 0, v[134:135]
	s_mov_b32 m0, s33
	v_lshl_add_u64 v[234:235], s[48:49], 0, v[132:133]
	global_load_lds_dwordx4 v[196:197], off
	s_add_i32 m0, s33, 0x2000
	v_lshl_add_u64 v[196:197], s[16:17], 0, v[130:131]
	global_load_lds_dwordx4 v[196:197], off
	s_mov_b32 m0, s23
	v_lshl_add_u64 v[196:197], s[48:49], 0, v[136:137]
	global_load_lds_dwordx4 v[196:197], off
	s_mov_b32 m0, s4
	s_nop 0
	global_load_lds_dwordx4 v[234:235], off
	s_waitcnt vmcnt(8)
	s_waitcnt lgkmcnt(0)
	s_barrier
	v_mfma_f32_16x16x32_bf16 v[62:65], v[148:151], v[188:191], v[62:65]
	v_mfma_f32_16x16x32_bf16 v[54:57], v[164:167], v[188:191], v[54:57]
	v_mfma_f32_16x16x32_bf16 v[46:49], v[148:151], v[210:213], v[46:49]
	v_mfma_f32_16x16x32_bf16 v[38:41], v[164:167], v[210:213], v[38:41]
	v_mfma_f32_16x16x32_bf16 v[30:33], v[148:151], v[218:221], v[30:33]
	v_mfma_f32_16x16x32_bf16 v[22:25], v[164:167], v[218:221], v[22:25]
	v_mfma_f32_16x16x32_bf16 v[14:17], v[148:151], v[226:229], v[14:17]
	v_mfma_f32_16x16x32_bf16 v[6:9], v[164:167], v[226:229], v[6:9]
	v_mfma_f32_16x16x32_bf16 v[62:65], v[160:163], v[192:195], v[62:65]
	v_mfma_f32_16x16x32_bf16 v[54:57], v[168:171], v[192:195], v[54:57]
	v_mfma_f32_16x16x32_bf16 v[46:49], v[160:163], v[214:217], v[46:49]
	v_mfma_f32_16x16x32_bf16 v[38:41], v[168:171], v[214:217], v[38:41]
	v_mfma_f32_16x16x32_bf16 v[30:33], v[160:163], v[222:225], v[30:33]
	v_mfma_f32_16x16x32_bf16 v[22:25], v[168:171], v[222:225], v[22:25]
	v_mfma_f32_16x16x32_bf16 v[14:17], v[160:163], v[230:233], v[14:17]
	v_mfma_f32_16x16x32_bf16 v[6:9], v[168:171], v[230:233], v[6:9]
	v_mfma_f32_16x16x32_bf16 v[58:61], v[172:175], v[188:191], v[58:61]
	v_mfma_f32_16x16x32_bf16 v[50:53], v[180:183], v[188:191], v[50:53]
	v_mfma_f32_16x16x32_bf16 v[42:45], v[172:175], v[210:213], v[42:45]
	v_mfma_f32_16x16x32_bf16 v[34:37], v[180:183], v[210:213], v[34:37]
	v_mfma_f32_16x16x32_bf16 v[26:29], v[172:175], v[218:221], v[26:29]
	v_mfma_f32_16x16x32_bf16 v[18:21], v[180:183], v[218:221], v[18:21]
	v_mfma_f32_16x16x32_bf16 v[10:13], v[172:175], v[226:229], v[10:13]
	v_mfma_f32_16x16x32_bf16 v[2:5], v[180:183], v[226:229], v[2:5]
	v_mfma_f32_16x16x32_bf16 v[58:61], v[176:179], v[192:195], v[58:61]
	v_mfma_f32_16x16x32_bf16 v[50:53], v[184:187], v[192:195], v[50:53]
	v_mfma_f32_16x16x32_bf16 v[42:45], v[176:179], v[214:217], v[42:45]
	v_mfma_f32_16x16x32_bf16 v[34:37], v[184:187], v[214:217], v[34:37]
	v_mfma_f32_16x16x32_bf16 v[26:29], v[176:179], v[222:225], v[26:29]
	v_mfma_f32_16x16x32_bf16 v[18:21], v[184:187], v[222:225], v[18:21]
	v_mfma_f32_16x16x32_bf16 v[10:13], v[176:179], v[230:233], v[10:13]
	v_mfma_f32_16x16x32_bf16 v[2:5], v[184:187], v[230:233], v[2:5]
	s_barrier
; #define PG8_STAGE(bufoff, gbase, voff) do { _Pragma("unroll") for (int _i = 0; _i < 2; ++_i) \
;         __builtin_amdgcn_global_load_lds((const unsigned*)((const char*)(gbase) + (voff)[_i]), (LAS unsigned*)(lds + (bufoff) + ldsw + _i * 8192), 16, 0, 0); } while (0)
; #define PG8_LDA(dst, b, h) do { _Pragma("unroll") for (int m = 0; m < 4; ++m) _Pragma("unroll") for (int k = 0; k < 2; ++k) dst[m][k] = *(const LAS bf16x8*)(lds + PG8_SA(b, h) + aoff + m * 2048 + k * 1024); } while (0)
; #define PG8_LDB(dst, b, h) do { _Pragma("unroll") for (int n = 0; n < 2; ++n) _Pragma("unroll") for (int k = 0; k < 2; ++k) dst[n][k] = *(const LAS bf16x8*)(lds + PG8_SB(b, h) + boff + n * 2048 + k * 1024); } while (0)
; #define PG8_MMA(ai, bj, At, Bt) do { __builtin_amdgcn_s_setprio(1); _Pragma("unroll") for (int m = 0; m < 4; ++m) _Pragma("unroll") for (int n = 0; n < 2; ++n) _Pragma("unroll") for (int k = 0; k < 2; ++k) \
;         acc[ai][bj][m][n] = __builtin_amdgcn_mfma_f32_16x16x32_bf16(Bt[n][k], At[m][k], acc[ai][bj][m][n], 0, 0, 0); __builtin_amdgcn_s_setprio(0); } while (0)
; #define PG8_WAIT_V(n) asm volatile("s_waitcnt vmcnt(" #n ")" ::: "memory")
; #define PG8_WAIT_L(n) asm volatile("s_waitcnt lgkmcnt(" #n ")" ::: "memory")
; #define PG8_BAR __builtin_amdgcn_s_barrier()
; #define PG8_SCHED __builtin_amdgcn_sched_barrier(0)
; template <class Epi, class Sched = StaticOrder, bool ALIGN_EPI = true>
; __device__ __forceinline__ void gemm_phase(LAS unsigned char* lds, const Gemm g, const Sched& S, const Epi& E) {
;     ...
;             PG8_LDB(B0, 1, 0); PG8_LDB(B1, 1, 1); PG8_SCHED; PG8_LDA(At, 1, 0); PG8_STAGE(PG8_SA(0, 1), a2 + hstep, voffA);
;             PG8_WAIT_V(8); PG8_WAIT_L(0); PG8_BAR; PG8_MMA(0, 0, At, B0); PG8_MMA(0, 1, At, B1); PG8_BAR; PG8_SCHED;
;             PG8_LDA(At, 1, 1); PG8_STAGE(PG8_SB(1, 0), b3, voffB); PG8_STAGE(PG8_SB(1, 1), b3 + hstep, voffB); PG8_STAGE(PG8_SA(1, 0), a3, voffA);
;             PG8_WAIT_V(8); PG8_WAIT_L(0); PG8_BAR; PG8_MMA(1, 0, At, B0); PG8_MMA(1, 1, At, B1); PG8_BAR; PG8_SCHED;
	s_add_i32 s33, 0, 0x18000
	v_add_u32_e32 v147, s33, v144
	s_add_i32 s83, 0, 0x1c000
	ds_read_b128 v[148:151], v147
	ds_read_b128 v[160:163], v147 offset:1024
	ds_read_b128 v[164:167], v147 offset:2048
	ds_read_b128 v[168:171], v147 offset:3072
	v_add_u32_e32 v147, s83, v144
	ds_read_b128 v[172:175], v147
	ds_read_b128 v[176:179], v147 offset:1024
	ds_read_b128 v[180:183], v147 offset:2048
	ds_read_b128 v[184:187], v147 offset:3072
	s_add_u32 s16, s48, 0x80000
	s_addc_u32 s17, s49, 0
	s_mov_b32 m0, s5
	v_lshl_add_u64 v[236:237], s[16:17], 0, v[136:137]
	ds_read_b128 v[188:191], v146 offset:32768
	ds_read_b128 v[192:195], v146 offset:33792
	ds_read_b128 v[210:213], v146 offset:34816
	ds_read_b128 v[214:217], v146 offset:35840
	ds_read_b128 v[218:221], v146 offset:36864
	ds_read_b128 v[222:225], v146 offset:37888
	ds_read_b128 v[226:229], v146 offset:38912
	ds_read_b128 v[230:233], v146 offset:39936
	global_load_lds_dwordx4 v[236:237], off
	s_mov_b32 m0, s6
	v_lshl_add_u64 v[236:237], s[16:17], 0, v[132:133]
	global_load_lds_dwordx4 v[236:237], off
	s_waitcnt vmcnt(8)
	s_waitcnt lgkmcnt(0)
	s_barrier
	v_mfma_f32_16x16x32_bf16 v[126:129], v[148:151], v[188:191], v[126:129]
	v_mfma_f32_16x16x32_bf16 v[118:121], v[164:167], v[188:191], v[118:121]
	v_mfma_f32_16x16x32_bf16 v[110:113], v[148:151], v[210:213], v[110:113]
	v_mfma_f32_16x16x32_bf16 v[102:105], v[164:167], v[210:213], v[102:105]
	v_mfma_f32_16x16x32_bf16 v[94:97], v[148:151], v[218:221], v[94:97]
	v_mfma_f32_16x16x32_bf16 v[86:89], v[164:167], v[218:221], v[86:89]
	v_mfma_f32_16x16x32_bf16 v[78:81], v[148:151], v[226:229], v[78:81]
	v_mfma_f32_16x16x32_bf16 v[70:73], v[164:167], v[226:229], v[70:73]
	v_mfma_f32_16x16x32_bf16 v[126:129], v[160:163], v[192:195], v[126:129]
	v_mfma_f32_16x16x32_bf16 v[118:121], v[168:171], v[192:195], v[118:121]
	v_mfma_f32_16x16x32_bf16 v[110:113], v[160:163], v[214:217], v[110:113]
	v_mfma_f32_16x16x32_bf16 v[102:105], v[168:171], v[214:217], v[102:105]
	v_mfma_f32_16x16x32_bf16 v[94:97], v[160:163], v[222:225], v[94:97]
	v_mfma_f32_16x16x32_bf16 v[86:89], v[168:171], v[222:225], v[86:89]
	v_mfma_f32_16x16x32_bf16 v[78:81], v[160:163], v[230:233], v[78:81]
	v_mfma_f32_16x16x32_bf16 v[70:73], v[168:171], v[230:233], v[70:73]
	v_mfma_f32_16x16x32_bf16 v[122:125], v[172:175], v[188:191], v[122:125]
	v_mfma_f32_16x16x32_bf16 v[114:117], v[180:183], v[188:191], v[114:117]
	v_mfma_f32_16x16x32_bf16 v[106:109], v[172:175], v[210:213], v[106:109]
	v_mfma_f32_16x16x32_bf16 v[98:101], v[180:183], v[210:213], v[98:101]
	v_mfma_f32_16x16x32_bf16 v[90:93], v[172:175], v[218:221], v[90:93]
	v_mfma_f32_16x16x32_bf16 v[82:85], v[180:183], v[218:221], v[82:85]
	v_mfma_f32_16x16x32_bf16 v[74:77], v[172:175], v[226:229], v[74:77]
	v_mfma_f32_16x16x32_bf16 v[66:69], v[180:183], v[226:229], v[66:69]
	v_mfma_f32_16x16x32_bf16 v[122:125], v[176:179], v[192:195], v[122:125]
	v_mfma_f32_16x16x32_bf16 v[114:117], v[184:187], v[192:195], v[114:117]
	v_mfma_f32_16x16x32_bf16 v[106:109], v[176:179], v[214:217], v[106:109]
	v_mfma_f32_16x16x32_bf16 v[98:101], v[184:187], v[214:217], v[98:101]
	v_mfma_f32_16x16x32_bf16 v[90:93], v[176:179], v[222:225], v[90:93]
	v_mfma_f32_16x16x32_bf16 v[82:85], v[184:187], v[222:225], v[82:85]
	v_mfma_f32_16x16x32_bf16 v[74:77], v[176:179], v[230:233], v[74:77]
	v_mfma_f32_16x16x32_bf16 v[66:69], v[184:187], v[230:233], v[66:69]
	s_barrier
	s_add_i32 s16, s33, s92
	v_lshl_add_u64 v[142:143], v[142:143], 0, s[34:35]
	s_mov_b32 m0, s16
	ds_read_b128 v[188:191], v146 offset:49152
	ds_read_b128 v[192:195], v146 offset:50176
	ds_read_b128 v[210:213], v146 offset:51200
	ds_read_b128 v[214:217], v146 offset:52224
	ds_read_b128 v[218:221], v146 offset:53248
	ds_read_b128 v[222:225], v146 offset:54272
	ds_read_b128 v[226:229], v146 offset:55296
	ds_read_b128 v[230:233], v146 offset:56320
	global_load_lds_dwordx4 v[142:143], off
	s_add_i32 m0, s16, 0x2000
	s_add_u32 s16, s46, 0x80080
	v_lshl_add_u64 v[142:143], v[152:153], 0, s[34:35]
	s_addc_u32 s17, s47, 0
	s_add_i32 s33, s83, s92
	global_load_lds_dwordx4 v[142:143], off
	s_mov_b32 m0, s33
	v_lshl_add_u64 v[142:143], s[16:17], 0, v[134:135]
	global_load_lds_dwordx4 v[142:143], off
	s_add_i32 m0, s33, 0x2000
	v_lshl_add_u64 v[142:143], s[16:17], 0, v[130:131]
	global_load_lds_dwordx4 v[142:143], off
	s_mov_b32 m0, s7
	v_lshl_add_u64 v[142:143], v[196:197], 0, s[34:35]
	global_load_lds_dwordx4 v[142:143], off
	s_mov_b32 m0, s8
	v_lshl_add_u64 v[142:143], v[234:235], 0, s[34:35]
	global_load_lds_dwordx4 v[142:143], off
	s_waitcnt vmcnt(8)
	s_waitcnt lgkmcnt(0)
	s_barrier
	v_mfma_f32_16x16x32_bf16 v[62:65], v[148:151], v[188:191], v[62:65]
	v_mfma_f32_16x16x32_bf16 v[54:57], v[164:167], v[188:191], v[54:57]
	v_mfma_f32_16x16x32_bf16 v[46:49], v[148:151], v[210:213], v[46:49]
	v_mfma_f32_16x16x32_bf16 v[38:41], v[164:167], v[210:213], v[38:41]
	v_mfma_f32_16x16x32_bf16 v[30:33], v[148:151], v[218:221], v[30:33]
	v_mfma_f32_16x16x32_bf16 v[22:25], v[164:167], v[218:221], v[22:25]
	v_mfma_f32_16x16x32_bf16 v[14:17], v[148:151], v[226:229], v[14:17]
	v_mfma_f32_16x16x32_bf16 v[6:9], v[164:167], v[226:229], v[6:9]
	v_mfma_f32_16x16x32_bf16 v[62:65], v[160:163], v[192:195], v[62:65]
	v_mfma_f32_16x16x32_bf16 v[54:57], v[168:171], v[192:195], v[54:57]
	v_mfma_f32_16x16x32_bf16 v[46:49], v[160:163], v[214:217], v[46:49]
	v_mfma_f32_16x16x32_bf16 v[38:41], v[168:171], v[214:217], v[38:41]
	v_mfma_f32_16x16x32_bf16 v[30:33], v[160:163], v[222:225], v[30:33]
	v_mfma_f32_16x16x32_bf16 v[22:25], v[168:171], v[222:225], v[22:25]
	v_mfma_f32_16x16x32_bf16 v[14:17], v[160:163], v[230:233], v[14:17]
	v_mfma_f32_16x16x32_bf16 v[6:9], v[168:171], v[230:233], v[6:9]
	v_mfma_f32_16x16x32_bf16 v[58:61], v[172:175], v[188:191], v[58:61]
	v_mfma_f32_16x16x32_bf16 v[50:53], v[180:183], v[188:191], v[50:53]
	v_mfma_f32_16x16x32_bf16 v[42:45], v[172:175], v[210:213], v[42:45]
	v_mfma_f32_16x16x32_bf16 v[34:37], v[180:183], v[210:213], v[34:37]
	v_mfma_f32_16x16x32_bf16 v[26:29], v[172:175], v[218:221], v[26:29]
	v_mfma_f32_16x16x32_bf16 v[18:21], v[180:183], v[218:221], v[18:21]
	v_mfma_f32_16x16x32_bf16 v[10:13], v[172:175], v[226:229], v[10:13]
	v_mfma_f32_16x16x32_bf16 v[2:5], v[180:183], v[226:229], v[2:5]
	v_mfma_f32_16x16x32_bf16 v[58:61], v[176:179], v[192:195], v[58:61]
	v_mfma_f32_16x16x32_bf16 v[50:53], v[184:187], v[192:195], v[50:53]
	v_mfma_f32_16x16x32_bf16 v[42:45], v[176:179], v[214:217], v[42:45]
	v_mfma_f32_16x16x32_bf16 v[34:37], v[184:187], v[214:217], v[34:37]
	v_mfma_f32_16x16x32_bf16 v[26:29], v[176:179], v[222:225], v[26:29]
	v_mfma_f32_16x16x32_bf16 v[18:21], v[184:187], v[222:225], v[18:21]
	v_mfma_f32_16x16x32_bf16 v[10:13], v[176:179], v[230:233], v[10:13]
	v_mfma_f32_16x16x32_bf16 v[2:5], v[184:187], v[230:233], v[2:5]
	s_barrier
	s_add_i32 s82, s82, 2
	s_add_u32 s44, s44, 0x100
	s_addc_u32 s45, s45, 0
	s_add_u32 vcc_lo, vcc_lo, 0x100
	s_addc_u32 vcc_hi, vcc_hi, 0
	s_cmp_gt_u32 s82, 29
	s_cbranch_scc0 .LBB0_467
